# adds: redundant s_nop 0 between dependent v_max3 removed in attention loops; packed f32 rescale multiplies split into scalar pairs in attention code
# baseline (speedup 1.0000x reference)
.LBB0_92:
	global_load_dwordx4 v[2:5], v[18:19], off offset:-3072
	v_add_u32_e32 v14, s2, v14
	s_waitcnt vmcnt(0)
	v_pk_mul_f32 v[6:7], v[4:5], v[4:5]
	v_pk_mul_f32 v[8:9], v[2:3], v[2:3]
	s_nop 0
	v_pk_mov_b32 v[10:11], v[8:9], v[6:7] op_sel:[1,0]
	v_mov_b32_e32 v9, v7
	v_pk_add_f32 v[30:31], v[10:11], v[8:9]
	global_load_dwordx4 v[10:13], v[18:19], off offset:-2048
	v_pk_add_f32 v[30:31], v[30:31], v[30:31] op_sel:[0,1] op_sel_hi:[1,0]
	s_waitcnt vmcnt(0)
	v_pk_mul_f32 v[6:7], v[12:13], v[12:13]
	v_pk_mul_f32 v[8:9], v[10:11], v[10:11]
	s_nop 0
	v_pk_mov_b32 v[26:27], v[8:9], v[6:7] op_sel:[1,0]
	v_mov_b32_e32 v9, v7
	v_pk_add_f32 v[32:33], v[26:27], v[8:9]
	global_load_dwordx4 v[6:9], v[18:19], off offset:-1024
	global_load_dwordx4 v[26:29], v[18:19], off
	v_pk_add_f32 v[32:33], v[32:33], v[32:33] op_sel:[0,1] op_sel_hi:[1,0]
	s_waitcnt vmcnt(0)
	v_mul_f32_e32 v0, v26, v26
	v_mul_f32_e32 v15, v27, v27
	v_mov_b32_e32 v31, v0
	v_mov_b32_e32 v33, v15
	v_mul_f32_e32 v0, v7, v7
	v_pk_add_f32 v[30:31], v[30:31], v[32:33]
	v_pk_fma_f32 v[32:33], v[6:7], v[6:7], v[0:1] op_sel_hi:[1,1,0]
	v_mul_f32_e32 v0, v9, v9
	v_mul_f32_e32 v25, v28, v28
	v_mul_f32_e32 v36, v29, v29
	v_pk_fma_f32 v[34:35], v[8:9], v[8:9], v[0:1] op_sel_hi:[1,1,0]
	v_mov_b32_e32 v33, v25
	v_mov_b32_e32 v35, v36
	v_pk_add_f32 v[32:33], v[32:33], v[34:35]
	s_nop 0
	v_pk_add_f32 v[30:31], v[30:31], v[32:33]
	s_nop 0
	v_add_f32_e32 v0, v30, v31
	ds_bpermute_b32 v15, v20, v0
	s_waitcnt lgkmcnt(0)
	v_add_f32_e32 v0, v0, v15
	ds_bpermute_b32 v15, v21, v0
	s_waitcnt lgkmcnt(0)
	v_add_f32_e32 v0, v0, v15
	ds_bpermute_b32 v15, v22, v0
	s_waitcnt lgkmcnt(0)
	v_add_f32_e32 v0, v0, v15
	ds_bpermute_b32 v15, v23, v0
	s_waitcnt lgkmcnt(0)
	v_add_f32_e32 v0, v0, v15
	ds_bpermute_b32 v15, v24, v0
	s_waitcnt lgkmcnt(0)
	v_add_f32_e32 v0, v0, v15
	v_mov_b32_e32 v15, v0
	v_nop
	v_nop
	v_permlane32_swap_b32 v0, v15
	global_load_dwordx4 v[30:33], v[16:17], off
	v_add_f32_e32 v0, v0, v15
	v_fmamk_f32 v0, v0, 0x3a800000, v252
	v_cmp_gt_f32_e32 vcc, s67, v0
	v_mul_f32_e32 v15, 0x4b800000, v0
	s_nop 0
	v_cndmask_b32_e32 v0, v0, v15, vcc
	v_rsq_f32_e32 v0, v0
	s_nop 0
	v_mul_f32_e32 v15, 0x45800000, v0
	v_cndmask_b32_e32 v0, v0, v15, vcc
	v_mul_f32_e32 v2, v0, v2
	v_mul_f32_e32 v3, v0, v3
	v_mul_f32_e32 v4, v0, v4
	v_mul_f32_e32 v5, v0, v5
	v_mul_f32_e32 v12, v0, v12
	v_mul_f32_e32 v13, v0, v13
	v_mul_f32_e32 v10, v0, v10
	v_mul_f32_e32 v11, v0, v11
	v_mul_f32_e32 v8, v0, v8
	v_mul_f32_e32 v9, v0, v9
	v_mul_f32_e32 v6, v0, v6
	v_mul_f32_e32 v7, v0, v7
	v_cmp_lt_i32_e32 vcc, s45, v14
	s_or_b64 s[6:7], vcc, s[6:7]
	s_waitcnt vmcnt(0)
	v_pk_mul_f32 v[4:5], v[32:33], v[4:5]
	v_pk_mul_f32 v[2:3], v[30:31], v[2:3]
	global_store_dwordx4 v[18:19], v[2:5], off offset:-3072
	global_load_dwordx4 v[2:5], v[16:17], off offset:1024
	s_waitcnt vmcnt(0)
	v_pk_mul_f32 v[2:3], v[2:3], v[10:11]
	v_pk_mul_f32 v[4:5], v[4:5], v[12:13]
	global_store_dwordx4 v[18:19], v[2:5], off offset:-2048
	global_load_dwordx4 v[2:5], v[16:17], off offset:2048
	s_waitcnt vmcnt(0)
	v_pk_mul_f32 v[2:3], v[2:3], v[6:7]
	v_pk_mul_f32 v[4:5], v[4:5], v[8:9]
	global_store_dwordx4 v[18:19], v[2:5], off offset:-1024
	global_load_dwordx4 v[2:5], v[16:17], off offset:3072
	v_pk_mul_f32 v[6:7], v[28:29], v[0:1] op_sel_hi:[1,0]
	v_pk_mul_f32 v[8:9], v[26:27], v[0:1] op_sel_hi:[1,0]
	s_waitcnt vmcnt(0)
	v_pk_mul_f32 v[4:5], v[4:5], v[6:7]
	v_pk_mul_f32 v[2:3], v[2:3], v[8:9]
	global_store_dwordx4 v[18:19], v[2:5], off
	v_lshl_add_u64 v[18:19], v[18:19], 0, s[4:5]
	s_andn2_b64 exec, exec, s[6:7]
	s_cbranch_execnz .LBB0_92

.Lgqa_stag_in:
.LBB0_106:
	global_load_dwordx4 v[2:5], v[178:179], off
	s_and_b32 s1, s0, 1
	s_mul_i32 s31, s1, 0x2400
	v_add_u32_e32 v202, s31, v190
	ds_read_b128 v[10:13], v202 offset:4608
	ds_read_b128 v[80:83], v202
	ds_read_b128 v[186:189], v202 offset:32
	v_mov_b32_e32 v0, v194
	s_waitcnt lgkmcnt(2)
	v_mfma_f32_32x32x16_bf16 v[112:127], v[10:13], v[156:159], 0
	s_waitcnt lgkmcnt(1)
	v_mfma_f32_32x32x16_bf16 v[128:143], v[80:83], v[156:159], 0
	v_mfma_f32_32x32x16_bf16 v[96:111], v[80:83], v[172:175], 0
	v_mfma_f32_32x32x16_bf16 v[80:95], v[10:13], v[172:175], 0
	ds_read_b128 v[10:13], v202 offset:4640
	s_waitcnt lgkmcnt(1)
	v_mfma_f32_32x32x16_bf16 v[128:143], v[186:189], v[148:151], v[128:143]
	s_waitcnt lgkmcnt(0)
	v_mfma_f32_32x32x16_bf16 v[112:127], v[10:13], v[148:151], v[112:127]
	v_mfma_f32_32x32x16_bf16 v[96:111], v[186:189], v[168:171], v[96:111]
	v_mfma_f32_32x32x16_bf16 v[80:95], v[10:13], v[168:171], v[80:95]
	ds_read_b128 v[10:13], v202 offset:64
	ds_read_b128 v[186:189], v202 offset:4672
	s_waitcnt lgkmcnt(1)
	v_mfma_f32_32x32x16_bf16 v[128:143], v[10:13], v[152:155], v[128:143]
	s_waitcnt lgkmcnt(0)
	v_mfma_f32_32x32x16_bf16 v[112:127], v[186:189], v[152:155], v[112:127]
	v_mfma_f32_32x32x16_bf16 v[96:111], v[10:13], v[164:167], v[96:111]
	v_mfma_f32_32x32x16_bf16 v[80:95], v[186:189], v[164:167], v[80:95]
	ds_read_b128 v[10:13], v202 offset:96
	ds_read_b128 v[186:189], v202 offset:4704
	s_waitcnt lgkmcnt(1)
	v_mfma_f32_32x32x16_bf16 v[128:143], v[10:13], v[144:147], v[128:143]
	s_waitcnt lgkmcnt(0)
	v_mfma_f32_32x32x16_bf16 v[112:127], v[186:189], v[144:147], v[112:127]
	v_mfma_f32_32x32x16_bf16 v[96:111], v[10:13], v[160:163], v[96:111]
	v_max3_f32 v10, v128, v112, v129
	s_nop 10
	v_max_f32_e32 v11, v127, v127
	v_max3_f32 v10, v10, v113, v130
	v_max3_f32 v10, v10, v114, v131
	v_max3_f32 v10, v10, v115, v132
	v_mfma_f32_32x32x16_bf16 v[80:95], v[186:189], v[160:163], v[80:95]
	v_max3_f32 v10, v10, v116, v133
	v_max3_f32 v10, v10, v117, v134
	v_max3_f32 v10, v10, v118, v135
	v_max3_f32 v10, v10, v119, v136
	v_max3_f32 v10, v10, v120, v137
	v_max3_f32 v10, v10, v121, v138
	v_max3_f32 v10, v10, v122, v139
	v_max3_f32 v10, v10, v123, v140
	v_max3_f32 v10, v10, v124, v141
	v_max3_f32 v10, v10, v125, v142
	v_max3_f32 v10, v10, v126, v143
	s_nop 0
	v_max_f32_e32 v10, v10, v10
	v_max_f32_e32 v10, v10, v11
	v_mov_b32_e32 v11, v10
	v_nop
	v_nop
	v_permlane32_swap_b32 v10, v11
	s_nop 0
	v_max3_f32 v194, v0, v10, v11
	v_sub_f32_e32 v0, v0, v194
	v_exp_f32_e32 v14, v0
	s_nop 0
	v_cmp_neq_f32_e32 vcc, 1.0, v14
	s_cbranch_vccz .LBB0_108
	v_mul_f32_e32 v78, v14, v78
	v_mul_f32_e32 v79, v14, v79
	v_mul_f32_e32 v76, v14, v76
	v_mul_f32_e32 v77, v14, v77
	v_mul_f32_e32 v74, v14, v74
	v_mul_f32_e32 v75, v14, v75
	v_mul_f32_e32 v72, v14, v72
	v_mul_f32_e32 v73, v14, v73
	v_mul_f32_e32 v70, v14, v70
	v_mul_f32_e32 v71, v14, v71
	v_mul_f32_e32 v68, v14, v68
	v_mul_f32_e32 v69, v14, v69
	v_mul_f32_e32 v66, v14, v66
	v_mul_f32_e32 v67, v14, v67
	v_mul_f32_e32 v64, v14, v64
	v_mul_f32_e32 v65, v14, v65
	v_mul_f32_e32 v62, v14, v62
	v_mul_f32_e32 v63, v14, v63
	v_mul_f32_e32 v60, v14, v60
	v_mul_f32_e32 v61, v14, v61
	v_mul_f32_e32 v58, v14, v58
	v_mul_f32_e32 v59, v14, v59
	v_mul_f32_e32 v56, v14, v56
	v_mul_f32_e32 v57, v14, v57
	v_mul_f32_e32 v54, v14, v54
	v_mul_f32_e32 v55, v14, v55
	v_mul_f32_e32 v52, v14, v52
	v_mul_f32_e32 v53, v14, v53
	v_mul_f32_e32 v50, v14, v50
	v_mul_f32_e32 v51, v14, v51
	v_mul_f32_e32 v48, v14, v48
	v_mul_f32_e32 v49, v14, v49
.LBB0_108:
	v_max3_f32 v0, v96, v80, v97
	v_max_f32_e32 v10, v95, v95
	v_max3_f32 v0, v0, v81, v98
	v_max3_f32 v0, v0, v82, v99
	v_max3_f32 v0, v0, v83, v100
	v_max3_f32 v0, v0, v84, v101
	v_max3_f32 v0, v0, v85, v102
	v_max3_f32 v0, v0, v86, v103
	v_max3_f32 v0, v0, v87, v104
	v_max3_f32 v0, v0, v88, v105
	v_max3_f32 v0, v0, v89, v106
	v_max3_f32 v0, v0, v90, v107
	v_max3_f32 v0, v0, v91, v108
	v_max3_f32 v0, v0, v92, v109
	v_max3_f32 v0, v0, v93, v110
	v_max3_f32 v0, v0, v94, v111
	s_nop 0
	v_max_f32_e32 v0, v0, v0
	v_max_f32_e32 v0, v0, v10
	v_mov_b32_e32 v10, v0
	v_nop
	v_nop
	v_permlane32_swap_b32 v10, v0
	s_nop 0
	v_max3_f32 v195, v182, v10, v0
	v_sub_f32_e32 v0, v182, v195
	v_exp_f32_e32 v182, v0
	s_nop 0
	v_cmp_neq_f32_e32 vcc, 1.0, v182
	s_cbranch_vccz .LBB0_110
	v_mul_f32_e32 v46, v182, v46
	v_mul_f32_e32 v47, v182, v47
	v_mul_f32_e32 v44, v182, v44
	v_mul_f32_e32 v45, v182, v45
	v_mul_f32_e32 v42, v182, v42
	v_mul_f32_e32 v43, v182, v43
	v_mul_f32_e32 v40, v182, v40
	v_mul_f32_e32 v41, v182, v41
	v_mul_f32_e32 v38, v182, v38
	v_mul_f32_e32 v39, v182, v39
	v_mul_f32_e32 v36, v182, v36
	v_mul_f32_e32 v37, v182, v37
	v_mul_f32_e32 v34, v182, v34
	v_mul_f32_e32 v35, v182, v35
	v_mul_f32_e32 v32, v182, v32
	v_mul_f32_e32 v33, v182, v33
	v_mul_f32_e32 v30, v182, v30
	v_mul_f32_e32 v31, v182, v31
	v_mul_f32_e32 v28, v182, v28
	v_mul_f32_e32 v29, v182, v29
	v_mul_f32_e32 v26, v182, v26
	v_mul_f32_e32 v27, v182, v27
	v_mul_f32_e32 v24, v182, v24
	v_mul_f32_e32 v25, v182, v25
	v_mul_f32_e32 v22, v182, v22
	v_mul_f32_e32 v23, v182, v23
	v_mul_f32_e32 v20, v182, v20
	v_mul_f32_e32 v21, v182, v21
	v_mul_f32_e32 v18, v182, v18
	v_mul_f32_e32 v19, v182, v19
	v_mul_f32_e32 v16, v182, v16
	v_mul_f32_e32 v17, v182, v17

.Lgqa_stag_out:
	ds_read_b128 v[2:5], v190 offset:9216
	ds_read_b128 v[10:13], v190 offset:9312
	ds_read_b128 v[6:9], v190 offset:13824
	s_waitcnt lgkmcnt(2)
	v_mfma_f32_32x32x16_bf16 v[80:95], v[2:5], v[156:159], 0
	v_mfma_f32_32x32x16_bf16 v[112:127], v[2:5], v[172:175], 0
	ds_read_b128 v[2:5], v190 offset:9248
	s_waitcnt lgkmcnt(1)
	v_mfma_f32_32x32x16_bf16 v[96:111], v[6:9], v[156:159], 0
	v_mfma_f32_32x32x16_bf16 v[128:143], v[6:9], v[172:175], 0
	ds_read_b128 v[6:9], v190 offset:13856
	s_waitcnt lgkmcnt(1)
	v_mfma_f32_32x32x16_bf16 v[80:95], v[2:5], v[148:151], v[80:95]
	v_mfma_f32_32x32x16_bf16 v[112:127], v[2:5], v[168:171], v[112:127]
	ds_read_b128 v[2:5], v190 offset:9280
	s_waitcnt lgkmcnt(1)
	v_mfma_f32_32x32x16_bf16 v[96:111], v[6:9], v[148:151], v[96:111]
	ds_read_b128 v[148:151], v190 offset:13920
	v_mfma_f32_32x32x16_bf16 v[128:143], v[6:9], v[168:171], v[128:143]
	ds_read_b128 v[6:9], v190 offset:13888
	s_waitcnt lgkmcnt(2)
	v_mfma_f32_32x32x16_bf16 v[80:95], v[2:5], v[152:155], v[80:95]
	s_waitcnt lgkmcnt(0)
	v_mfma_f32_32x32x16_bf16 v[96:111], v[6:9], v[152:155], v[96:111]
	v_mfma_f32_32x32x16_bf16 v[80:95], v[10:13], v[144:147], v[80:95]
	v_mfma_f32_32x32x16_bf16 v[96:111], v[148:151], v[144:147], v[96:111]
	v_max3_f32 v0, v80, v96, v81
	v_max3_f32 v0, v0, v97, v82
	v_max3_f32 v0, v0, v98, v83
	v_max3_f32 v0, v0, v99, v84
	v_mfma_f32_32x32x16_bf16 v[112:127], v[2:5], v[164:167], v[112:127]
	v_max3_f32 v0, v0, v100, v85
	s_nop 7
	v_max_f32_e32 v2, v111, v111
	v_max3_f32 v0, v0, v101, v86
	v_max3_f32 v0, v0, v102, v87
	v_max3_f32 v0, v0, v103, v88
	v_mfma_f32_32x32x16_bf16 v[128:143], v[6:9], v[164:167], v[128:143]
	v_max3_f32 v0, v0, v104, v89
	v_max3_f32 v0, v0, v105, v90
	v_max3_f32 v0, v0, v106, v91
	v_max3_f32 v0, v0, v107, v92
	v_mfma_f32_32x32x16_bf16 v[112:127], v[10:13], v[160:163], v[112:127]
	v_max3_f32 v0, v0, v108, v93
	v_max3_f32 v0, v0, v109, v94
	v_max3_f32 v0, v0, v110, v95
	s_nop 0
	v_max_f32_e32 v0, v0, v0
	v_max_f32_e32 v0, v0, v2
	v_mov_b32_e32 v2, v0
	v_mfma_f32_32x32x16_bf16 v[128:143], v[148:151], v[160:163], v[128:143]
	v_nop
	v_nop
	v_permlane32_swap_b32 v0, v2
	s_nop 0
	v_max3_f32 v147, v194, v0, v2
	v_sub_f32_e32 v0, v194, v147
	v_exp_f32_e32 v14, v0
	s_nop 0
	v_cmp_neq_f32_e32 vcc, 1.0, v14
	s_cbranch_vccz .LBB0_114
	v_mul_f32_e32 v78, v14, v78
	v_mul_f32_e32 v79, v14, v79
	v_mul_f32_e32 v76, v14, v76
	v_mul_f32_e32 v77, v14, v77
	v_mul_f32_e32 v74, v14, v74
	v_mul_f32_e32 v75, v14, v75
	v_mul_f32_e32 v72, v14, v72
	v_mul_f32_e32 v73, v14, v73
	v_mul_f32_e32 v70, v14, v70
	v_mul_f32_e32 v71, v14, v71
	v_mul_f32_e32 v68, v14, v68
	v_mul_f32_e32 v69, v14, v69
	v_mul_f32_e32 v66, v14, v66
	v_mul_f32_e32 v67, v14, v67
	v_mul_f32_e32 v64, v14, v64
	v_mul_f32_e32 v65, v14, v65
	v_mul_f32_e32 v62, v14, v62
	v_mul_f32_e32 v63, v14, v63
	v_mul_f32_e32 v60, v14, v60
	v_mul_f32_e32 v61, v14, v61
	v_mul_f32_e32 v58, v14, v58
	v_mul_f32_e32 v59, v14, v59
	v_mul_f32_e32 v56, v14, v56
	v_mul_f32_e32 v57, v14, v57
	v_mul_f32_e32 v54, v14, v54
	v_mul_f32_e32 v55, v14, v55
	v_mul_f32_e32 v52, v14, v52
	v_mul_f32_e32 v53, v14, v53
	v_mul_f32_e32 v50, v14, v50
	v_mul_f32_e32 v51, v14, v51
	v_mul_f32_e32 v48, v14, v48
	v_mul_f32_e32 v49, v14, v49
.LBB0_114:
	v_max3_f32 v0, v112, v128, v113
	v_max_f32_e32 v2, v143, v143
	v_max3_f32 v0, v0, v129, v114
	v_max3_f32 v0, v0, v130, v115
	v_max3_f32 v0, v0, v131, v116
	v_max3_f32 v0, v0, v132, v117
	v_max3_f32 v0, v0, v133, v118
	v_max3_f32 v0, v0, v134, v119
	v_max3_f32 v0, v0, v135, v120
	v_max3_f32 v0, v0, v136, v121
	v_max3_f32 v0, v0, v137, v122
	v_max3_f32 v0, v0, v138, v123
	v_max3_f32 v0, v0, v139, v124
	v_max3_f32 v0, v0, v140, v125
	v_max3_f32 v0, v0, v141, v126
	v_max3_f32 v0, v0, v142, v127
	s_nop 0
	v_max_f32_e32 v0, v0, v0
	v_max_f32_e32 v0, v0, v2
	v_mov_b32_e32 v2, v0
	v_nop
	v_nop
	v_permlane32_swap_b32 v0, v2
	s_nop 0
	v_max3_f32 v2, v195, v0, v2
	v_sub_f32_e32 v0, v195, v2
	v_exp_f32_e32 v144, v0
	s_nop 0
	v_cmp_neq_f32_e32 vcc, 1.0, v144
	s_cbranch_vccz .LBB0_104
	v_mul_f32_e32 v46, v144, v46
	v_mul_f32_e32 v47, v144, v47
	v_mul_f32_e32 v44, v144, v44
	v_mul_f32_e32 v45, v144, v45
	v_mul_f32_e32 v42, v144, v42
	v_mul_f32_e32 v43, v144, v43
	v_mul_f32_e32 v40, v144, v40
	v_mul_f32_e32 v41, v144, v41
	v_mul_f32_e32 v38, v144, v38
	v_mul_f32_e32 v39, v144, v39
	v_mul_f32_e32 v36, v144, v36
	v_mul_f32_e32 v37, v144, v37
	v_mul_f32_e32 v34, v144, v34
	v_mul_f32_e32 v35, v144, v35
	v_mul_f32_e32 v32, v144, v32
	v_mul_f32_e32 v33, v144, v33
	v_mul_f32_e32 v30, v144, v30
	v_mul_f32_e32 v31, v144, v31
	v_mul_f32_e32 v28, v144, v28
	v_mul_f32_e32 v29, v144, v29
	v_mul_f32_e32 v26, v144, v26
	v_mul_f32_e32 v27, v144, v27
	v_mul_f32_e32 v24, v144, v24
	v_mul_f32_e32 v25, v144, v25
	v_mul_f32_e32 v22, v144, v22
	v_mul_f32_e32 v23, v144, v23
	v_mul_f32_e32 v20, v144, v20
	v_mul_f32_e32 v21, v144, v21
	v_mul_f32_e32 v18, v144, v18
	v_mul_f32_e32 v19, v144, v19
	v_mul_f32_e32 v16, v144, v16
	v_mul_f32_e32 v17, v144, v17
	s_branch .LBB0_104

.LBB0_122:
	v_add_f32_e32 v102, v137, v138
	v_add_f32_e32 v102, 0, v102
	v_add_f32_e32 v103, v139, v140
	v_add_f32_e32 v102, v103, v102
	v_add_f32_e32 v103, v141, v142
	v_add_f32_e32 v102, v103, v102
	v_add_f32_e32 v103, v143, v144
	v_add_f32_e32 v102, v103, v102
	v_add_f32_e32 v103, v145, v146
	v_add_f32_e32 v102, v103, v102
	v_add_f32_e32 v103, v147, v148
	v_add_f32_e32 v102, v103, v102
	v_add_f32_e32 v103, v149, v150
	v_add_f32_e32 v102, v103, v102
	v_add_f32_e32 v103, v151, v152
	v_add_f32_e32 v102, v103, v102
	v_add_f32_e32 v103, v153, v154
	v_add_f32_e32 v102, v103, v102
	v_add_f32_e32 v103, v155, v156
	v_add_f32_e32 v102, v103, v102
	v_add_f32_e32 v103, v157, v158
	v_add_f32_e32 v102, v103, v102
	v_add_f32_e32 v103, v159, v160
	v_add_f32_e32 v102, v103, v102
	v_add_f32_e32 v103, v161, v162
	v_add_f32_e32 v102, v103, v102
	v_add_f32_e32 v103, v163, v164
	v_add_f32_e32 v102, v103, v102
	v_add_f32_e32 v103, v165, v166
	v_add_f32_e32 v102, v103, v102
	v_add_f32_e32 v103, v167, v169
	v_add_f32_e32 v102, v103, v102
	v_add_f32_e32 v103, v170, v171
	v_add_f32_e32 v103, 0, v103
	v_add_f32_e32 v104, v172, v173
	v_add_f32_e32 v103, v104, v103
	v_add_f32_e32 v104, v174, v175
	v_add_f32_e32 v103, v104, v103
	v_add_f32_e32 v104, v176, v177
	v_add_f32_e32 v103, v104, v103
	v_add_f32_e32 v104, v178, v179
	v_add_f32_e32 v103, v104, v103
	v_add_f32_e32 v104, v180, v181
	v_add_f32_e32 v103, v104, v103
	v_add_f32_e32 v104, v182, v183
	v_add_f32_e32 v103, v104, v103
	v_add_f32_e32 v104, v184, v185
	v_add_f32_e32 v103, v104, v103
	v_add_f32_e32 v104, v186, v187
	v_add_f32_e32 v103, v104, v103
	v_add_f32_e32 v104, v188, v189
	v_add_f32_e32 v103, v104, v103
	v_add_f32_e32 v104, v190, v191
	v_add_f32_e32 v103, v104, v103
	v_add_f32_e32 v104, v192, v193
	v_add_f32_e32 v103, v104, v103
	v_add_f32_e32 v104, v194, v195
	v_add_f32_e32 v103, v104, v103
	v_add_f32_e32 v104, v202, v203
	v_add_f32_e32 v103, v104, v103
	v_add_f32_e32 v104, v204, v205
	v_add_f32_e32 v103, v104, v103
	v_add_f32_e32 v104, v206, v207
	v_add_f32_e32 v102, v168, v102
	v_add_f32_e32 v103, v104, v103
	v_fmac_f32_e32 v103, v102, v0
	v_add_f32_e32 v0, v135, v136
	v_add_f32_e32 v0, 0, v0
	v_add_f32_e32 v102, v208, v209
	v_add_f32_e32 v0, v102, v0
	v_add_f32_e32 v102, v219, v220
	v_add_f32_e32 v0, v102, v0
	v_add_f32_e32 v102, v221, v222
	v_add_f32_e32 v0, v102, v0
	v_add_f32_e32 v102, v223, v224
	v_add_f32_e32 v0, v102, v0
	v_add_f32_e32 v102, v225, v226
	v_add_f32_e32 v0, v102, v0
	v_add_f32_e32 v102, v227, v228
	v_add_f32_e32 v0, v102, v0
	v_add_f32_e32 v102, v229, v230
	v_add_f32_e32 v0, v102, v0
	v_add_f32_e32 v102, v231, v232
	v_add_f32_e32 v0, v102, v0
	v_add_f32_e32 v102, v233, v234
	v_add_f32_e32 v0, v102, v0
	v_add_f32_e32 v102, v235, v236
	v_add_f32_e32 v0, v102, v0
	v_add_f32_e32 v102, v237, v238
	v_add_f32_e32 v0, v102, v0
	v_add_f32_e32 v102, v239, v240
	v_add_f32_e32 v0, v102, v0
	v_add_f32_e32 v102, v241, v242
	v_add_f32_e32 v0, v102, v0
	v_add_f32_e32 v102, v243, v244
	v_add_f32_e32 v0, v102, v0
	v_add_f32_e32 v102, v245, v246
	v_add_f32_e32 v0, v102, v0
	v_sub_f32_e32 v36, v36, v99
	v_fmac_f32_e32 v0, v103, v132
	v_exp_f32_e32 v103, v36
	v_sub_f32_e32 v36, v53, v99
	v_exp_f32_e32 v53, v36
	v_sub_f32_e32 v36, v37, v99
	v_sub_f32_e32 v34, v34, v99
	v_exp_f32_e32 v105, v36
	v_sub_f32_e32 v36, v54, v99
	v_sub_f32_e32 v50, v50, v99
	v_exp_f32_e32 v102, v34
	v_sub_f32_e32 v34, v51, v99
	v_exp_f32_e32 v54, v36
	v_sub_f32_e32 v36, v38, v99
	v_exp_f32_e32 v50, v50
	v_exp_f32_e32 v51, v34
	v_sub_f32_e32 v34, v35, v99
	v_exp_f32_e32 v106, v36
	v_sub_f32_e32 v36, v55, v99
	v_exp_f32_e32 v104, v34
	v_sub_f32_e32 v52, v52, v99
	v_exp_f32_e32 v55, v36
	v_sub_f32_e32 v36, v39, v99
	v_exp_f32_e32 v52, v52
	v_exp_f32_e32 v107, v36
	v_sub_f32_e32 v36, v56, v99
	v_exp_f32_e32 v56, v36
	v_sub_f32_e32 v36, v40, v99
	v_add_f32_e32 v34, v50, v102
	v_exp_f32_e32 v108, v36
	v_sub_f32_e32 v36, v57, v99
	v_add_f32_e32 v34, 0, v34
	v_add_f32_e32 v35, v51, v104
	v_exp_f32_e32 v57, v36
	v_sub_f32_e32 v36, v41, v99
	v_add_f32_e32 v34, v35, v34
	v_add_f32_e32 v35, v52, v103
	v_exp_f32_e32 v41, v36
	v_sub_f32_e32 v36, v58, v99
	v_add_f32_e32 v34, v35, v34
	v_add_f32_e32 v35, v53, v105
	v_exp_f32_e32 v58, v36
	v_sub_f32_e32 v36, v42, v99
	v_sub_f32_e32 v37, v59, v99
	v_add_f32_e32 v34, v35, v34
	v_add_f32_e32 v35, v54, v106
	v_exp_f32_e32 v36, v36
	v_exp_f32_e32 v42, v37
	v_sub_f32_e32 v37, v43, v99
	v_sub_f32_e32 v38, v60, v99
	v_add_f32_e32 v34, v35, v34
	v_add_f32_e32 v35, v55, v107
	v_exp_f32_e32 v37, v37
	v_exp_f32_e32 v43, v38
	v_sub_f32_e32 v38, v44, v99
	v_sub_f32_e32 v39, v61, v99
	v_add_f32_e32 v34, v35, v34
	v_add_f32_e32 v35, v56, v108
	v_exp_f32_e32 v38, v38
	v_exp_f32_e32 v44, v39
	v_sub_f32_e32 v39, v45, v99
	v_sub_f32_e32 v40, v62, v99
	v_add_f32_e32 v34, v35, v34
	v_add_f32_e32 v35, v57, v41
	v_exp_f32_e32 v39, v39
	v_exp_f32_e32 v45, v40
	v_sub_f32_e32 v40, v46, v99
	v_add_f32_e32 v34, v35, v34
	v_add_f32_e32 v35, v58, v36
	v_exp_f32_e32 v40, v40
	v_sub_f32_e32 v46, v63, v99
	v_sub_f32_e32 v47, v47, v99
	v_add_f32_e32 v34, v35, v34
	v_add_f32_e32 v35, v42, v37
	v_exp_f32_e32 v46, v46
	v_exp_f32_e32 v47, v47
	v_sub_f32_e32 v59, v64, v99
	v_sub_f32_e32 v48, v48, v99
	v_add_f32_e32 v34, v35, v34
	v_add_f32_e32 v35, v43, v38
	v_exp_f32_e32 v59, v59
	v_exp_f32_e32 v48, v48
	v_sub_f32_e32 v60, v65, v99
	v_sub_f32_e32 v49, v49, v99
	v_add_f32_e32 v34, v35, v34
	v_add_f32_e32 v35, v44, v39
	v_exp_f32_e32 v60, v60
	v_exp_f32_e32 v49, v49
	v_add_f32_e32 v34, v35, v34
	v_add_f32_e32 v35, v45, v40
	v_add_f32_e32 v34, v35, v34
	v_add_f32_e32 v35, v46, v47
	v_add_f32_e32 v34, v35, v34
	v_add_f32_e32 v35, v59, v48
	v_add_f32_e32 v34, v35, v34
	v_add_f32_e32 v35, v60, v49
	v_add_f32_e32 v61, v35, v34
	s_lshl_b32 s0, s17, 6
	v_lshlrev_b64 v[100:101], 10, v[130:131]
	v_fmac_f32_e32 v61, v0, v98
	v_cvt_pk_bf16_f32 v34, v36, v37
	v_cvt_pk_bf16_f32 v35, v38, v39
	v_cvt_pk_bf16_f32 v36, v40, v47
	v_cvt_pk_bf16_f32 v37, v48, v49
	v_cvt_pk_bf16_f32 v38, v102, v104
	v_cvt_pk_bf16_f32 v39, v103, v105
	v_cvt_pk_bf16_f32 v40, v106, v107
	v_cvt_pk_bf16_f32 v41, v108, v41
	v_cvt_pk_bf16_f32 v42, v58, v42
	v_cvt_pk_bf16_f32 v43, v43, v44
	v_cvt_pk_bf16_f32 v44, v45, v46
	v_cvt_pk_bf16_f32 v45, v59, v60
	v_cvt_pk_bf16_f32 v46, v50, v51
	v_cvt_pk_bf16_f32 v47, v52, v53
	v_cvt_pk_bf16_f32 v48, v54, v55
	v_cvt_pk_bf16_f32 v49, v56, v57
	s_waitcnt lgkmcnt(7)
	s_nop 0
	v_mfma_f32_32x32x16_bf16 v[18:33], v[94:97], v[46:49], v[18:33]
	s_waitcnt lgkmcnt(3)
	v_mfma_f32_32x32x16_bf16 v[2:17], v[78:81], v[46:49], v[2:17]
	v_mfma_f32_32x32x16_bf16 v[18:33], v[90:93], v[42:45], v[18:33]
	s_waitcnt lgkmcnt(2)
	v_mfma_f32_32x32x16_bf16 v[2:17], v[74:77], v[42:45], v[2:17]
	v_mfma_f32_32x32x16_bf16 v[18:33], v[86:89], v[38:41], v[18:33]
	s_waitcnt lgkmcnt(1)
	v_mfma_f32_32x32x16_bf16 v[2:17], v[70:73], v[38:41], v[2:17]
	v_mfma_f32_32x32x16_bf16 v[18:33], v[82:85], v[34:37], v[18:33]
	s_waitcnt lgkmcnt(0)
	v_mfma_f32_32x32x16_bf16 v[2:17], v[66:69], v[34:37], v[2:17]
	v_mov_b32_e32 v0, v61
	s_barrier
	v_nop
	v_nop
	v_permlane32_swap_b32 v61, v0
	s_lshl_b32 s80, s0, 1
	v_add_f32_e32 v0, v61, v0
	v_div_scale_f32 v34, s[20:21], v0, v0, 1.0
	v_rcp_f32_e32 v35, v34
	v_readlane_b32 s20, v254, 63
	v_readlane_b32 s21, v255, 0
	s_add_i32 s4, s4, s5
	v_fma_f32 v36, -v34, v35, 1.0
	v_fmac_f32_e32 v35, v36, v35
	v_div_scale_f32 v36, vcc, 1.0, v0, 1.0
	v_mul_f32_e32 v37, v36, v35
	v_fma_f32 v38, -v34, v37, v36
	v_fmac_f32_e32 v37, v38, v35
	v_fma_f32 v34, -v34, v37, v36
	v_div_fmas_f32 v34, v34, v35, v37
	v_div_fixup_f32 v34, v34, v0, 1.0
	v_lshl_add_u64 v[36:37], v[100:101], 1, s[20:21]
	v_lshl_add_u64 v[36:37], v[36:37], 0, s[80:81]
	v_lshlrev_b32_e32 v0, 3, v133
	v_mul_f32_e32 v18, v34, v18
	v_mul_f32_e32 v19, v34, v19
	v_mul_f32_e32 v20, v34, v20
	v_mul_f32_e32 v21, v34, v21
	v_mul_f32_e32 v2, v34, v2
	v_mul_f32_e32 v3, v34, v3
	v_mul_f32_e32 v4, v34, v4
	v_mul_f32_e32 v5, v34, v5
	v_lshl_add_u64 v[36:37], v[36:37], 0, v[0:1]
	v_cvt_pk_bf16_f32 v18, v18, v19
	v_cvt_pk_bf16_f32 v19, v20, v21
	v_cvt_pk_bf16_f32 v2, v2, v3
	v_cvt_pk_bf16_f32 v3, v4, v5
	global_store_dwordx2 v[36:37], v[18:19], off
	v_pk_mul_f32 v[18:19], v[22:23], v[34:35] op_sel_hi:[1,0]
	v_pk_mul_f32 v[20:21], v[24:25], v[34:35] op_sel_hi:[1,0]
	global_store_dwordx2 v[36:37], v[2:3], off offset:64
	v_pk_mul_f32 v[2:3], v[6:7], v[34:35] op_sel_hi:[1,0]
	v_pk_mul_f32 v[4:5], v[8:9], v[34:35] op_sel_hi:[1,0]
	v_cvt_pk_bf16_f32 v18, v18, v19
	v_cvt_pk_bf16_f32 v19, v20, v21
	v_cvt_pk_bf16_f32 v2, v2, v3
	v_cvt_pk_bf16_f32 v3, v4, v5
	global_store_dwordx2 v[36:37], v[18:19], off offset:16
	v_pk_mul_f32 v[18:19], v[26:27], v[34:35] op_sel_hi:[1,0]
	v_pk_mul_f32 v[20:21], v[28:29], v[34:35] op_sel_hi:[1,0]
	global_store_dwordx2 v[36:37], v[2:3], off offset:80
	v_pk_mul_f32 v[2:3], v[10:11], v[34:35] op_sel_hi:[1,0]
	v_pk_mul_f32 v[4:5], v[12:13], v[34:35] op_sel_hi:[1,0]
	v_cvt_pk_bf16_f32 v18, v18, v19
	v_cvt_pk_bf16_f32 v19, v20, v21
	v_cvt_pk_bf16_f32 v2, v2, v3
	v_cvt_pk_bf16_f32 v3, v4, v5
	global_store_dwordx2 v[36:37], v[18:19], off offset:32
	v_pk_mul_f32 v[18:19], v[30:31], v[34:35] op_sel_hi:[1,0]
	v_pk_mul_f32 v[20:21], v[32:33], v[34:35] op_sel_hi:[1,0]
	global_store_dwordx2 v[36:37], v[2:3], off offset:96
	v_pk_mul_f32 v[2:3], v[14:15], v[34:35] op_sel_hi:[1,0]
	v_pk_mul_f32 v[4:5], v[16:17], v[34:35] op_sel_hi:[1,0]
	s_add_i32 s2, s2, s3
	v_cvt_pk_bf16_f32 v18, v18, v19
	v_cvt_pk_bf16_f32 v19, v20, v21
	v_cvt_pk_bf16_f32 v2, v2, v3
	v_cvt_pk_bf16_f32 v3, v4, v5
	s_cmpk_gt_i32 s4, 0x1ff
	global_store_dwordx2 v[36:37], v[18:19], off offset:48
	global_store_dwordx2 v[36:37], v[2:3], off offset:112
	s_cbranch_scc1 .LBB0_129
.LBB0_123:
	v_mov_b32_e32 v68, v197
	s_and_b32 s0, s2, 0xffffff00
	s_and_b32 s17, s4, 15
	v_and_b32_e32 v7, 31, v68
	v_ashrrev_i32_e32 v0, 1, v68
	v_and_b32_e32 v0, 0xffffffe0, v0
	v_or_b32_e32 v2, s0, v7
	v_add_u32_e32 v130, v2, v0
	v_ashrrev_i32_e32 v131, 31, v130
	v_lshlrev_b64 v[2:3], 11, v[130:131]
	s_waitcnt vmcnt(0)
	v_bfe_u32 v133, v68, 5, 1
	v_lshl_add_u64 v[2:3], s[48:49], 0, v[2:3]
	s_lshl_b32 s80, s17, 7
	v_lshl_add_u64 v[2:3], v[2:3], 0, s[80:81]
	v_lshlrev_b32_e32 v0, 4, v133
	v_lshl_add_u64 v[16:17], v[2:3], 0, v[0:1]
	global_load_dwordx4 v[2:5], v[16:17], off
	global_load_dwordx4 v[8:11], v[16:17], off offset:32
	global_load_dwordx4 v[12:15], v[16:17], off offset:64
	s_nop 0
	global_load_dwordx4 v[16:19], v[16:17], off offset:96
	v_lshlrev_b32_e32 v69, 5, v133
	s_mov_b32 s20, 0x3e38aa3b
	s_lshl_b32 s1, s4, 4
	s_and_b32 s28, s1, 0xc0
	s_lshl_b32 s80, s28, 1
	s_ashr_i32 s1, s0, 31
	s_waitcnt vmcnt(3)
	v_and_b32_e32 v67, 0xffff0000, v2
	v_lshlrev_b32_e32 v66, 16, v2
	v_and_b32_e32 v63, 0xffff0000, v3
	v_lshlrev_b32_e32 v62, 16, v3
	v_pk_mul_f32 v[2:3], v[66:67], v[66:67]
	v_pk_mul_f32 v[64:65], v[62:63], v[62:63]
	v_add_f32_e32 v2, v2, v3
	v_and_b32_e32 v61, 0xffff0000, v4
	v_lshlrev_b32_e32 v60, 16, v4
	v_add_f32_e32 v2, v64, v2
	v_and_b32_e32 v57, 0xffff0000, v5
	v_lshlrev_b32_e32 v56, 16, v5
	v_pk_mul_f32 v[4:5], v[60:61], v[60:61]
	v_add_f32_e32 v2, v65, v2
	v_add_f32_e32 v2, v4, v2
	v_pk_mul_f32 v[58:59], v[56:57], v[56:57]
	v_add_f32_e32 v2, v5, v2
	s_waitcnt vmcnt(2)
	v_and_b32_e32 v55, 0xffff0000, v8
	v_lshlrev_b32_e32 v54, 16, v8
	v_add_f32_e32 v2, v58, v2
	v_and_b32_e32 v51, 0xffff0000, v9
	v_lshlrev_b32_e32 v50, 16, v9
	v_pk_mul_f32 v[8:9], v[54:55], v[54:55]
	v_add_f32_e32 v2, v59, v2
	v_add_f32_e32 v2, v8, v2
	v_pk_mul_f32 v[52:53], v[50:51], v[50:51]
	v_add_f32_e32 v2, v9, v2
	v_and_b32_e32 v49, 0xffff0000, v10
	v_lshlrev_b32_e32 v48, 16, v10
	v_add_f32_e32 v2, v52, v2
	v_and_b32_e32 v45, 0xffff0000, v11
	v_lshlrev_b32_e32 v44, 16, v11
	v_pk_mul_f32 v[10:11], v[48:49], v[48:49]
	v_add_f32_e32 v2, v53, v2
	v_add_f32_e32 v2, v10, v2
	v_pk_mul_f32 v[46:47], v[44:45], v[44:45]
	v_add_f32_e32 v2, v11, v2
	s_waitcnt vmcnt(1)
	v_and_b32_e32 v39, 0xffff0000, v13
	v_lshlrev_b32_e32 v38, 16, v13
	v_and_b32_e32 v13, 0xffff0000, v12
	v_lshlrev_b32_e32 v12, 16, v12
	v_add_f32_e32 v2, v46, v2
	v_pk_mul_f32 v[42:43], v[12:13], v[12:13]
	v_add_f32_e32 v2, v47, v2
	v_add_f32_e32 v2, v42, v2
	v_pk_mul_f32 v[40:41], v[38:39], v[38:39]
	v_add_f32_e32 v2, v43, v2
	v_and_b32_e32 v33, 0xffff0000, v15
	v_lshlrev_b32_e32 v32, 16, v15
	v_and_b32_e32 v15, 0xffff0000, v14
	v_lshlrev_b32_e32 v14, 16, v14
	v_add_f32_e32 v2, v40, v2
	v_pk_mul_f32 v[36:37], v[14:15], v[14:15]
	v_add_f32_e32 v2, v41, v2
	v_add_f32_e32 v2, v36, v2
	v_pk_mul_f32 v[34:35], v[32:33], v[32:33]
	v_add_f32_e32 v2, v37, v2
	s_waitcnt vmcnt(0)
	v_and_b32_e32 v27, 0xffff0000, v17
	v_lshlrev_b32_e32 v26, 16, v17
	v_and_b32_e32 v17, 0xffff0000, v16
	v_lshlrev_b32_e32 v16, 16, v16
	v_add_f32_e32 v2, v34, v2
	v_pk_mul_f32 v[30:31], v[16:17], v[16:17]
	v_add_f32_e32 v2, v35, v2
	v_add_f32_e32 v2, v30, v2
	v_pk_mul_f32 v[28:29], v[26:27], v[26:27]
	v_add_f32_e32 v2, v31, v2
	v_and_b32_e32 v21, 0xffff0000, v19
	v_lshlrev_b32_e32 v20, 16, v19
	v_and_b32_e32 v19, 0xffff0000, v18
	v_lshlrev_b32_e32 v18, 16, v18
	v_add_f32_e32 v2, v28, v2
	v_pk_mul_f32 v[24:25], v[18:19], v[18:19]
	v_add_f32_e32 v2, v29, v2
	v_add_f32_e32 v2, v24, v2
	v_pk_mul_f32 v[22:23], v[20:21], v[20:21]
	v_add_f32_e32 v2, v25, v2
	v_add_f32_e32 v2, v22, v2
	v_add_f32_e32 v2, v23, v2
	v_mov_b32_e32 v3, v2
	v_nop
	v_nop
	v_permlane32_swap_b32 v2, v3
	s_nop 0
	v_add_f32_e32 v2, v2, v3
	v_fmamk_f32 v2, v2, 0x3c800000, v252
	v_cmp_gt_f32_e32 vcc, s67, v2
	v_mul_f32_e32 v3, 0x4b800000, v2
	s_nop 0
	v_cndmask_b32_e32 v2, v2, v3, vcc
	v_rsq_f32_e32 v2, v2
	s_nop 0
	v_mul_f32_e32 v3, 0x45800000, v2
	v_cndmask_b32_e32 v6, v2, v3, vcc
	s_waitcnt lgkmcnt(0)
	global_load_dwordx4 v[2:5], v69, s[8:9] offset:16
	global_load_dwordx4 v[8:11], v69, s[8:9]
	s_waitcnt vmcnt(1)
	v_mul_f32_e32 v2, v6, v2
	v_mul_f32_e32 v3, v6, v3
	s_waitcnt vmcnt(0)
	v_mul_f32_e32 v8, v6, v8
	v_mul_f32_e32 v9, v6, v9
	v_pk_mul_f32 v[28:29], v[2:3], v[60:61]
	v_pk_mul_f32 v[22:23], v[8:9], v[66:67]
	v_pk_mul_f32 v[8:9], v[10:11], v[6:7] op_sel_hi:[1,0]
	v_pk_mul_f32 v[2:3], v[4:5], v[6:7] op_sel_hi:[1,0]
	v_pk_mul_f32 v[24:25], v[8:9], v[62:63]
	v_pk_mul_f32 v[30:31], v[2:3], v[56:57]
	global_load_dwordx4 v[2:5], v69, s[8:9] offset:80
	global_load_dwordx4 v[8:11], v69, s[8:9] offset:64
	s_waitcnt vmcnt(1)
	v_pk_mul_f32 v[2:3], v[6:7], v[2:3] op_sel_hi:[0,1]
	s_waitcnt vmcnt(0)
	v_pk_mul_f32 v[8:9], v[6:7], v[8:9] op_sel_hi:[0,1]
	v_pk_mul_f32 v[34:35], v[8:9], v[54:55]
	v_pk_mul_f32 v[8:9], v[6:7], v[10:11] op_sel_hi:[0,1]
	v_pk_mul_f32 v[40:41], v[2:3], v[48:49]
	v_pk_mul_f32 v[2:3], v[6:7], v[4:5] op_sel_hi:[0,1]
	v_pk_mul_f32 v[36:37], v[8:9], v[50:51]
	v_pk_mul_f32 v[42:43], v[2:3], v[44:45]
	global_load_dwordx4 v[2:5], v69, s[8:9] offset:144
	global_load_dwordx4 v[8:11], v69, s[8:9] offset:128
	s_waitcnt vmcnt(1)
	v_pk_mul_f32 v[2:3], v[6:7], v[2:3] op_sel_hi:[0,1]
	s_waitcnt vmcnt(0)
	v_pk_mul_f32 v[8:9], v[6:7], v[8:9] op_sel_hi:[0,1]
	v_pk_mul_f32 v[12:13], v[8:9], v[12:13]
	v_pk_mul_f32 v[8:9], v[6:7], v[10:11] op_sel_hi:[0,1]
	v_pk_mul_f32 v[14:15], v[2:3], v[14:15]
	v_pk_mul_f32 v[2:3], v[6:7], v[4:5] op_sel_hi:[0,1]
	v_pk_mul_f32 v[38:39], v[8:9], v[38:39]
	v_pk_mul_f32 v[32:33], v[2:3], v[32:33]
	global_load_dwordx4 v[2:5], v69, s[8:9] offset:208
	global_load_dwordx4 v[8:11], v69, s[8:9] offset:192
	v_pk_mul_f32 v[12:13], v[12:13], s[20:21] op_sel_hi:[1,0]
	s_waitcnt vmcnt(1)
	v_pk_mul_f32 v[2:3], v[6:7], v[2:3] op_sel_hi:[0,1]
	s_waitcnt vmcnt(0)
	v_pk_mul_f32 v[8:9], v[6:7], v[8:9] op_sel_hi:[0,1]
	v_pk_mul_f32 v[8:9], v[8:9], v[16:17]
	v_pk_mul_f32 v[16:17], v[22:23], s[20:21] op_sel_hi:[1,0]
	v_pk_mul_f32 v[2:3], v[2:3], v[18:19]
	v_pk_mul_f32 v[4:5], v[6:7], v[4:5] op_sel_hi:[0,1]
	v_cvt_pk_bf16_f32 v98, v16, v17
	v_pk_mul_f32 v[16:17], v[24:25], s[20:21] op_sel_hi:[1,0]
	v_pk_mul_f32 v[4:5], v[4:5], v[20:21]
	v_cvt_pk_bf16_f32 v99, v16, v17
	v_pk_mul_f32 v[16:17], v[28:29], s[20:21] op_sel_hi:[1,0]
	v_pk_mul_f32 v[2:3], v[2:3], s[20:21] op_sel_hi:[1,0]
	v_cvt_pk_bf16_f32 v100, v16, v17
	v_pk_mul_f32 v[16:17], v[30:31], s[20:21] op_sel_hi:[1,0]
	v_cvt_pk_bf16_f32 v106, v12, v13
	v_pk_mul_f32 v[12:13], v[38:39], s[20:21] op_sel_hi:[1,0]
	v_cvt_pk_bf16_f32 v112, v2, v3
	v_pk_mul_f32 v[2:3], v[4:5], s[20:21] op_sel_hi:[1,0]
	v_ashrrev_i32_e32 v4, 3, v68
	v_cvt_pk_bf16_f32 v101, v16, v17
	v_pk_mul_f32 v[16:17], v[34:35], s[20:21] op_sel_hi:[1,0]
	v_cvt_pk_bf16_f32 v107, v12, v13
	v_pk_mul_f32 v[12:13], v[14:15], s[20:21] op_sel_hi:[1,0]
	v_cvt_pk_bf16_f32 v113, v2, v3
	v_add_u32_e32 v2, s0, v4
	v_pk_mul_f32 v[10:11], v[6:7], v[10:11] op_sel_hi:[0,1]
	v_cvt_pk_bf16_f32 v102, v16, v17
	v_pk_mul_f32 v[16:17], v[36:37], s[20:21] op_sel_hi:[1,0]
	v_cvt_pk_bf16_f32 v108, v12, v13
	v_pk_mul_f32 v[12:13], v[32:33], s[20:21] op_sel_hi:[1,0]
	v_ashrrev_i32_e32 v3, 31, v2
	v_lshlrev_b32_e32 v6, 4, v68
	v_pk_mul_f32 v[10:11], v[10:11], v[26:27]
	v_cvt_pk_bf16_f32 v103, v16, v17
	v_pk_mul_f32 v[16:17], v[40:41], s[20:21] op_sel_hi:[1,0]
	v_cvt_pk_bf16_f32 v109, v12, v13
	v_pk_mul_f32 v[8:9], v[8:9], s[20:21] op_sel_hi:[1,0]
	v_and_b32_e32 v12, 0x70, v6
	v_lshlrev_b64 v[2:3], 9, v[2:3]
	v_cvt_pk_bf16_f32 v104, v16, v17
	v_pk_mul_f32 v[16:17], v[42:43], s[20:21] op_sel_hi:[1,0]
	v_cvt_pk_bf16_f32 v110, v8, v9
	v_pk_mul_f32 v[8:9], v[10:11], s[20:21] op_sel_hi:[1,0]
	v_mad_u64_u32 v[4:5], s[20:21], v4, s42, v[12:13]
	v_lshl_add_u64 v[2:3], s[10:11], 0, v[2:3]
	v_ashrrev_i32_e32 v10, 4, v68
	v_lshlrev_b32_e32 v5, 3, v68
	v_lshl_add_u64 v[2:3], v[2:3], 0, s[80:81]
	v_mov_b32_e32 v13, v1
	v_cvt_pk_bf16_f32 v111, v8, v9
	v_add_u32_e32 v8, s28, v10
	v_and_b32_e32 v5, 8, v5
	s_movk_i32 s20, 0xe0
	v_lshl_add_u64 v[2:3], v[2:3], 0, v[12:13]
	v_mov_b64_e32 v[12:13], s[18:19]
	v_and_or_b32 v6, v6, s20, v5
	v_mad_i64_i32 v[8:9], s[20:21], v8, s68, v[12:13]
	v_and_b32_e32 v11, 15, v68
	v_lshl_add_u64 v[8:9], s[0:1], 1, v[8:9]
	s_mov_b32 s0, 0x8000
	v_cvt_pk_bf16_f32 v105, v16, v17
	v_lshlrev_b32_e32 v12, 4, v11
	v_mov_b32_e32 v13, v1
	v_add_co_u32_e32 v16, vcc, s0, v2
	v_lshl_add_u64 v[8:9], v[8:9], 0, v[12:13]
	s_nop 0
	v_addc_co_u32_e32 v17, vcc, 0, v3, vcc
	v_add_co_u32_e32 v28, vcc, s41, v8
	global_load_dwordx4 v[12:15], v[2:3], off
	s_nop 0
	global_load_dwordx4 v[16:19], v[16:17], off
	s_nop 0
	global_load_dwordx4 v[20:23], v[8:9], off
	v_addc_co_u32_e32 v29, vcc, 0, v9, vcc
	global_load_dwordx4 v[24:27], v[28:29], off
	v_mad_u64_u32 v[10:11], s[0:1], v10, s43, v[6:7]
	v_add_u32_e32 v135, 0, v10
	v_add_u32_e32 v136, 0, v4
	v_add_u32_e32 v4, 0x9000, v135
	s_waitcnt vmcnt(3)
	ds_write_b128 v136, v[12:15]
	s_waitcnt vmcnt(2)
	ds_write_b128 v136, v[16:19] offset:9216
	s_waitcnt vmcnt(1)
	ds_write2_b64 v4, v[20:21], v[22:23] offset1:2
	v_add_u32_e32 v4, 0xb000, v135
	s_mov_b32 s0, 0x10000
	s_waitcnt vmcnt(0)
	ds_write2_b64 v4, v[24:25], v[26:27] offset0:64 offset1:66
	v_mad_u32_u24 v4, v7, s42, 0
	v_add_u32_e32 v132, v4, v0
	v_lshl_add_u32 v4, v7, 7, v4
	v_add_u32_e32 v134, v4, v0
	v_add_co_u32_e32 v4, vcc, s0, v2
	s_mov_b32 s0, 0x18000
	s_nop 0
	v_addc_co_u32_e32 v5, vcc, 0, v3, vcc
	v_add_co_u32_e32 v2, vcc, s0, v2
	s_waitcnt lgkmcnt(0)
	s_nop 0
	v_addc_co_u32_e32 v3, vcc, 0, v3, vcc
	s_barrier
	global_load_dwordx4 v[66:69], v[4:5], off
	global_load_dwordx4 v[78:81], v[2:3], off
	global_load_dwordx4 v[74:77], v[8:9], off offset:256
	global_load_dwordx4 v[70:73], v[28:29], off offset:256
	ds_read_b128 v[2:5], v132 offset:4608
	ds_read_b128 v[6:9], v132
	ds_read_b128 v[34:37], v132 offset:32
	ds_read_b128 v[38:41], v132 offset:4640
	ds_read_b128 v[42:45], v132 offset:64
	ds_read_b128 v[46:49], v132 offset:4672
	ds_read_b128 v[50:53], v132 offset:96
	ds_read_b128 v[54:57], v132 offset:4704
	s_waitcnt lgkmcnt(6)
	v_mfma_f32_32x32x16_bf16 v[18:33], v[6:9], v[98:101], 0
	v_mfma_f32_32x32x16_bf16 v[2:17], v[2:5], v[98:101], 0
	s_waitcnt lgkmcnt(5)
	v_mfma_f32_32x32x16_bf16 v[18:33], v[34:37], v[102:105], v[18:33]
	s_waitcnt lgkmcnt(4)
	v_mfma_f32_32x32x16_bf16 v[2:17], v[38:41], v[102:105], v[2:17]
	s_waitcnt lgkmcnt(3)
	v_mfma_f32_32x32x16_bf16 v[18:33], v[42:45], v[106:109], v[18:33]
	s_waitcnt lgkmcnt(2)
	v_mfma_f32_32x32x16_bf16 v[2:17], v[46:49], v[106:109], v[2:17]
	s_waitcnt lgkmcnt(1)
	v_mfma_f32_32x32x16_bf16 v[18:33], v[50:53], v[110:113], v[18:33]
	s_waitcnt lgkmcnt(0)
	v_mfma_f32_32x32x16_bf16 v[2:17], v[54:57], v[110:113], v[2:17]
	ds_read_b128 v[34:37], v132 offset:9216
	ds_read_b128 v[82:85], v132 offset:9248
	ds_read_b128 v[38:41], v132 offset:13824
	ds_read_b128 v[86:89], v132 offset:13856
	ds_read_b128 v[90:93], v132 offset:9280
	ds_read_b128 v[94:97], v132 offset:9312
	ds_read_b128 v[114:117], v132 offset:13888
	ds_read_b128 v[118:121], v132 offset:13920
	s_waitcnt lgkmcnt(7)
	v_mfma_f32_32x32x16_bf16 v[50:65], v[34:37], v[98:101], 0
	s_waitcnt lgkmcnt(5)
	v_mfma_f32_32x32x16_bf16 v[34:49], v[38:41], v[98:101], 0
	v_mfma_f32_32x32x16_bf16 v[50:65], v[82:85], v[102:105], v[50:65]
	s_waitcnt lgkmcnt(4)
	v_mfma_f32_32x32x16_bf16 v[34:49], v[86:89], v[102:105], v[34:49]
	s_waitcnt lgkmcnt(3)
	v_mfma_f32_32x32x16_bf16 v[50:65], v[90:93], v[106:109], v[50:65]
	s_waitcnt lgkmcnt(1)
	v_mfma_f32_32x32x16_bf16 v[34:49], v[114:117], v[106:109], v[34:49]
	v_mfma_f32_32x32x16_bf16 v[50:65], v[94:97], v[110:113], v[50:65]
	s_waitcnt lgkmcnt(0)
	v_mfma_f32_32x32x16_bf16 v[34:49], v[118:121], v[110:113], v[34:49]
	ds_read_b128 v[82:85], v134 offset:36864
	ds_read_b128 v[86:89], v134 offset:36896
	ds_read_b128 v[90:93], v134 offset:36928
	ds_read_b128 v[94:97], v134 offset:36960
	ds_read_b128 v[114:117], v134 offset:45568
	ds_read_b128 v[118:121], v134 offset:45600
	ds_read_b128 v[122:125], v134 offset:45632
	ds_read_b128 v[126:129], v134 offset:45664
	v_max3_f32 v0, v18, v2, v19
	v_max_f32_e32 v137, v17, v17
	v_max3_f32 v0, v0, v3, v20
	s_mov_b32 s0, 0xf149f2ca
	v_max3_f32 v0, v0, v4, v21
	v_max3_f32 v0, v0, v5, v22
	v_max3_f32 v0, v0, v6, v23
	v_max3_f32 v0, v0, v7, v24
	v_max3_f32 v0, v0, v8, v25
	v_max3_f32 v0, v0, v9, v26
	v_max3_f32 v0, v0, v10, v27
	v_max3_f32 v0, v0, v11, v28
	v_max3_f32 v0, v0, v12, v29
	v_max3_f32 v0, v0, v13, v30
	v_max3_f32 v0, v0, v14, v31
	v_max3_f32 v0, v0, v15, v32
	v_max3_f32 v0, v0, v16, v33
	s_nop 0
	v_max_f32_e32 v0, v0, v0
	v_max_f32_e32 v0, v0, v137
	v_mov_b32_e32 v137, v0
	v_nop
	v_nop
	v_permlane32_swap_b32 v0, v137
	s_nop 0
	v_max3_f32 v0, v0, v137, s0
	v_sub_f32_e32 v2, v2, v0
	v_exp_f32_e32 v138, v2
	v_sub_f32_e32 v2, v19, v0
	v_exp_f32_e32 v139, v2
	v_sub_f32_e32 v2, v3, v0
	v_exp_f32_e32 v140, v2
	v_sub_f32_e32 v2, v20, v0
	v_exp_f32_e32 v141, v2
	v_sub_f32_e32 v2, v4, v0
	v_exp_f32_e32 v142, v2
	v_sub_f32_e32 v2, v21, v0
	v_exp_f32_e32 v143, v2
	v_sub_f32_e32 v2, v5, v0
	v_exp_f32_e32 v144, v2
	v_sub_f32_e32 v2, v22, v0
	v_exp_f32_e32 v145, v2
	v_sub_f32_e32 v2, v6, v0
	v_exp_f32_e32 v146, v2
	v_sub_f32_e32 v2, v23, v0
	v_exp_f32_e32 v147, v2
	v_sub_f32_e32 v2, v7, v0
	v_exp_f32_e32 v148, v2
	v_sub_f32_e32 v2, v24, v0
	v_exp_f32_e32 v149, v2
	v_sub_f32_e32 v2, v8, v0
	v_exp_f32_e32 v150, v2
	v_sub_f32_e32 v2, v25, v0
	v_exp_f32_e32 v151, v2
	v_sub_f32_e32 v2, v9, v0
	v_exp_f32_e32 v152, v2
	v_sub_f32_e32 v2, v26, v0
	v_exp_f32_e32 v153, v2
	v_sub_f32_e32 v2, v10, v0
	v_exp_f32_e32 v154, v2
	v_sub_f32_e32 v2, v27, v0
	v_exp_f32_e32 v155, v2
	v_sub_f32_e32 v2, v11, v0
	v_exp_f32_e32 v156, v2
	v_sub_f32_e32 v2, v28, v0
	v_exp_f32_e32 v157, v2
	v_sub_f32_e32 v2, v12, v0
	v_exp_f32_e32 v158, v2
	v_sub_f32_e32 v2, v29, v0
	v_exp_f32_e32 v159, v2
	v_sub_f32_e32 v2, v13, v0
	v_exp_f32_e32 v160, v2
	v_sub_f32_e32 v2, v30, v0
	v_exp_f32_e32 v161, v2
	v_sub_f32_e32 v2, v14, v0
	v_sub_f32_e32 v167, 0xf149f2ca, v0
	v_exp_f32_e32 v162, v2
	v_sub_f32_e32 v2, v31, v0
	v_exp_f32_e32 v163, v2
	v_sub_f32_e32 v2, v15, v0
	v_exp_f32_e32 v3, v167
	v_exp_f32_e32 v164, v2
	v_sub_f32_e32 v2, v32, v0
	v_exp_f32_e32 v165, v2
	v_sub_f32_e32 v2, v16, v0
	v_exp_f32_e32 v166, v2
	v_sub_f32_e32 v2, v33, v0
	v_sub_f32_e32 v18, v18, v0
	v_exp_f32_e32 v167, v2
	v_sub_f32_e32 v2, v17, v0
	v_cmp_neq_f32_e32 vcc, 1.0, v3
	v_exp_f32_e32 v137, v18
	v_exp_f32_e32 v169, v2
	s_cmp_lg_u64 vcc, 0
	v_mul_f32_e32 v168, 0, v3
	s_cselect_b64 vcc, -1, 0
	v_cndmask_b32_e32 v2, 0, v168, vcc
	v_mov_b32_e32 v3, v2
	v_mov_b32_e32 v4, v2
	v_mov_b32_e32 v5, v2
	v_mov_b32_e32 v6, v2
	v_mov_b32_e32 v7, v2
	v_mov_b32_e32 v8, v2
	v_mov_b32_e32 v9, v2
	v_mov_b32_e32 v10, v2
	v_mov_b32_e32 v11, v2
	v_mov_b32_e32 v12, v2
	v_mov_b32_e32 v13, v2
	v_mov_b32_e32 v14, v2
	v_mov_b32_e32 v15, v2
	v_mov_b32_e32 v16, v2
	v_mov_b32_e32 v17, v2
	v_cvt_pk_bf16_f32 v170, v154, v156
	v_cvt_pk_bf16_f32 v171, v158, v160
	v_cvt_pk_bf16_f32 v172, v162, v164
	v_cvt_pk_bf16_f32 v173, v166, v169
	v_cvt_pk_bf16_f32 v174, v138, v140
	v_cvt_pk_bf16_f32 v175, v142, v144
	v_cvt_pk_bf16_f32 v176, v146, v148
	v_cvt_pk_bf16_f32 v177, v150, v152
	v_cvt_pk_bf16_f32 v178, v153, v155
	v_cvt_pk_bf16_f32 v179, v157, v159
	v_cvt_pk_bf16_f32 v180, v161, v163
	v_cvt_pk_bf16_f32 v181, v165, v167
	v_cvt_pk_bf16_f32 v182, v137, v139
	v_cvt_pk_bf16_f32 v183, v141, v143
	v_cvt_pk_bf16_f32 v184, v145, v147
	v_cvt_pk_bf16_f32 v185, v149, v151
	s_waitcnt lgkmcnt(7)
	s_nop 0
	v_mfma_f32_32x32x16_bf16 v[18:33], v[82:85], v[182:185], v[2:17]
	s_waitcnt lgkmcnt(3)
	v_mfma_f32_32x32x16_bf16 v[2:17], v[114:117], v[182:185], v[2:17]
	v_mfma_f32_32x32x16_bf16 v[18:33], v[86:89], v[178:181], v[18:33]
	s_waitcnt lgkmcnt(2)
	v_mfma_f32_32x32x16_bf16 v[2:17], v[118:121], v[178:181], v[2:17]
	v_mfma_f32_32x32x16_bf16 v[18:33], v[90:93], v[174:177], v[18:33]
	s_waitcnt lgkmcnt(1)
	v_mfma_f32_32x32x16_bf16 v[2:17], v[122:125], v[174:177], v[2:17]
	v_mfma_f32_32x32x16_bf16 v[18:33], v[94:97], v[170:173], v[18:33]
	s_waitcnt lgkmcnt(0)
	v_mfma_f32_32x32x16_bf16 v[2:17], v[126:129], v[170:173], v[2:17]
	ds_read_b128 v[126:129], v134 offset:36992
	ds_read_b128 v[122:125], v134 offset:37024
	ds_read_b128 v[118:121], v134 offset:37056
	ds_read_b128 v[114:117], v134 offset:37088
	ds_read_b128 v[94:97], v134 offset:45696
	ds_read_b128 v[90:93], v134 offset:45728
	ds_read_b128 v[86:89], v134 offset:45760
	ds_read_b128 v[82:85], v134 offset:45792
	v_max3_f32 v170, v50, v34, v51
	v_max_f32_e32 v171, v49, v49
	v_max3_f32 v170, v170, v35, v52
	v_max3_f32 v170, v170, v36, v53
	v_max3_f32 v170, v170, v37, v54
	v_max3_f32 v170, v170, v38, v55
	v_max3_f32 v170, v170, v39, v56
	v_max3_f32 v170, v170, v40, v57
	v_max3_f32 v170, v170, v41, v58
	v_max3_f32 v170, v170, v42, v59
	v_max3_f32 v170, v170, v43, v60
	v_max3_f32 v170, v170, v44, v61
	v_max3_f32 v170, v170, v45, v62
	v_max3_f32 v170, v170, v46, v63
	v_max3_f32 v170, v170, v47, v64
	v_max3_f32 v170, v170, v48, v65
	s_nop 0
	v_max_f32_e32 v170, v170, v170
	v_max_f32_e32 v170, v170, v171
	v_mov_b32_e32 v171, v170
	v_nop
	v_nop
	v_permlane32_swap_b32 v170, v171
	s_nop 0
	v_max3_f32 v208, v0, v170, v171
	v_sub_f32_e32 v0, v0, v208
	v_exp_f32_e32 v0, v0
	s_nop 0
	v_cmp_neq_f32_e32 vcc, 1.0, v0
	s_cbranch_vccz .LBB0_125
	v_mul_f32_e32 v32, v0, v32
	v_mul_f32_e32 v33, v0, v33
	v_mul_f32_e32 v30, v0, v30
	v_mul_f32_e32 v31, v0, v31
	v_mul_f32_e32 v28, v0, v28
	v_mul_f32_e32 v29, v0, v29
	v_mul_f32_e32 v26, v0, v26
	v_mul_f32_e32 v27, v0, v27
	v_mul_f32_e32 v24, v0, v24
	v_mul_f32_e32 v25, v0, v25
	v_mul_f32_e32 v22, v0, v22
	v_mul_f32_e32 v23, v0, v23
	v_mul_f32_e32 v20, v0, v20
	v_mul_f32_e32 v21, v0, v21
	v_mul_f32_e32 v18, v0, v18
	v_mul_f32_e32 v19, v0, v19
	v_mul_f32_e32 v16, v0, v16
	v_mul_f32_e32 v17, v0, v17
	v_mul_f32_e32 v14, v0, v14
	v_mul_f32_e32 v15, v0, v15
	v_mul_f32_e32 v12, v0, v12
	v_mul_f32_e32 v13, v0, v13
	v_mul_f32_e32 v10, v0, v10
	v_mul_f32_e32 v11, v0, v11
	v_mul_f32_e32 v8, v0, v8
	v_mul_f32_e32 v9, v0, v9
	v_mul_f32_e32 v6, v0, v6
	v_mul_f32_e32 v7, v0, v7
	v_mul_f32_e32 v4, v0, v4
	v_mul_f32_e32 v5, v0, v5
	v_mul_f32_e32 v2, v0, v2
	v_mul_f32_e32 v3, v0, v3
.LBB0_125:
	v_sub_f32_e32 v34, v34, v208
	v_exp_f32_e32 v171, v34
	v_sub_f32_e32 v34, v51, v208
	v_exp_f32_e32 v172, v34
	v_sub_f32_e32 v34, v35, v208
	v_exp_f32_e32 v173, v34
	v_sub_f32_e32 v34, v52, v208
	v_exp_f32_e32 v174, v34
	v_sub_f32_e32 v34, v36, v208
	v_exp_f32_e32 v175, v34
	v_sub_f32_e32 v34, v53, v208
	v_exp_f32_e32 v176, v34
	v_sub_f32_e32 v34, v37, v208
	v_exp_f32_e32 v177, v34
	v_sub_f32_e32 v34, v54, v208
	v_exp_f32_e32 v178, v34
	v_sub_f32_e32 v34, v38, v208
	v_exp_f32_e32 v179, v34
	v_sub_f32_e32 v34, v55, v208
	v_exp_f32_e32 v180, v34
	v_sub_f32_e32 v34, v39, v208
	v_exp_f32_e32 v181, v34
	v_sub_f32_e32 v34, v56, v208
	v_exp_f32_e32 v182, v34
	v_sub_f32_e32 v34, v40, v208
	v_exp_f32_e32 v183, v34
	v_sub_f32_e32 v34, v57, v208
	v_exp_f32_e32 v184, v34
	v_sub_f32_e32 v34, v41, v208
	v_exp_f32_e32 v185, v34
	v_sub_f32_e32 v34, v58, v208
	v_exp_f32_e32 v186, v34
	v_sub_f32_e32 v34, v42, v208
	v_exp_f32_e32 v187, v34
	v_sub_f32_e32 v34, v59, v208
	v_exp_f32_e32 v188, v34
	v_sub_f32_e32 v34, v43, v208
	v_exp_f32_e32 v189, v34
	v_sub_f32_e32 v34, v60, v208
	v_exp_f32_e32 v190, v34
	v_sub_f32_e32 v34, v44, v208
	v_exp_f32_e32 v191, v34
	v_sub_f32_e32 v34, v61, v208
	v_exp_f32_e32 v192, v34
	v_sub_f32_e32 v34, v45, v208
	v_exp_f32_e32 v193, v34
	v_sub_f32_e32 v34, v62, v208
	v_exp_f32_e32 v194, v34
	v_sub_f32_e32 v34, v46, v208
	v_exp_f32_e32 v195, v34
	v_sub_f32_e32 v34, v63, v208
	v_exp_f32_e32 v202, v34
	v_sub_f32_e32 v34, v47, v208
	v_exp_f32_e32 v203, v34
	v_sub_f32_e32 v34, v64, v208
	v_exp_f32_e32 v204, v34
	v_sub_f32_e32 v34, v48, v208
	v_exp_f32_e32 v205, v34
	v_sub_f32_e32 v34, v65, v208
	v_sub_f32_e32 v50, v50, v208
	v_exp_f32_e32 v206, v34
	v_sub_f32_e32 v34, v49, v208
	v_exp_f32_e32 v170, v50
	v_exp_f32_e32 v207, v34
	v_cvt_pk_bf16_f32 v34, v187, v189
	v_cvt_pk_bf16_f32 v35, v191, v193
	v_cvt_pk_bf16_f32 v36, v195, v203
	v_cvt_pk_bf16_f32 v37, v205, v207
	v_cvt_pk_bf16_f32 v38, v171, v173
	v_cvt_pk_bf16_f32 v39, v175, v177
	v_cvt_pk_bf16_f32 v40, v179, v181
	v_cvt_pk_bf16_f32 v41, v183, v185
	v_cvt_pk_bf16_f32 v42, v186, v188
	v_cvt_pk_bf16_f32 v43, v190, v192
	v_cvt_pk_bf16_f32 v44, v194, v202
	v_cvt_pk_bf16_f32 v45, v204, v206
	v_cvt_pk_bf16_f32 v46, v170, v172
	v_cvt_pk_bf16_f32 v47, v174, v176
	v_cvt_pk_bf16_f32 v48, v178, v180
	v_cvt_pk_bf16_f32 v49, v182, v184
	s_waitcnt lgkmcnt(7)
	s_nop 0
	v_mfma_f32_32x32x16_bf16 v[18:33], v[126:129], v[46:49], v[18:33]
	s_waitcnt lgkmcnt(3)
	v_mfma_f32_32x32x16_bf16 v[2:17], v[94:97], v[46:49], v[2:17]
	v_mfma_f32_32x32x16_bf16 v[18:33], v[122:125], v[42:45], v[18:33]
	s_waitcnt lgkmcnt(2)
	v_mfma_f32_32x32x16_bf16 v[2:17], v[90:93], v[42:45], v[2:17]
	v_mfma_f32_32x32x16_bf16 v[18:33], v[118:121], v[38:41], v[18:33]
	s_waitcnt lgkmcnt(1)
	v_mfma_f32_32x32x16_bf16 v[2:17], v[86:89], v[38:41], v[2:17]
	v_mfma_f32_32x32x16_bf16 v[18:33], v[114:117], v[34:37], v[18:33]
	s_waitcnt lgkmcnt(0)
	v_mfma_f32_32x32x16_bf16 v[2:17], v[82:85], v[34:37], v[2:17]
	v_add_u32_e32 v34, 0xd000, v135
	s_waitcnt vmcnt(3)
	ds_write_b128 v136, v[66:69] offset:18432
	s_waitcnt vmcnt(2)
	ds_write_b128 v136, v[78:81] offset:27648
	s_waitcnt vmcnt(1)
	ds_write2_b64 v34, v[74:75], v[76:77] offset0:128 offset1:130
	v_add_u32_e32 v34, 0xf000, v135
	s_waitcnt vmcnt(0)
	ds_write2_b64 v34, v[70:71], v[72:73] offset0:192 offset1:194
	s_waitcnt lgkmcnt(0)
	s_barrier
	ds_read_b128 v[34:37], v132 offset:18432
	ds_read_b128 v[38:41], v132 offset:18464
	ds_read_b128 v[42:45], v132 offset:23040
	ds_read_b128 v[46:49], v132 offset:23072
	ds_read_b128 v[50:53], v132 offset:18496
	ds_read_b128 v[54:57], v132 offset:18528
	ds_read_b128 v[58:61], v132 offset:23104
	ds_read_b128 v[62:65], v132 offset:23136
	s_waitcnt lgkmcnt(7)
	v_mfma_f32_32x32x16_bf16 v[82:97], v[34:37], v[98:101], 0
	s_waitcnt lgkmcnt(5)
	v_mfma_f32_32x32x16_bf16 v[66:81], v[42:45], v[98:101], 0
	v_mfma_f32_32x32x16_bf16 v[82:97], v[38:41], v[102:105], v[82:97]
	s_waitcnt lgkmcnt(4)
	v_mfma_f32_32x32x16_bf16 v[66:81], v[46:49], v[102:105], v[66:81]
	s_waitcnt lgkmcnt(3)
	v_mfma_f32_32x32x16_bf16 v[82:97], v[50:53], v[106:109], v[82:97]
	s_waitcnt lgkmcnt(1)
	v_mfma_f32_32x32x16_bf16 v[66:81], v[58:61], v[106:109], v[66:81]
	v_mfma_f32_32x32x16_bf16 v[82:97], v[54:57], v[110:113], v[82:97]
	s_waitcnt lgkmcnt(0)
	v_mfma_f32_32x32x16_bf16 v[66:81], v[62:65], v[110:113], v[66:81]
	ds_read_b128 v[34:37], v132 offset:27648
	ds_read_b128 v[114:117], v132 offset:27680
	ds_read_b128 v[38:41], v132 offset:32256
	ds_read_b128 v[118:121], v132 offset:32288
	ds_read_b128 v[122:125], v132 offset:27712
	ds_read_b128 v[126:129], v132 offset:27744
	ds_read_b128 v[198:201], v132 offset:32320
	ds_read_b128 v[210:213], v132 offset:32352
	s_waitcnt lgkmcnt(7)
	v_mfma_f32_32x32x16_bf16 v[50:65], v[34:37], v[98:101], 0
	s_waitcnt lgkmcnt(5)
	v_mfma_f32_32x32x16_bf16 v[34:49], v[38:41], v[98:101], 0
	v_mfma_f32_32x32x16_bf16 v[50:65], v[114:117], v[102:105], v[50:65]
	s_waitcnt lgkmcnt(4)
	v_mfma_f32_32x32x16_bf16 v[34:49], v[118:121], v[102:105], v[34:49]
	s_waitcnt lgkmcnt(3)
	v_mfma_f32_32x32x16_bf16 v[50:65], v[122:125], v[106:109], v[50:65]
	s_waitcnt lgkmcnt(1)
	v_mfma_f32_32x32x16_bf16 v[34:49], v[198:201], v[106:109], v[34:49]
	v_mfma_f32_32x32x16_bf16 v[50:65], v[126:129], v[110:113], v[50:65]
	s_waitcnt lgkmcnt(0)
	v_mfma_f32_32x32x16_bf16 v[34:49], v[210:213], v[110:113], v[34:49]
	ds_read_b128 v[126:129], v134 offset:54272
	ds_read_b128 v[122:125], v134 offset:54304
	ds_read_b128 v[118:121], v134 offset:54336
	ds_read_b128 v[114:117], v134 offset:54368
	ds_read_b128 v[110:113], v134 offset:62976
	ds_read_b128 v[106:109], v134 offset:63008
	ds_read_b128 v[102:105], v134 offset:63040
	ds_read_b128 v[98:101], v134 offset:63072
	v_max3_f32 v132, v82, v66, v83
	v_max_f32_e32 v135, v81, v81
	v_max3_f32 v132, v132, v67, v84
	v_max3_f32 v132, v132, v68, v85
	v_max3_f32 v132, v132, v69, v86
	v_max3_f32 v132, v132, v70, v87
	v_max3_f32 v132, v132, v71, v88
	v_max3_f32 v132, v132, v72, v89
	v_max3_f32 v132, v132, v73, v90
	v_max3_f32 v132, v132, v74, v91
	v_max3_f32 v132, v132, v75, v92
	v_max3_f32 v132, v132, v76, v93
	v_max3_f32 v132, v132, v77, v94
	v_max3_f32 v132, v132, v78, v95
	v_max3_f32 v132, v132, v79, v96
	v_max3_f32 v132, v132, v80, v97
	s_nop 0
	v_max_f32_e32 v132, v132, v132
	v_max_f32_e32 v132, v132, v135
	v_mov_b32_e32 v135, v132
	v_nop
	v_nop
	v_permlane32_swap_b32 v132, v135
	s_nop 0
	v_max3_f32 v247, v208, v132, v135
	v_sub_f32_e32 v132, v208, v247
	v_exp_f32_e32 v132, v132
	s_nop 0
	v_cmp_neq_f32_e32 vcc, 1.0, v132
	s_cbranch_vccz .LBB0_127
	v_mul_f32_e32 v32, v132, v32
	v_mul_f32_e32 v33, v132, v33
	v_mul_f32_e32 v30, v132, v30
	v_mul_f32_e32 v31, v132, v31
	v_mul_f32_e32 v28, v132, v28
	v_mul_f32_e32 v29, v132, v29
	v_mul_f32_e32 v26, v132, v26
	v_mul_f32_e32 v27, v132, v27
	v_mul_f32_e32 v24, v132, v24
	v_mul_f32_e32 v25, v132, v25
	v_mul_f32_e32 v22, v132, v22
	v_mul_f32_e32 v23, v132, v23
	v_mul_f32_e32 v20, v132, v20
	v_mul_f32_e32 v21, v132, v21
	v_mul_f32_e32 v18, v132, v18
	v_mul_f32_e32 v19, v132, v19
	v_mul_f32_e32 v16, v132, v16
	v_mul_f32_e32 v17, v132, v17
	v_mul_f32_e32 v14, v132, v14
	v_mul_f32_e32 v15, v132, v15
	v_mul_f32_e32 v12, v132, v12
	v_mul_f32_e32 v13, v132, v13
	v_mul_f32_e32 v10, v132, v10
	v_mul_f32_e32 v11, v132, v11
	v_mul_f32_e32 v8, v132, v8
	v_mul_f32_e32 v9, v132, v9
	v_mul_f32_e32 v6, v132, v6
	v_mul_f32_e32 v7, v132, v7
	v_mul_f32_e32 v4, v132, v4
	v_mul_f32_e32 v5, v132, v5
	v_mul_f32_e32 v2, v132, v2
	v_mul_f32_e32 v3, v132, v3
.LBB0_127:
	v_sub_f32_e32 v66, v66, v247
	v_exp_f32_e32 v136, v66
	v_sub_f32_e32 v66, v83, v247
	v_exp_f32_e32 v208, v66
	v_sub_f32_e32 v66, v67, v247
	v_exp_f32_e32 v209, v66
	v_sub_f32_e32 v66, v84, v247
	v_exp_f32_e32 v219, v66
	v_sub_f32_e32 v66, v68, v247
	v_exp_f32_e32 v220, v66
	v_sub_f32_e32 v66, v85, v247
	v_exp_f32_e32 v221, v66
	v_sub_f32_e32 v66, v69, v247
	v_exp_f32_e32 v222, v66
	v_sub_f32_e32 v66, v86, v247
	v_exp_f32_e32 v223, v66
	v_sub_f32_e32 v66, v70, v247
	v_exp_f32_e32 v224, v66
	v_sub_f32_e32 v66, v87, v247
	v_exp_f32_e32 v225, v66
	v_sub_f32_e32 v66, v71, v247
	v_exp_f32_e32 v226, v66
	v_sub_f32_e32 v66, v88, v247
	v_exp_f32_e32 v227, v66
	v_sub_f32_e32 v66, v72, v247
	v_exp_f32_e32 v228, v66
	v_sub_f32_e32 v66, v89, v247
	v_exp_f32_e32 v229, v66
	v_sub_f32_e32 v66, v73, v247
	v_exp_f32_e32 v230, v66
	v_sub_f32_e32 v66, v90, v247
	v_exp_f32_e32 v231, v66
	v_sub_f32_e32 v66, v74, v247
	v_exp_f32_e32 v232, v66
	v_sub_f32_e32 v66, v91, v247
	v_exp_f32_e32 v233, v66
	v_sub_f32_e32 v66, v75, v247
	v_exp_f32_e32 v234, v66
	v_sub_f32_e32 v66, v92, v247
	v_exp_f32_e32 v235, v66
	v_sub_f32_e32 v66, v76, v247
	v_exp_f32_e32 v236, v66
	v_sub_f32_e32 v66, v93, v247
	v_exp_f32_e32 v237, v66
	v_sub_f32_e32 v66, v77, v247
	v_exp_f32_e32 v238, v66
	v_sub_f32_e32 v66, v94, v247
	v_exp_f32_e32 v239, v66
	v_sub_f32_e32 v66, v78, v247
	v_exp_f32_e32 v240, v66
	v_sub_f32_e32 v66, v95, v247
	v_exp_f32_e32 v241, v66
	v_sub_f32_e32 v66, v79, v247
	v_exp_f32_e32 v242, v66
	v_sub_f32_e32 v66, v96, v247
	v_exp_f32_e32 v243, v66
	v_sub_f32_e32 v66, v80, v247
	v_exp_f32_e32 v244, v66
	v_sub_f32_e32 v66, v97, v247
	v_sub_f32_e32 v82, v82, v247
	v_exp_f32_e32 v245, v66
	v_sub_f32_e32 v66, v81, v247
	v_exp_f32_e32 v135, v82
	v_exp_f32_e32 v246, v66
	v_cvt_pk_bf16_f32 v66, v232, v234
	v_cvt_pk_bf16_f32 v67, v236, v238
	v_cvt_pk_bf16_f32 v68, v240, v242
	v_cvt_pk_bf16_f32 v69, v244, v246
	v_cvt_pk_bf16_f32 v70, v136, v209
	v_cvt_pk_bf16_f32 v71, v220, v222
	v_cvt_pk_bf16_f32 v72, v224, v226
	v_cvt_pk_bf16_f32 v73, v228, v230
	v_cvt_pk_bf16_f32 v74, v231, v233
	v_cvt_pk_bf16_f32 v75, v235, v237
	v_cvt_pk_bf16_f32 v76, v239, v241
	v_cvt_pk_bf16_f32 v77, v243, v245
	v_cvt_pk_bf16_f32 v78, v135, v208
	v_cvt_pk_bf16_f32 v79, v219, v221
	v_cvt_pk_bf16_f32 v80, v223, v225
	v_cvt_pk_bf16_f32 v81, v227, v229
	s_waitcnt lgkmcnt(7)
	s_nop 0
	v_mfma_f32_32x32x16_bf16 v[18:33], v[126:129], v[78:81], v[18:33]
	s_waitcnt lgkmcnt(3)
	v_mfma_f32_32x32x16_bf16 v[2:17], v[110:113], v[78:81], v[2:17]
	v_mfma_f32_32x32x16_bf16 v[18:33], v[122:125], v[74:77], v[18:33]
	s_waitcnt lgkmcnt(2)
	v_mfma_f32_32x32x16_bf16 v[2:17], v[106:109], v[74:77], v[2:17]
	v_mfma_f32_32x32x16_bf16 v[18:33], v[118:121], v[70:73], v[18:33]
	s_waitcnt lgkmcnt(1)
	v_mfma_f32_32x32x16_bf16 v[2:17], v[102:105], v[70:73], v[2:17]
	v_mfma_f32_32x32x16_bf16 v[18:33], v[114:117], v[66:69], v[18:33]
	s_waitcnt lgkmcnt(0)
	v_mfma_f32_32x32x16_bf16 v[2:17], v[98:101], v[66:69], v[2:17]
	ds_read_b128 v[94:97], v134 offset:54400
	ds_read_b128 v[90:93], v134 offset:54432
	ds_read_b128 v[86:89], v134 offset:54464
	ds_read_b128 v[82:85], v134 offset:54496
	ds_read_b128 v[78:81], v134 offset:63104
	ds_read_b128 v[74:77], v134 offset:63136
	ds_read_b128 v[70:73], v134 offset:63168
	ds_read_b128 v[66:69], v134 offset:63200
	v_max3_f32 v98, v50, v34, v51
	v_max_f32_e32 v99, v49, v49
	v_max3_f32 v98, v98, v35, v52
	v_max3_f32 v98, v98, v36, v53
	v_max3_f32 v98, v98, v37, v54
	v_max3_f32 v98, v98, v38, v55
	v_max3_f32 v98, v98, v39, v56
	v_max3_f32 v98, v98, v40, v57
	v_max3_f32 v98, v98, v41, v58
	v_max3_f32 v98, v98, v42, v59
	v_max3_f32 v98, v98, v43, v60
	v_max3_f32 v98, v98, v44, v61
	v_max3_f32 v98, v98, v45, v62
	v_max3_f32 v98, v98, v46, v63
	v_max3_f32 v98, v98, v47, v64
	v_max3_f32 v98, v98, v48, v65
	s_nop 0
	v_max_f32_e32 v98, v98, v98
	v_max_f32_e32 v98, v98, v99
	v_mov_b32_e32 v99, v98
	v_nop
	v_nop
	v_permlane32_swap_b32 v99, v98
	s_nop 0
	v_max3_f32 v99, v247, v99, v98
	v_sub_f32_e32 v98, v247, v99
	v_exp_f32_e32 v98, v98
	s_nop 0
	v_cmp_neq_f32_e32 vcc, 1.0, v98
	s_cbranch_vccz .LBB0_122
	v_mul_f32_e32 v32, v98, v32
	v_mul_f32_e32 v33, v98, v33
	v_mul_f32_e32 v30, v98, v30
	v_mul_f32_e32 v31, v98, v31
	v_mul_f32_e32 v28, v98, v28
	v_mul_f32_e32 v29, v98, v29
	v_mul_f32_e32 v26, v98, v26
	v_mul_f32_e32 v27, v98, v27
	v_mul_f32_e32 v24, v98, v24
	v_mul_f32_e32 v25, v98, v25
	v_mul_f32_e32 v22, v98, v22
	v_mul_f32_e32 v23, v98, v23
	v_mul_f32_e32 v20, v98, v20
	v_mul_f32_e32 v21, v98, v21
	v_mul_f32_e32 v18, v98, v18
	v_mul_f32_e32 v19, v98, v19
	v_mul_f32_e32 v16, v98, v16
	v_mul_f32_e32 v17, v98, v17
	v_mul_f32_e32 v14, v98, v14
	v_mul_f32_e32 v15, v98, v15
	v_mul_f32_e32 v12, v98, v12
	v_mul_f32_e32 v13, v98, v13
	v_mul_f32_e32 v10, v98, v10
	v_mul_f32_e32 v11, v98, v11
	v_mul_f32_e32 v8, v98, v8
	v_mul_f32_e32 v9, v98, v9
	v_mul_f32_e32 v6, v98, v6
	v_mul_f32_e32 v7, v98, v7
	v_mul_f32_e32 v4, v98, v4
	v_mul_f32_e32 v5, v98, v5
	v_mul_f32_e32 v2, v98, v2
	v_mul_f32_e32 v3, v98, v3
	s_branch .LBB0_122

.LBB0_136:
	v_mov_b32_e32 v66, v204
	v_nop
	v_nop
	v_permlane32_swap_b32 v204, v66
	s_mov_b32 s3, s81
	v_add_f32_e32 v66, v204, v66
	v_div_scale_f32 v67, s[0:1], v66, v66, 1.0
	v_rcp_f32_e32 v68, v67
	s_waitcnt vmcnt(0)
	v_mov_b32_e32 v87, v56
	v_mov_b32_e32 v56, v55
	v_fma_f32 v69, -v67, v68, 1.0
	v_fmac_f32_e32 v68, v69, v68
	v_div_scale_f32 v69, vcc, 1.0, v66, 1.0
	v_mul_f32_e32 v70, v69, v68
	v_fma_f32 v71, -v67, v70, v69
	v_fmac_f32_e32 v70, v71, v68
	v_fma_f32 v67, -v67, v70, v69
	v_div_fmas_f32 v67, v67, v68, v70
	v_div_fixup_f32 v70, v67, v66, 1.0
	v_or_b32_e32 v66, s31, v193
	v_add_u32_e32 v66, v66, v194
	v_ashrrev_i32_e32 v67, 31, v66
	v_lshlrev_b64 v[84:85], 11, v[66:67]
	v_lshl_add_u64 v[66:67], s[18:19], 0, v[84:85]
	v_lshl_add_u64 v[66:67], v[66:67], 0, s[2:3]
	v_lshl_add_u64 v[94:95], v[66:67], 0, v[0:1]
	global_load_dwordx2 v[72:73], v1, s[50:51]
	global_load_dwordx2 v[82:83], v[94:95], off
	global_load_dwordx2 v[80:81], v[94:95], off offset:16
	global_load_dwordx2 v[76:77], v[94:95], off offset:32
	global_load_dwordx2 v[74:75], v[94:95], off offset:48
	global_load_dwordx2 v[66:67], v[94:95], off offset:64
	v_mov_b32_e32 v86, v54
	v_pk_mul_f32 v[54:55], v[56:57], v[70:71] op_sel_hi:[1,0]
	v_mul_f32_e32 v86, v70, v86
	v_mul_f32_e32 v87, v70, v87
	v_mov_b32_e32 v89, v60
	v_mov_b32_e32 v60, v59
	v_mov_b32_e32 v88, v58
	v_pk_mul_f32 v[58:59], v[60:61], v[70:71] op_sel_hi:[1,0]
	v_mul_f32_e32 v88, v70, v88
	v_mul_f32_e32 v89, v70, v89
	v_mov_b32_e32 v91, v64
	v_mov_b32_e32 v64, v63
	v_mov_b32_e32 v90, v62
	v_pk_mul_f32 v[62:63], v[64:65], v[70:71] op_sel_hi:[1,0]
	v_mul_f32_e32 v90, v70, v90
	v_mul_f32_e32 v91, v70, v91
	v_mov_b32_e32 v97, v40
	v_mov_b32_e32 v40, v39
	v_mov_b32_e32 v96, v38
	v_pk_mul_f32 v[38:39], v[40:41], v[70:71] op_sel_hi:[1,0]
	v_mul_f32_e32 v96, v70, v96
	v_mul_f32_e32 v97, v70, v97
	v_mov_b32_e32 v99, v44
	v_mov_b32_e32 v44, v43
	v_mov_b32_e32 v98, v42
	v_pk_mul_f32 v[42:43], v[44:45], v[70:71] op_sel_hi:[1,0]
	v_mul_f32_e32 v98, v70, v98
	v_mul_f32_e32 v99, v70, v99
	v_mov_b32_e32 v101, v48
	v_mov_b32_e32 v48, v47
	v_mov_b32_e32 v100, v46
	v_pk_mul_f32 v[46:47], v[48:49], v[70:71] op_sel_hi:[1,0]
	v_mul_f32_e32 v100, v70, v100
	v_mul_f32_e32 v101, v70, v101
	v_mov_b32_e32 v105, v24
	v_mov_b32_e32 v24, v23
	v_mov_b32_e32 v104, v22
	v_pk_mul_f32 v[22:23], v[24:25], v[70:71] op_sel_hi:[1,0]
	v_mul_f32_e32 v104, v70, v104
	v_mul_f32_e32 v105, v70, v105
	v_mov_b32_e32 v107, v28
	v_mov_b32_e32 v28, v27
	v_mov_b32_e32 v106, v26
	v_pk_mul_f32 v[26:27], v[28:29], v[70:71] op_sel_hi:[1,0]
	v_mul_f32_e32 v106, v70, v106
	v_mul_f32_e32 v107, v70, v107
	v_readlane_b32 s0, v254, 63
	v_readlane_b32 s1, v255, 0
	v_mul_f32_e32 v4, v70, v4
	v_mul_f32_e32 v5, v70, v5
	v_mul_f32_e32 v2, v70, v2
	v_mul_f32_e32 v3, v70, v3
	v_mul_f32_e32 v8, v70, v8
	v_mul_f32_e32 v9, v70, v9
	v_mul_f32_e32 v6, v70, v6
	v_mul_f32_e32 v7, v70, v7
	v_mul_f32_e32 v12, v70, v12
	v_mul_f32_e32 v13, v70, v13
	v_mul_f32_e32 v10, v70, v10
	v_mul_f32_e32 v11, v70, v11
	v_mul_f32_e32 v16, v70, v16
	v_mul_f32_e32 v17, v70, v17
	v_mul_f32_e32 v14, v70, v14
	v_mul_f32_e32 v15, v70, v15
	s_add_i32 s29, s29, s20
	s_add_i32 s21, s21, s28
	s_cmpk_lt_i32 s29, 0x100
	s_waitcnt vmcnt(0)
	v_lshlrev_b32_e32 v69, 16, v67
	v_and_b32_e32 v79, 0xffff0000, v67
	v_mov_b32_e32 v67, v52
	v_mov_b32_e32 v52, v51
	v_lshlrev_b32_e32 v68, 16, v66
	v_and_b32_e32 v78, 0xffff0000, v66
	v_mov_b32_e32 v66, v50
	v_pk_mul_f32 v[50:51], v[52:53], v[70:71] op_sel_hi:[1,0]
	v_mul_f32_e32 v66, v70, v66
	v_mul_f32_e32 v67, v70, v67
	v_pk_fma_f32 v[50:51], v[72:73], v[50:51], v[78:79] op_sel_hi:[0,1,1] neg_lo:[1,0,0] neg_hi:[1,0,0]
	v_pk_fma_f32 v[66:67], v[72:73], v[66:67], v[68:69] op_sel_hi:[0,1,1] neg_lo:[1,0,0] neg_hi:[1,0,0]
	v_pk_mul_f32 v[52:53], v[50:51], v[50:51]
	s_nop 0
	v_pk_fma_f32 v[52:53], v[66:67], v[66:67], v[52:53]
	s_nop 0
	v_pk_add_f32 v[78:79], v[52:53], v[52:53] op_sel:[0,1] op_sel_hi:[1,0]
	global_load_dwordx2 v[52:53], v[94:95], off offset:80
	s_waitcnt vmcnt(0)
	v_lshlrev_b32_e32 v69, 16, v53
	v_lshlrev_b32_e32 v68, 16, v52
	v_and_b32_e32 v53, 0xffff0000, v53
	v_and_b32_e32 v52, 0xffff0000, v52
	v_pk_fma_f32 v[52:53], v[72:73], v[54:55], v[52:53] op_sel_hi:[0,1,1] neg_lo:[1,0,0] neg_hi:[1,0,0]
	v_pk_fma_f32 v[68:69], v[72:73], v[86:87], v[68:69] op_sel_hi:[0,1,1] neg_lo:[1,0,0] neg_hi:[1,0,0]
	v_pk_mul_f32 v[54:55], v[52:53], v[52:53]
	s_nop 0
	v_pk_fma_f32 v[54:55], v[68:69], v[68:69], v[54:55]
	s_nop 0
	v_pk_add_f32 v[86:87], v[54:55], v[54:55] op_sel:[0,1] op_sel_hi:[1,0]
	global_load_dwordx2 v[54:55], v[94:95], off offset:96
	s_waitcnt vmcnt(0)
	v_lshlrev_b32_e32 v57, 16, v55
	v_lshlrev_b32_e32 v56, 16, v54
	v_and_b32_e32 v55, 0xffff0000, v55
	v_and_b32_e32 v54, 0xffff0000, v54
	v_pk_fma_f32 v[54:55], v[72:73], v[58:59], v[54:55] op_sel_hi:[0,1,1] neg_lo:[1,0,0] neg_hi:[1,0,0]
	v_pk_fma_f32 v[56:57], v[72:73], v[88:89], v[56:57] op_sel_hi:[0,1,1] neg_lo:[1,0,0] neg_hi:[1,0,0]
	v_pk_mul_f32 v[58:59], v[54:55], v[54:55]
	s_nop 0
	v_pk_fma_f32 v[58:59], v[56:57], v[56:57], v[58:59]
	s_nop 0
	v_pk_add_f32 v[88:89], v[58:59], v[58:59] op_sel:[0,1] op_sel_hi:[1,0]
	global_load_dwordx2 v[58:59], v[94:95], off offset:112
	s_waitcnt vmcnt(0)
	v_lshlrev_b32_e32 v61, 16, v59
	v_lshlrev_b32_e32 v60, 16, v58
	v_and_b32_e32 v59, 0xffff0000, v59
	v_and_b32_e32 v58, 0xffff0000, v58
	v_pk_fma_f32 v[58:59], v[72:73], v[62:63], v[58:59] op_sel_hi:[0,1,1] neg_lo:[1,0,0] neg_hi:[1,0,0]
	v_pk_fma_f32 v[60:61], v[72:73], v[90:91], v[60:61] op_sel_hi:[0,1,1] neg_lo:[1,0,0] neg_hi:[1,0,0]
	v_pk_mul_f32 v[62:63], v[58:59], v[58:59]
	s_nop 0
	v_pk_fma_f32 v[62:63], v[60:61], v[60:61], v[62:63]
	s_nop 0
	v_pk_add_f32 v[90:91], v[62:63], v[62:63] op_sel:[0,1] op_sel_hi:[1,0]
	global_load_dwordx2 v[62:63], v[94:95], off offset:128
	s_waitcnt vmcnt(0)
	v_lshlrev_b32_e32 v65, 16, v63
	v_and_b32_e32 v93, 0xffff0000, v63
	v_mov_b32_e32 v63, v36
	v_mov_b32_e32 v36, v35
	v_lshlrev_b32_e32 v64, 16, v62
	v_and_b32_e32 v92, 0xffff0000, v62
	v_mov_b32_e32 v62, v34
	v_pk_mul_f32 v[34:35], v[36:37], v[70:71] op_sel_hi:[1,0]
	v_mul_f32_e32 v62, v70, v62
	v_mul_f32_e32 v63, v70, v63
	v_pk_fma_f32 v[34:35], v[72:73], v[34:35], v[92:93] op_sel_hi:[0,1,1] neg_lo:[1,0,0] neg_hi:[1,0,0]
	v_pk_fma_f32 v[62:63], v[72:73], v[62:63], v[64:65] op_sel_hi:[0,1,1] neg_lo:[1,0,0] neg_hi:[1,0,0]
	v_pk_mul_f32 v[36:37], v[34:35], v[34:35]
	s_nop 0
	v_pk_fma_f32 v[36:37], v[62:63], v[62:63], v[36:37]
	s_nop 0
	v_pk_add_f32 v[92:93], v[36:37], v[36:37] op_sel:[0,1] op_sel_hi:[1,0]
	global_load_dwordx2 v[36:37], v[94:95], off offset:144
	s_waitcnt vmcnt(0)
	v_lshlrev_b32_e32 v65, 16, v37
	v_lshlrev_b32_e32 v64, 16, v36
	v_and_b32_e32 v37, 0xffff0000, v37
	v_and_b32_e32 v36, 0xffff0000, v36
	v_pk_fma_f32 v[36:37], v[72:73], v[38:39], v[36:37] op_sel_hi:[0,1,1] neg_lo:[1,0,0] neg_hi:[1,0,0]
	v_pk_fma_f32 v[64:65], v[72:73], v[96:97], v[64:65] op_sel_hi:[0,1,1] neg_lo:[1,0,0] neg_hi:[1,0,0]
	v_pk_mul_f32 v[38:39], v[36:37], v[36:37]
	s_nop 0
	v_pk_fma_f32 v[38:39], v[64:65], v[64:65], v[38:39]
	s_nop 0
	v_pk_add_f32 v[96:97], v[38:39], v[38:39] op_sel:[0,1] op_sel_hi:[1,0]
	global_load_dwordx2 v[38:39], v[94:95], off offset:160
	s_waitcnt vmcnt(0)
	v_lshlrev_b32_e32 v41, 16, v39
	v_lshlrev_b32_e32 v40, 16, v38
	v_and_b32_e32 v39, 0xffff0000, v39
	v_and_b32_e32 v38, 0xffff0000, v38
	v_pk_fma_f32 v[38:39], v[72:73], v[42:43], v[38:39] op_sel_hi:[0,1,1] neg_lo:[1,0,0] neg_hi:[1,0,0]
	v_pk_fma_f32 v[40:41], v[72:73], v[98:99], v[40:41] op_sel_hi:[0,1,1] neg_lo:[1,0,0] neg_hi:[1,0,0]
	v_pk_mul_f32 v[42:43], v[38:39], v[38:39]
	s_nop 0
	v_pk_fma_f32 v[42:43], v[40:41], v[40:41], v[42:43]
	s_nop 0
	v_pk_add_f32 v[98:99], v[42:43], v[42:43] op_sel:[0,1] op_sel_hi:[1,0]
	global_load_dwordx2 v[42:43], v[94:95], off offset:176
	s_waitcnt vmcnt(0)
	v_lshlrev_b32_e32 v45, 16, v43
	v_lshlrev_b32_e32 v44, 16, v42
	v_and_b32_e32 v43, 0xffff0000, v43
	v_and_b32_e32 v42, 0xffff0000, v42
	v_pk_fma_f32 v[42:43], v[72:73], v[46:47], v[42:43] op_sel_hi:[0,1,1] neg_lo:[1,0,0] neg_hi:[1,0,0]
	v_pk_fma_f32 v[44:45], v[72:73], v[100:101], v[44:45] op_sel_hi:[0,1,1] neg_lo:[1,0,0] neg_hi:[1,0,0]
	v_pk_mul_f32 v[46:47], v[42:43], v[42:43]
	s_nop 0
	v_pk_fma_f32 v[46:47], v[44:45], v[44:45], v[46:47]
	s_nop 0
	v_pk_add_f32 v[100:101], v[46:47], v[46:47] op_sel:[0,1] op_sel_hi:[1,0]
	global_load_dwordx2 v[46:47], v[94:95], off offset:192
	s_waitcnt vmcnt(0)
	v_lshlrev_b32_e32 v49, 16, v47
	v_and_b32_e32 v103, 0xffff0000, v47
	v_mov_b32_e32 v47, v20
	v_mov_b32_e32 v20, v19
	v_lshlrev_b32_e32 v48, 16, v46
	v_and_b32_e32 v102, 0xffff0000, v46
	v_mov_b32_e32 v46, v18
	v_pk_mul_f32 v[18:19], v[20:21], v[70:71] op_sel_hi:[1,0]
	v_mul_f32_e32 v46, v70, v46
	v_mul_f32_e32 v47, v70, v47
	v_pk_fma_f32 v[18:19], v[72:73], v[18:19], v[102:103] op_sel_hi:[0,1,1] neg_lo:[1,0,0] neg_hi:[1,0,0]
	v_pk_fma_f32 v[46:47], v[72:73], v[46:47], v[48:49] op_sel_hi:[0,1,1] neg_lo:[1,0,0] neg_hi:[1,0,0]
	v_pk_mul_f32 v[20:21], v[18:19], v[18:19]
	s_nop 0
	v_pk_fma_f32 v[20:21], v[46:47], v[46:47], v[20:21]
	s_nop 0
	v_pk_add_f32 v[102:103], v[20:21], v[20:21] op_sel:[0,1] op_sel_hi:[1,0]
	global_load_dwordx2 v[20:21], v[94:95], off offset:208
	s_waitcnt vmcnt(0)
	v_lshlrev_b32_e32 v49, 16, v21
	v_lshlrev_b32_e32 v48, 16, v20
	v_and_b32_e32 v21, 0xffff0000, v21
	v_and_b32_e32 v20, 0xffff0000, v20
	v_pk_fma_f32 v[20:21], v[72:73], v[22:23], v[20:21] op_sel_hi:[0,1,1] neg_lo:[1,0,0] neg_hi:[1,0,0]
	v_pk_fma_f32 v[48:49], v[72:73], v[104:105], v[48:49] op_sel_hi:[0,1,1] neg_lo:[1,0,0] neg_hi:[1,0,0]
	v_pk_mul_f32 v[22:23], v[20:21], v[20:21]
	s_nop 0
	v_pk_fma_f32 v[22:23], v[48:49], v[48:49], v[22:23]
	s_nop 0
	v_pk_add_f32 v[104:105], v[22:23], v[22:23] op_sel:[0,1] op_sel_hi:[1,0]
	global_load_dwordx2 v[22:23], v[94:95], off offset:224
	s_waitcnt vmcnt(0)
	v_lshlrev_b32_e32 v25, 16, v23
	v_lshlrev_b32_e32 v24, 16, v22
	v_and_b32_e32 v23, 0xffff0000, v23
	v_and_b32_e32 v22, 0xffff0000, v22
	v_pk_fma_f32 v[22:23], v[72:73], v[26:27], v[22:23] op_sel_hi:[0,1,1] neg_lo:[1,0,0] neg_hi:[1,0,0]
	v_pk_fma_f32 v[24:25], v[72:73], v[106:107], v[24:25] op_sel_hi:[0,1,1] neg_lo:[1,0,0] neg_hi:[1,0,0]
	v_pk_mul_f32 v[26:27], v[22:23], v[22:23]
	s_nop 0
	v_pk_fma_f32 v[26:27], v[24:25], v[24:25], v[26:27]
	s_nop 0
	v_pk_add_f32 v[106:107], v[26:27], v[26:27] op_sel:[0,1] op_sel_hi:[1,0]
	global_load_dwordx2 v[26:27], v[94:95], off offset:240
	s_waitcnt vmcnt(0)
	v_lshlrev_b32_e32 v29, 16, v27
	v_lshlrev_b32_e32 v28, 16, v26
	v_and_b32_e32 v95, 0xffff0000, v27
	v_and_b32_e32 v94, 0xffff0000, v26
	v_mov_b32_e32 v26, v30
	v_mov_b32_e32 v27, v32
	v_mul_f32_e32 v26, v70, v26
	v_mul_f32_e32 v27, v70, v27
	v_mov_b32_e32 v32, v31
	v_pk_fma_f32 v[26:27], v[72:73], v[26:27], v[28:29] op_sel_hi:[0,1,1] neg_lo:[1,0,0] neg_hi:[1,0,0]
	v_pk_mul_f32 v[28:29], v[32:33], v[70:71] op_sel_hi:[1,0]
	s_nop 0
	v_pk_fma_f32 v[28:29], v[72:73], v[28:29], v[94:95] op_sel_hi:[0,1,1] neg_lo:[1,0,0] neg_hi:[1,0,0]
	v_pk_mul_f32 v[30:31], v[28:29], v[28:29]
	v_sub_f32_e32 v94, 1.0, v73
	v_pk_fma_f32 v[32:33], v[26:27], v[26:27], v[30:31]
	v_lshl_add_u64 v[30:31], s[0:1], 0, v[84:85]
	v_and_b32_e32 v85, 0xffff0000, v83
	v_lshlrev_b32_e32 v84, 16, v83
	v_lshl_add_u64 v[30:31], v[30:31], 0, s[2:3]
	v_pk_fma_f32 v[84:85], v[72:73], v[4:5], v[84:85] op_sel_hi:[0,1,1] neg_lo:[1,0,0] neg_hi:[1,0,0]
	v_and_b32_e32 v83, 0xffff0000, v82
	v_lshlrev_b32_e32 v82, 16, v82
	v_lshl_add_u64 v[30:31], v[30:31], 0, v[0:1]
	v_mul_f32_e32 v0, v85, v85
	v_pk_fma_f32 v[82:83], v[72:73], v[2:3], v[82:83] op_sel_hi:[0,1,1] neg_lo:[1,0,0] neg_hi:[1,0,0]
	v_pk_fma_f32 v[4:5], v[84:85], v[84:85], v[0:1] op_sel_hi:[1,1,0]
	v_mul_f32_e32 v0, v83, v83
	v_pk_fma_f32 v[2:3], v[82:83], v[82:83], v[0:1] op_sel_hi:[1,1,0]
	v_mov_b32_e32 v107, v33
	v_pk_add_f32 v[2:3], v[2:3], v[4:5]
	v_and_b32_e32 v5, 0xffff0000, v81
	v_lshlrev_b32_e32 v4, 16, v81
	v_pk_fma_f32 v[8:9], v[72:73], v[8:9], v[4:5] op_sel_hi:[0,1,1] neg_lo:[1,0,0] neg_hi:[1,0,0]
	v_and_b32_e32 v81, 0xffff0000, v80
	v_lshlrev_b32_e32 v80, 16, v80
	v_mul_f32_e32 v0, v9, v9
	v_pk_fma_f32 v[6:7], v[72:73], v[6:7], v[80:81] op_sel_hi:[0,1,1] neg_lo:[1,0,0] neg_hi:[1,0,0]
	v_pk_fma_f32 v[4:5], v[8:9], v[8:9], v[0:1] op_sel_hi:[1,1,0]
	v_mul_f32_e32 v0, v7, v7
	v_pk_fma_f32 v[80:81], v[6:7], v[6:7], v[0:1] op_sel_hi:[1,1,0]
	s_nop 0
	v_pk_add_f32 v[4:5], v[80:81], v[4:5]
	s_nop 0
	v_pk_add_f32 v[2:3], v[2:3], v[4:5]
	v_and_b32_e32 v5, 0xffff0000, v77
	v_lshlrev_b32_e32 v4, 16, v77
	v_pk_fma_f32 v[12:13], v[72:73], v[12:13], v[4:5] op_sel_hi:[0,1,1] neg_lo:[1,0,0] neg_hi:[1,0,0]
	v_and_b32_e32 v77, 0xffff0000, v76
	v_lshlrev_b32_e32 v76, 16, v76
	v_mul_f32_e32 v0, v13, v13
	v_pk_fma_f32 v[10:11], v[72:73], v[10:11], v[76:77] op_sel_hi:[0,1,1] neg_lo:[1,0,0] neg_hi:[1,0,0]
	v_pk_fma_f32 v[4:5], v[12:13], v[12:13], v[0:1] op_sel_hi:[1,1,0]
	v_mul_f32_e32 v0, v11, v11
	v_pk_fma_f32 v[76:77], v[10:11], v[10:11], v[0:1] op_sel_hi:[1,1,0]
	s_nop 0
	v_pk_add_f32 v[4:5], v[76:77], v[4:5]
	s_nop 0
	v_pk_add_f32 v[2:3], v[2:3], v[4:5]
	v_and_b32_e32 v5, 0xffff0000, v75
	v_lshlrev_b32_e32 v4, 16, v75
	v_pk_fma_f32 v[16:17], v[72:73], v[16:17], v[4:5] op_sel_hi:[0,1,1] neg_lo:[1,0,0] neg_hi:[1,0,0]
	v_and_b32_e32 v75, 0xffff0000, v74
	v_lshlrev_b32_e32 v74, 16, v74
	v_mul_f32_e32 v0, v17, v17
	v_pk_fma_f32 v[14:15], v[72:73], v[14:15], v[74:75] op_sel_hi:[0,1,1] neg_lo:[1,0,0] neg_hi:[1,0,0]
	v_pk_fma_f32 v[4:5], v[16:17], v[16:17], v[0:1] op_sel_hi:[1,1,0]
	v_mul_f32_e32 v0, v15, v15
	v_pk_fma_f32 v[70:71], v[14:15], v[14:15], v[0:1] op_sel_hi:[1,1,0]
	s_nop 0
	v_pk_add_f32 v[4:5], v[70:71], v[4:5]
	s_nop 0
	v_pk_add_f32 v[2:3], v[2:3], v[4:5]
	s_nop 0
	v_pk_add_f32 v[2:3], v[2:3], v[78:79]
	s_nop 0
	v_pk_add_f32 v[2:3], v[2:3], v[86:87]
	s_nop 0
	v_pk_add_f32 v[2:3], v[2:3], v[88:89]
	s_nop 0
	v_pk_add_f32 v[2:3], v[2:3], v[90:91]
	s_nop 0
	v_pk_add_f32 v[2:3], v[2:3], v[92:93]
	s_nop 0
	v_pk_add_f32 v[2:3], v[2:3], v[96:97]
	s_nop 0
	v_pk_add_f32 v[2:3], v[2:3], v[98:99]
	s_nop 0
	v_pk_add_f32 v[2:3], v[2:3], v[100:101]
	s_nop 0
	v_pk_add_f32 v[2:3], v[2:3], v[102:103]
	s_nop 0
	v_pk_add_f32 v[2:3], v[2:3], v[104:105]
	s_nop 0
	v_mov_b32_e32 v3, v32
	v_pk_add_f32 v[2:3], v[2:3], v[106:107]
	s_nop 0
	v_add_f32_e32 v0, v2, v3
	v_mov_b32_e32 v2, v0
	v_nop
	v_nop
	v_permlane32_swap_b32 v0, v2
	s_nop 0
	v_add_f32_e32 v0, v0, v2
	v_fmamk_f32 v0, v0, 0x3c000000, v252
	v_cmp_gt_f32_e32 vcc, s67, v0
	v_mul_f32_e32 v2, 0x4b800000, v0
	s_nop 0
	v_cndmask_b32_e32 v0, v0, v2, vcc
	v_rsq_f32_e32 v0, v0
	s_nop 0
	v_mul_f32_e32 v2, 0x45800000, v0
	v_cndmask_b32_e32 v0, v0, v2, vcc
	global_load_dwordx4 v[2:5], v186, s[6:7]
	v_mul_f32_e32 v0, v94, v0
	v_pk_mul_f32 v[32:33], v[82:83], v[0:1] op_sel_hi:[1,0]
	v_mul_f32_e32 v6, v0, v6
	v_mul_f32_e32 v7, v0, v7
	s_waitcnt vmcnt(0)
	v_pk_mul_f32 v[2:3], v[2:3], v[32:33]
	v_pk_mul_f32 v[32:33], v[84:85], v[0:1] op_sel_hi:[1,0]
	v_cvt_pk_bf16_f32 v2, v2, v3
	v_pk_mul_f32 v[4:5], v[4:5], v[32:33]
	s_nop 0
	v_cvt_pk_bf16_f32 v3, v4, v5
	global_store_dwordx2 v[30:31], v[2:3], off
	global_load_dwordx4 v[2:5], v186, s[6:7] offset:32
	s_waitcnt vmcnt(0)
	v_pk_mul_f32 v[2:3], v[2:3], v[6:7]
	v_pk_mul_f32 v[6:7], v[8:9], v[0:1] op_sel_hi:[1,0]
	v_cvt_pk_bf16_f32 v2, v2, v3
	v_pk_mul_f32 v[4:5], v[4:5], v[6:7]
	v_pk_mul_f32 v[6:7], v[10:11], v[0:1] op_sel_hi:[1,0]
	v_cvt_pk_bf16_f32 v3, v4, v5
	global_store_dwordx2 v[30:31], v[2:3], off offset:16
	global_load_dwordx4 v[2:5], v186, s[6:7] offset:64
	s_waitcnt vmcnt(0)
	v_pk_mul_f32 v[2:3], v[2:3], v[6:7]
	v_pk_mul_f32 v[6:7], v[12:13], v[0:1] op_sel_hi:[1,0]
	v_cvt_pk_bf16_f32 v2, v2, v3
	v_pk_mul_f32 v[4:5], v[4:5], v[6:7]
	v_pk_mul_f32 v[6:7], v[14:15], v[0:1] op_sel_hi:[1,0]
	v_cvt_pk_bf16_f32 v3, v4, v5
	global_store_dwordx2 v[30:31], v[2:3], off offset:32
	global_load_dwordx4 v[2:5], v186, s[6:7] offset:96
	s_waitcnt vmcnt(0)
	v_pk_mul_f32 v[2:3], v[2:3], v[6:7]
	v_pk_mul_f32 v[6:7], v[16:17], v[0:1] op_sel_hi:[1,0]
	v_cvt_pk_bf16_f32 v2, v2, v3
	v_pk_mul_f32 v[4:5], v[4:5], v[6:7]
	v_mov_b32_e32 v6, v66
	v_cvt_pk_bf16_f32 v3, v4, v5
	global_store_dwordx2 v[30:31], v[2:3], off offset:48
	global_load_dwordx4 v[2:5], v186, s[6:7] offset:128
	v_mov_b32_e32 v7, v50
	v_mul_f32_e32 v6, v0, v6
	v_mul_f32_e32 v7, v0, v7
	v_mov_b32_e32 v50, v67
	s_waitcnt vmcnt(0)
	v_pk_mul_f32 v[2:3], v[2:3], v[6:7]
	v_pk_mul_f32 v[6:7], v[50:51], v[0:1] op_sel_hi:[1,0]
	v_cvt_pk_bf16_f32 v2, v2, v3
	v_pk_mul_f32 v[4:5], v[4:5], v[6:7]
	v_mov_b32_e32 v6, v68
	v_cvt_pk_bf16_f32 v3, v4, v5
	global_store_dwordx2 v[30:31], v[2:3], off offset:64
	global_load_dwordx4 v[2:5], v186, s[6:7] offset:160
	v_mov_b32_e32 v7, v52
	v_mul_f32_e32 v6, v0, v6
	v_mul_f32_e32 v7, v0, v7
	v_mov_b32_e32 v52, v69
	s_waitcnt vmcnt(0)
	v_pk_mul_f32 v[2:3], v[6:7], v[2:3]
	v_pk_mul_f32 v[6:7], v[52:53], v[0:1] op_sel_hi:[1,0]
	v_cvt_pk_bf16_f32 v2, v2, v3
	v_pk_mul_f32 v[4:5], v[6:7], v[4:5]
	v_mov_b32_e32 v6, v56
	v_cvt_pk_bf16_f32 v3, v4, v5
	global_store_dwordx2 v[30:31], v[2:3], off offset:80
	global_load_dwordx4 v[2:5], v186, s[6:7] offset:192
	v_mov_b32_e32 v7, v54
	v_mul_f32_e32 v6, v0, v6
	v_mul_f32_e32 v7, v0, v7
	v_mov_b32_e32 v54, v57
	s_waitcnt vmcnt(0)
	v_pk_mul_f32 v[2:3], v[6:7], v[2:3]
	v_pk_mul_f32 v[6:7], v[54:55], v[0:1] op_sel_hi:[1,0]
	v_cvt_pk_bf16_f32 v2, v2, v3
	v_pk_mul_f32 v[4:5], v[6:7], v[4:5]
	v_mov_b32_e32 v6, v60
	v_cvt_pk_bf16_f32 v3, v4, v5
	global_store_dwordx2 v[30:31], v[2:3], off offset:96
	global_load_dwordx4 v[2:5], v186, s[6:7] offset:224
	v_mov_b32_e32 v7, v58
	v_mul_f32_e32 v6, v0, v6
	v_mul_f32_e32 v7, v0, v7
	v_mov_b32_e32 v58, v61
	s_waitcnt vmcnt(0)
	v_pk_mul_f32 v[2:3], v[6:7], v[2:3]
	v_pk_mul_f32 v[6:7], v[58:59], v[0:1] op_sel_hi:[1,0]
	v_cvt_pk_bf16_f32 v2, v2, v3
	v_pk_mul_f32 v[4:5], v[6:7], v[4:5]
	v_mov_b32_e32 v6, v62
	v_cvt_pk_bf16_f32 v3, v4, v5
	global_store_dwordx2 v[30:31], v[2:3], off offset:112
	global_load_dwordx4 v[2:5], v186, s[6:7] offset:256
	v_mov_b32_e32 v7, v34
	v_mul_f32_e32 v6, v0, v6
	v_mul_f32_e32 v7, v0, v7
	v_mov_b32_e32 v34, v63
	s_waitcnt vmcnt(0)
	v_pk_mul_f32 v[2:3], v[6:7], v[2:3]
	v_pk_mul_f32 v[6:7], v[34:35], v[0:1] op_sel_hi:[1,0]
	v_cvt_pk_bf16_f32 v2, v2, v3
	v_pk_mul_f32 v[4:5], v[6:7], v[4:5]
	v_mov_b32_e32 v6, v64
	v_cvt_pk_bf16_f32 v3, v4, v5
	global_store_dwordx2 v[30:31], v[2:3], off offset:128
	global_load_dwordx4 v[2:5], v186, s[6:7] offset:288
	v_mov_b32_e32 v7, v36
	v_mul_f32_e32 v6, v0, v6
	v_mul_f32_e32 v7, v0, v7
	v_mov_b32_e32 v36, v65
	s_waitcnt vmcnt(0)
	v_pk_mul_f32 v[2:3], v[6:7], v[2:3]
	v_pk_mul_f32 v[6:7], v[36:37], v[0:1] op_sel_hi:[1,0]
	v_cvt_pk_bf16_f32 v2, v2, v3
	v_pk_mul_f32 v[4:5], v[6:7], v[4:5]
	v_mov_b32_e32 v6, v40
	v_cvt_pk_bf16_f32 v3, v4, v5
	global_store_dwordx2 v[30:31], v[2:3], off offset:144
	global_load_dwordx4 v[2:5], v186, s[6:7] offset:320
	v_mov_b32_e32 v7, v38
	v_mul_f32_e32 v6, v0, v6
	v_mul_f32_e32 v7, v0, v7
	v_mov_b32_e32 v38, v41
	s_waitcnt vmcnt(0)
	v_pk_mul_f32 v[2:3], v[6:7], v[2:3]
	v_pk_mul_f32 v[6:7], v[38:39], v[0:1] op_sel_hi:[1,0]
	v_cvt_pk_bf16_f32 v2, v2, v3
	v_pk_mul_f32 v[4:5], v[6:7], v[4:5]
	v_mov_b32_e32 v6, v44
	v_cvt_pk_bf16_f32 v3, v4, v5
	global_store_dwordx2 v[30:31], v[2:3], off offset:160
	global_load_dwordx4 v[2:5], v186, s[6:7] offset:352
	v_mov_b32_e32 v7, v42
	v_mul_f32_e32 v6, v0, v6
	v_mul_f32_e32 v7, v0, v7
	v_mov_b32_e32 v42, v45
	s_waitcnt vmcnt(0)
	v_pk_mul_f32 v[2:3], v[6:7], v[2:3]
	v_pk_mul_f32 v[6:7], v[42:43], v[0:1] op_sel_hi:[1,0]
	v_cvt_pk_bf16_f32 v2, v2, v3
	v_pk_mul_f32 v[4:5], v[6:7], v[4:5]
	v_mov_b32_e32 v6, v46
	v_cvt_pk_bf16_f32 v3, v4, v5
	global_store_dwordx2 v[30:31], v[2:3], off offset:176
	global_load_dwordx4 v[2:5], v186, s[6:7] offset:384
	v_mov_b32_e32 v7, v18
	v_mul_f32_e32 v6, v0, v6
	v_mul_f32_e32 v7, v0, v7
	v_mov_b32_e32 v18, v47
	s_waitcnt vmcnt(0)
	v_pk_mul_f32 v[2:3], v[6:7], v[2:3]
	v_pk_mul_f32 v[6:7], v[18:19], v[0:1] op_sel_hi:[1,0]
	v_cvt_pk_bf16_f32 v2, v2, v3
	v_pk_mul_f32 v[4:5], v[6:7], v[4:5]
	v_mov_b32_e32 v6, v48
	v_cvt_pk_bf16_f32 v3, v4, v5
	global_store_dwordx2 v[30:31], v[2:3], off offset:192
	global_load_dwordx4 v[2:5], v186, s[6:7] offset:416
	v_mov_b32_e32 v7, v20
	v_mul_f32_e32 v6, v0, v6
	v_mul_f32_e32 v7, v0, v7
	v_mov_b32_e32 v20, v49
	s_waitcnt vmcnt(0)
	v_pk_mul_f32 v[2:3], v[6:7], v[2:3]
	v_pk_mul_f32 v[6:7], v[20:21], v[0:1] op_sel_hi:[1,0]
	v_cvt_pk_bf16_f32 v2, v2, v3
	v_pk_mul_f32 v[4:5], v[6:7], v[4:5]
	v_mov_b32_e32 v6, v24
	v_cvt_pk_bf16_f32 v3, v4, v5
	global_store_dwordx2 v[30:31], v[2:3], off offset:208
	global_load_dwordx4 v[2:5], v186, s[6:7] offset:448
	v_mov_b32_e32 v7, v22
	v_mul_f32_e32 v6, v0, v6
	v_mul_f32_e32 v7, v0, v7
	v_mov_b32_e32 v22, v25
	s_waitcnt vmcnt(0)
	v_pk_mul_f32 v[2:3], v[6:7], v[2:3]
	v_pk_mul_f32 v[6:7], v[22:23], v[0:1] op_sel_hi:[1,0]
	v_cvt_pk_bf16_f32 v2, v2, v3
	v_pk_mul_f32 v[4:5], v[6:7], v[4:5]
	v_mov_b32_e32 v6, v26
	v_cvt_pk_bf16_f32 v3, v4, v5
	global_store_dwordx2 v[30:31], v[2:3], off offset:224
	global_load_dwordx4 v[2:5], v186, s[6:7] offset:480
	v_mov_b32_e32 v7, v28
	v_mul_f32_e32 v6, v0, v6
	v_mul_f32_e32 v7, v0, v7
	v_mov_b32_e32 v28, v27
	s_waitcnt vmcnt(0)
	v_pk_mul_f32 v[2:3], v[6:7], v[2:3]
	v_pk_mul_f32 v[6:7], v[28:29], v[0:1] op_sel_hi:[1,0]
	v_cvt_pk_bf16_f32 v2, v2, v3
	v_pk_mul_f32 v[4:5], v[6:7], v[4:5]
	s_nop 0
	v_cvt_pk_bf16_f32 v3, v4, v5
	global_store_dwordx2 v[30:31], v[2:3], off offset:240
	s_cbranch_scc0 .LBB0_157

.LBB0_141:
	s_and_b32 s38, s37, 1
	s_mul_i32 s39, s38, 0x4800
	v_add_u32_e32 v0, s39, v203
	ds_read_b128 v[2:5], v0
	ds_read_b128 v[6:9], v0 offset:32
	ds_read_b128 v[10:13], v0 offset:4608
	ds_read_b128 v[80:83], v0 offset:4640
	ds_read_b128 v[84:87], v0 offset:64
	ds_read_b128 v[88:91], v0 offset:96
	ds_read_b128 v[92:95], v0 offset:4672
	ds_read_b128 v[96:99], v0 offset:4704
	s_waitcnt lgkmcnt(7)
	v_mfma_f32_32x32x16_bf16 v[128:143], v[2:5], v[144:147], 0
	s_waitcnt lgkmcnt(5)
	v_mfma_f32_32x32x16_bf16 v[112:127], v[10:13], v[144:147], 0
	v_mfma_f32_32x32x16_bf16 v[128:143], v[6:9], v[168:171], v[128:143]
	s_waitcnt lgkmcnt(4)
	v_mfma_f32_32x32x16_bf16 v[112:127], v[80:83], v[168:171], v[112:127]
	s_waitcnt lgkmcnt(3)
	v_mfma_f32_32x32x16_bf16 v[128:143], v[84:87], v[148:151], v[128:143]
	s_waitcnt lgkmcnt(1)
	v_mfma_f32_32x32x16_bf16 v[112:127], v[92:95], v[148:151], v[112:127]
	v_mfma_f32_32x32x16_bf16 v[128:143], v[88:91], v[172:175], v[128:143]
	s_waitcnt lgkmcnt(0)
	v_mfma_f32_32x32x16_bf16 v[112:127], v[96:99], v[172:175], v[112:127]
	ds_read_b128 v[2:5], v0 offset:9216
	ds_read_b128 v[6:9], v0 offset:9248
	ds_read_b128 v[10:13], v0 offset:13824
	ds_read_b128 v[184:187], v0 offset:13856
	ds_read_b128 v[198:201], v0 offset:9280
	ds_read_b128 v[208:211], v0 offset:9312
	ds_read_b128 v[212:215], v0 offset:13888
	ds_read_b128 v[220:223], v0 offset:13920
	s_waitcnt lgkmcnt(7)
	v_mfma_f32_32x32x16_bf16 v[96:111], v[2:5], v[144:147], 0
	s_waitcnt lgkmcnt(5)
	v_mfma_f32_32x32x16_bf16 v[80:95], v[10:13], v[144:147], 0
	v_mfma_f32_32x32x16_bf16 v[96:111], v[6:9], v[168:171], v[96:111]
	s_waitcnt lgkmcnt(4)
	v_mfma_f32_32x32x16_bf16 v[80:95], v[184:187], v[168:171], v[80:95]
	s_waitcnt lgkmcnt(3)
	v_mfma_f32_32x32x16_bf16 v[96:111], v[198:201], v[148:151], v[96:111]
	s_waitcnt lgkmcnt(1)
	v_mfma_f32_32x32x16_bf16 v[80:95], v[212:215], v[148:151], v[80:95]
	v_mfma_f32_32x32x16_bf16 v[96:111], v[208:211], v[172:175], v[96:111]
	s_waitcnt lgkmcnt(0)
	v_mfma_f32_32x32x16_bf16 v[80:95], v[220:223], v[172:175], v[80:95]
	s_mul_i32 s39, s38, 0x8800
	v_add_u32_e32 v15, s39, v204
	ds_read_b128 v[184:187], v15 offset:36864
	ds_read_b128 v[10:13], v15 offset:36896
	ds_read_b128 v[2:5], v15 offset:36928
	ds_read_b128 v[6:9], v15 offset:36960
	v_max3_f32 v0, v128, v112, v129
	v_max_f32_e32 v14, v127, v127
	v_max3_f32 v0, v0, v113, v130
	v_max3_f32 v0, v0, v114, v131
	v_max3_f32 v0, v0, v115, v132
	v_max3_f32 v0, v0, v116, v133
	v_max3_f32 v0, v0, v117, v134
	v_max3_f32 v0, v0, v118, v135
	v_max3_f32 v0, v0, v119, v136
	v_max3_f32 v0, v0, v120, v137
	v_max3_f32 v0, v0, v121, v138
	v_max3_f32 v0, v0, v122, v139
	v_max3_f32 v0, v0, v123, v140
	v_max3_f32 v0, v0, v124, v141
	v_max3_f32 v0, v0, v125, v142
	v_max3_f32 v0, v0, v126, v143
	s_nop 0
	v_max_f32_e32 v0, v0, v0
	v_max_f32_e32 v0, v0, v14
	v_mov_b32_e32 v14, v0
	v_nop
	v_nop
	v_permlane32_swap_b32 v14, v0
	s_nop 0
	v_max3_f32 v14, v206, v14, v0
	v_sub_f32_e32 v0, v206, v14
	v_exp_f32_e32 v0, v0
	s_nop 0
	v_cmp_neq_f32_e32 vcc, 1.0, v0
	s_cbranch_vccz .LBB0_143
	v_mul_f32_e32 v78, v0, v78
	v_mul_f32_e32 v79, v0, v79
	v_mul_f32_e32 v76, v0, v76
	v_mul_f32_e32 v77, v0, v77
	v_mul_f32_e32 v74, v0, v74
	v_mul_f32_e32 v75, v0, v75
	v_mul_f32_e32 v72, v0, v72
	v_mul_f32_e32 v73, v0, v73
	v_mul_f32_e32 v70, v0, v70
	v_mul_f32_e32 v71, v0, v71
	v_mul_f32_e32 v68, v0, v68
	v_mul_f32_e32 v69, v0, v69
	v_mul_f32_e32 v66, v0, v66
	v_mul_f32_e32 v67, v0, v67
	v_mul_f32_e32 v64, v0, v64
	v_mul_f32_e32 v65, v0, v65
	v_mul_f32_e32 v62, v0, v62
	v_mul_f32_e32 v63, v0, v63
	v_mul_f32_e32 v60, v0, v60
	v_mul_f32_e32 v61, v0, v61
	v_mul_f32_e32 v58, v0, v58
	v_mul_f32_e32 v59, v0, v59
	v_mul_f32_e32 v56, v0, v56
	v_mul_f32_e32 v57, v0, v57
	v_mul_f32_e32 v54, v0, v54
	v_mul_f32_e32 v55, v0, v55
	v_mul_f32_e32 v52, v0, v52
	v_mul_f32_e32 v53, v0, v53
	v_mul_f32_e32 v50, v0, v50
	v_mul_f32_e32 v51, v0, v51
	v_mul_f32_e32 v48, v0, v48
	v_mul_f32_e32 v49, v0, v49
	v_mul_f32_e32 v46, v0, v46
	v_mul_f32_e32 v47, v0, v47
	v_mul_f32_e32 v44, v0, v44
	v_mul_f32_e32 v45, v0, v45
	v_mul_f32_e32 v42, v0, v42
	v_mul_f32_e32 v43, v0, v43
	v_mul_f32_e32 v40, v0, v40
	v_mul_f32_e32 v41, v0, v41
	v_mul_f32_e32 v38, v0, v38
	v_mul_f32_e32 v39, v0, v39
	v_mul_f32_e32 v36, v0, v36
	v_mul_f32_e32 v37, v0, v37
	v_mul_f32_e32 v34, v0, v34
	v_mul_f32_e32 v35, v0, v35
	v_mul_f32_e32 v32, v0, v32
	v_mul_f32_e32 v33, v0, v33
	v_mul_f32_e32 v30, v0, v30
	v_mul_f32_e32 v31, v0, v31
	v_mul_f32_e32 v28, v0, v28
	v_mul_f32_e32 v29, v0, v29
	v_mul_f32_e32 v26, v0, v26
	v_mul_f32_e32 v27, v0, v27
	v_mul_f32_e32 v24, v0, v24
	v_mul_f32_e32 v25, v0, v25
	v_mul_f32_e32 v22, v0, v22
	v_mul_f32_e32 v23, v0, v23
	v_mul_f32_e32 v20, v0, v20
	v_mul_f32_e32 v21, v0, v21
	v_mul_f32_e32 v18, v0, v18
	v_mul_f32_e32 v19, v0, v19
	v_mul_f32_e32 v16, v0, v16
	v_mul_f32_e32 v17, v0, v17
.LBB0_143:
	v_sub_f32_e32 v112, v112, v14
	v_exp_f32_e32 v207, v112
	v_sub_f32_e32 v112, v129, v14
	v_exp_f32_e32 v129, v112
	v_sub_f32_e32 v112, v113, v14
	v_exp_f32_e32 v208, v112
	v_sub_f32_e32 v112, v130, v14
	v_exp_f32_e32 v130, v112
	v_sub_f32_e32 v112, v114, v14
	v_exp_f32_e32 v209, v112
	v_sub_f32_e32 v112, v131, v14
	v_exp_f32_e32 v131, v112
	v_sub_f32_e32 v112, v115, v14
	v_exp_f32_e32 v220, v112
	v_sub_f32_e32 v112, v132, v14
	v_exp_f32_e32 v132, v112
	v_sub_f32_e32 v112, v116, v14
	v_exp_f32_e32 v116, v112
	v_sub_f32_e32 v112, v133, v14
	v_exp_f32_e32 v133, v112
	v_sub_f32_e32 v112, v117, v14
	v_exp_f32_e32 v117, v112
	v_sub_f32_e32 v112, v134, v14
	v_exp_f32_e32 v134, v112
	v_sub_f32_e32 v112, v118, v14
	v_exp_f32_e32 v118, v112
	v_sub_f32_e32 v112, v135, v14
	v_exp_f32_e32 v135, v112
	v_sub_f32_e32 v112, v119, v14
	v_exp_f32_e32 v119, v112
	v_sub_f32_e32 v112, v136, v14
	v_exp_f32_e32 v136, v112
	v_sub_f32_e32 v112, v120, v14
	v_exp_f32_e32 v120, v112
	v_sub_f32_e32 v112, v137, v14
	v_exp_f32_e32 v137, v112
	v_sub_f32_e32 v112, v121, v14
	v_exp_f32_e32 v121, v112
	v_sub_f32_e32 v112, v138, v14
	v_exp_f32_e32 v138, v112
	v_sub_f32_e32 v112, v122, v14
	v_exp_f32_e32 v122, v112
	v_sub_f32_e32 v112, v139, v14
	v_exp_f32_e32 v139, v112
	v_sub_f32_e32 v112, v123, v14
	v_exp_f32_e32 v123, v112
	v_sub_f32_e32 v112, v140, v14
	v_exp_f32_e32 v140, v112
	v_sub_f32_e32 v112, v124, v14
	v_exp_f32_e32 v124, v112
	v_sub_f32_e32 v112, v141, v14
	v_exp_f32_e32 v141, v112
	v_sub_f32_e32 v112, v125, v14
	v_exp_f32_e32 v125, v112
	v_sub_f32_e32 v112, v142, v14
	v_exp_f32_e32 v142, v112
	v_sub_f32_e32 v112, v126, v14
	v_exp_f32_e32 v126, v112
	v_sub_f32_e32 v112, v143, v14
	v_exp_f32_e32 v143, v112
	v_sub_f32_e32 v112, v127, v14
	v_sub_f32_e32 v128, v128, v14
	v_exp_f32_e32 v127, v112
	v_exp_f32_e32 v128, v128
	v_cvt_pk_bf16_f32 v112, v120, v121
	v_cvt_pk_bf16_f32 v113, v122, v123
	v_cvt_pk_bf16_f32 v114, v124, v125
	v_cvt_pk_bf16_f32 v115, v126, v127
	v_cvt_pk_bf16_f32 v198, v207, v208
	v_cvt_pk_bf16_f32 v199, v209, v220
	v_cvt_pk_bf16_f32 v200, v116, v117
	v_cvt_pk_bf16_f32 v201, v118, v119
	v_cvt_pk_bf16_f32 v210, v136, v137
	v_cvt_pk_bf16_f32 v211, v138, v139
	v_cvt_pk_bf16_f32 v212, v140, v141
	v_cvt_pk_bf16_f32 v213, v142, v143
	v_cvt_pk_bf16_f32 v214, v128, v129
	v_cvt_pk_bf16_f32 v215, v130, v131
	v_cvt_pk_bf16_f32 v216, v132, v133
	v_cvt_pk_bf16_f32 v217, v134, v135
	s_waitcnt lgkmcnt(3)
	s_nop 0
	v_mfma_f32_32x32x16_bf16 v[64:79], v[184:187], v[214:217], v[64:79]
	s_waitcnt lgkmcnt(2)
	v_mfma_f32_32x32x16_bf16 v[64:79], v[10:13], v[210:213], v[64:79]
	s_waitcnt lgkmcnt(1)
	v_mfma_f32_32x32x16_bf16 v[64:79], v[2:5], v[198:201], v[64:79]
	s_waitcnt lgkmcnt(0)
	v_mfma_f32_32x32x16_bf16 v[64:79], v[6:9], v[112:115], v[64:79]
	ds_read_b128 v[2:5], v15 offset:45664
	ds_read_b128 v[6:9], v15 offset:45632
	ds_read_b128 v[10:13], v15 offset:45568
	ds_read_b128 v[184:187], v15 offset:45600
	s_waitcnt lgkmcnt(1)
	v_mfma_f32_32x32x16_bf16 v[48:63], v[10:13], v[214:217], v[48:63]
	s_waitcnt lgkmcnt(0)
	v_mfma_f32_32x32x16_bf16 v[48:63], v[184:187], v[210:213], v[48:63]
	v_mfma_f32_32x32x16_bf16 v[48:63], v[6:9], v[198:201], v[48:63]
	v_mfma_f32_32x32x16_bf16 v[48:63], v[2:5], v[112:115], v[48:63]
	ds_read_b128 v[2:5], v15 offset:54368
	ds_read_b128 v[6:9], v15 offset:54336
	ds_read_b128 v[10:13], v15 offset:54272
	ds_read_b128 v[184:187], v15 offset:54304
	s_waitcnt lgkmcnt(1)
	v_mfma_f32_32x32x16_bf16 v[32:47], v[10:13], v[214:217], v[32:47]
	s_waitcnt lgkmcnt(0)
	v_mfma_f32_32x32x16_bf16 v[32:47], v[184:187], v[210:213], v[32:47]
	v_mfma_f32_32x32x16_bf16 v[32:47], v[6:9], v[198:201], v[32:47]
	v_mfma_f32_32x32x16_bf16 v[32:47], v[2:5], v[112:115], v[32:47]
	ds_read_b128 v[2:5], v15 offset:63072
	ds_read_b128 v[6:9], v15 offset:63040
	ds_read_b128 v[10:13], v15 offset:62976
	ds_read_b128 v[184:187], v15 offset:63008
	s_waitcnt lgkmcnt(1)
	v_mfma_f32_32x32x16_bf16 v[16:31], v[10:13], v[214:217], v[16:31]
	s_waitcnt lgkmcnt(0)
	v_mfma_f32_32x32x16_bf16 v[16:31], v[184:187], v[210:213], v[16:31]
	v_mfma_f32_32x32x16_bf16 v[16:31], v[6:9], v[198:201], v[16:31]
	v_mfma_f32_32x32x16_bf16 v[16:31], v[2:5], v[112:115], v[16:31]
	ds_read_b128 v[112:115], v15 offset:36992
	ds_read_b128 v[10:13], v15 offset:37024
	ds_read_b128 v[2:5], v15 offset:37056
	ds_read_b128 v[6:9], v15 offset:37088
	v_max3_f32 v184, v96, v80, v97
	v_max_f32_e32 v185, v95, v95
	v_max3_f32 v184, v184, v81, v98
	v_max3_f32 v184, v184, v82, v99
	v_max3_f32 v184, v184, v83, v100
	v_max3_f32 v184, v184, v84, v101
	v_max3_f32 v184, v184, v85, v102
	v_max3_f32 v184, v184, v86, v103
	v_max3_f32 v184, v184, v87, v104
	v_max3_f32 v184, v184, v88, v105
	v_max3_f32 v184, v184, v89, v106
	v_max3_f32 v184, v184, v90, v107
	v_max3_f32 v184, v184, v91, v108
	v_max3_f32 v184, v184, v92, v109
	v_max3_f32 v184, v184, v93, v110
	v_max3_f32 v184, v184, v94, v111
	s_nop 0
	v_max_f32_e32 v184, v184, v184
	v_max_f32_e32 v184, v184, v185
	v_mov_b32_e32 v185, v184
	v_nop
	v_nop
	v_permlane32_swap_b32 v184, v185
	s_nop 0
	v_max3_f32 v206, v14, v184, v185
	v_sub_f32_e32 v14, v14, v206
	v_exp_f32_e32 v14, v14
	s_nop 0
	v_cmp_neq_f32_e32 vcc, 1.0, v14
	s_cbranch_vccz .LBB0_145
	v_mul_f32_e32 v78, v14, v78
	v_mul_f32_e32 v79, v14, v79
	v_mul_f32_e32 v76, v14, v76
	v_mul_f32_e32 v77, v14, v77
	v_mul_f32_e32 v74, v14, v74
	v_mul_f32_e32 v75, v14, v75
	v_mul_f32_e32 v72, v14, v72
	v_mul_f32_e32 v73, v14, v73
	v_mul_f32_e32 v70, v14, v70
	v_mul_f32_e32 v71, v14, v71
	v_mul_f32_e32 v68, v14, v68
	v_mul_f32_e32 v69, v14, v69
	v_mul_f32_e32 v66, v14, v66
	v_mul_f32_e32 v67, v14, v67
	v_mul_f32_e32 v64, v14, v64
	v_mul_f32_e32 v65, v14, v65
	v_mul_f32_e32 v62, v14, v62
	v_mul_f32_e32 v63, v14, v63
	v_mul_f32_e32 v60, v14, v60
	v_mul_f32_e32 v61, v14, v61
	v_mul_f32_e32 v58, v14, v58
	v_mul_f32_e32 v59, v14, v59
	v_mul_f32_e32 v56, v14, v56
	v_mul_f32_e32 v57, v14, v57
	v_mul_f32_e32 v54, v14, v54
	v_mul_f32_e32 v55, v14, v55
	v_mul_f32_e32 v52, v14, v52
	v_mul_f32_e32 v53, v14, v53
	v_mul_f32_e32 v50, v14, v50
	v_mul_f32_e32 v51, v14, v51
	v_mul_f32_e32 v48, v14, v48
	v_mul_f32_e32 v49, v14, v49
	v_mul_f32_e32 v46, v14, v46
	v_mul_f32_e32 v47, v14, v47
	v_mul_f32_e32 v44, v14, v44
	v_mul_f32_e32 v45, v14, v45
	v_mul_f32_e32 v42, v14, v42
	v_mul_f32_e32 v43, v14, v43
	v_mul_f32_e32 v40, v14, v40
	v_mul_f32_e32 v41, v14, v41
	v_mul_f32_e32 v38, v14, v38
	v_mul_f32_e32 v39, v14, v39
	v_mul_f32_e32 v36, v14, v36
	v_mul_f32_e32 v37, v14, v37
	v_mul_f32_e32 v34, v14, v34
	v_mul_f32_e32 v35, v14, v35
	v_mul_f32_e32 v32, v14, v32
	v_mul_f32_e32 v33, v14, v33
	v_mul_f32_e32 v30, v14, v30
	v_mul_f32_e32 v31, v14, v31
	v_mul_f32_e32 v28, v14, v28
	v_mul_f32_e32 v29, v14, v29
	v_mul_f32_e32 v26, v14, v26
	v_mul_f32_e32 v27, v14, v27
	v_mul_f32_e32 v24, v14, v24
	v_mul_f32_e32 v25, v14, v25
	v_mul_f32_e32 v22, v14, v22
	v_mul_f32_e32 v23, v14, v23
	v_mul_f32_e32 v20, v14, v20
	v_mul_f32_e32 v21, v14, v21
	v_mul_f32_e32 v18, v14, v18
	v_mul_f32_e32 v19, v14, v19
	v_mul_f32_e32 v16, v14, v16
	v_mul_f32_e32 v17, v14, v17

.LBB0_151:
	s_and_b32 s4, s3, 1
	s_mul_i32 s5, s4, 0x4800
	v_add_u32_e32 v192, s5, v202
	ds_read_b128 v[66:69], v192
	ds_read_b128 v[70:73], v192 offset:32
	ds_read_b128 v[74:77], v192 offset:4608
	ds_read_b128 v[78:81], v192 offset:4640
	ds_read_b128 v[82:85], v192 offset:64
	ds_read_b128 v[86:89], v192 offset:96
	ds_read_b128 v[90:93], v192 offset:4672
	ds_read_b128 v[94:97], v192 offset:4704
	s_waitcnt lgkmcnt(7)
	v_mfma_f32_32x32x16_bf16 v[114:129], v[66:69], v[130:133], 0
	s_waitcnt lgkmcnt(5)
	v_mfma_f32_32x32x16_bf16 v[98:113], v[74:77], v[130:133], 0
	v_mfma_f32_32x32x16_bf16 v[114:129], v[70:73], v[154:157], v[114:129]
	s_waitcnt lgkmcnt(4)
	v_mfma_f32_32x32x16_bf16 v[98:113], v[78:81], v[154:157], v[98:113]
	s_waitcnt lgkmcnt(3)
	v_mfma_f32_32x32x16_bf16 v[114:129], v[82:85], v[134:137], v[114:129]
	s_waitcnt lgkmcnt(1)
	v_mfma_f32_32x32x16_bf16 v[98:113], v[90:93], v[134:137], v[98:113]
	v_mfma_f32_32x32x16_bf16 v[114:129], v[86:89], v[158:161], v[114:129]
	s_waitcnt lgkmcnt(0)
	v_mfma_f32_32x32x16_bf16 v[98:113], v[94:97], v[158:161], v[98:113]
	ds_read_b128 v[66:69], v192 offset:9216
	ds_read_b128 v[170:173], v192 offset:9248
	ds_read_b128 v[70:73], v192 offset:13824
	ds_read_b128 v[174:177], v192 offset:13856
	ds_read_b128 v[178:181], v192 offset:9280
	ds_read_b128 v[182:185], v192 offset:9312
	ds_read_b128 v[198:201], v192 offset:13888
	ds_read_b128 v[208:211], v192 offset:13920
	s_waitcnt lgkmcnt(7)
	v_mfma_f32_32x32x16_bf16 v[82:97], v[66:69], v[130:133], 0
	s_waitcnt lgkmcnt(5)
	v_mfma_f32_32x32x16_bf16 v[66:81], v[70:73], v[130:133], 0
	v_mfma_f32_32x32x16_bf16 v[82:97], v[170:173], v[154:157], v[82:97]
	s_waitcnt lgkmcnt(4)
	v_mfma_f32_32x32x16_bf16 v[66:81], v[174:177], v[154:157], v[66:81]
	s_waitcnt lgkmcnt(3)
	v_mfma_f32_32x32x16_bf16 v[82:97], v[178:181], v[134:137], v[82:97]
	s_waitcnt lgkmcnt(1)
	v_mfma_f32_32x32x16_bf16 v[66:81], v[198:201], v[134:137], v[66:81]
	v_mfma_f32_32x32x16_bf16 v[82:97], v[182:185], v[158:161], v[82:97]
	s_waitcnt lgkmcnt(0)
	v_mfma_f32_32x32x16_bf16 v[66:81], v[208:211], v[158:161], v[66:81]
	s_mul_i32 s5, s4, 0x8800
	v_add_u32_e32 v205, s5, v203
	ds_read_b128 v[182:185], v205 offset:36864
	ds_read_b128 v[178:181], v205 offset:36896
	ds_read_b128 v[170:173], v205 offset:36928
	ds_read_b128 v[174:177], v205 offset:36960
	v_max3_f32 v192, v114, v98, v115
	v_max_f32_e32 v198, v113, v113
	v_max3_f32 v192, v192, v99, v116
	v_max3_f32 v192, v192, v100, v117
	v_max3_f32 v192, v192, v101, v118
	v_max3_f32 v192, v192, v102, v119
	v_max3_f32 v192, v192, v103, v120
	v_max3_f32 v192, v192, v104, v121
	v_max3_f32 v192, v192, v105, v122
	v_max3_f32 v192, v192, v106, v123
	v_max3_f32 v192, v192, v107, v124
	v_max3_f32 v192, v192, v108, v125
	v_max3_f32 v192, v192, v109, v126
	v_max3_f32 v192, v192, v110, v127
	v_max3_f32 v192, v192, v111, v128
	v_max3_f32 v192, v192, v112, v129
	s_nop 0
	v_max_f32_e32 v192, v192, v192
	v_max_f32_e32 v192, v192, v198
	v_mov_b32_e32 v198, v192
	v_nop
	v_nop
	v_permlane32_swap_b32 v192, v198
	s_nop 0
	v_max3_f32 v234, v206, v192, v198
	v_sub_f32_e32 v192, v206, v234
	v_exp_f32_e32 v192, v192
	s_nop 0
	v_cmp_neq_f32_e32 vcc, 1.0, v192
	s_cbranch_vccz .LBB0_153
	v_mul_f32_e32 v16, v192, v16
	v_mul_f32_e32 v17, v192, v17
	v_mul_f32_e32 v14, v192, v14
	v_mul_f32_e32 v15, v192, v15
	v_mul_f32_e32 v12, v192, v12
	v_mul_f32_e32 v13, v192, v13
	v_mul_f32_e32 v10, v192, v10
	v_mul_f32_e32 v11, v192, v11
	v_mul_f32_e32 v8, v192, v8
	v_mul_f32_e32 v9, v192, v9
	v_mul_f32_e32 v6, v192, v6
	v_mul_f32_e32 v7, v192, v7
	v_mul_f32_e32 v4, v192, v4
	v_mul_f32_e32 v5, v192, v5
	v_mul_f32_e32 v2, v192, v2
	v_mul_f32_e32 v3, v192, v3
	v_mul_f32_e32 v64, v192, v64
	v_mul_f32_e32 v65, v192, v65
	v_mul_f32_e32 v62, v192, v62
	v_mul_f32_e32 v63, v192, v63
	v_mul_f32_e32 v60, v192, v60
	v_mul_f32_e32 v61, v192, v61
	v_mul_f32_e32 v58, v192, v58
	v_mul_f32_e32 v59, v192, v59
	v_mul_f32_e32 v56, v192, v56
	v_mul_f32_e32 v57, v192, v57
	v_mul_f32_e32 v54, v192, v54
	v_mul_f32_e32 v55, v192, v55
	v_mul_f32_e32 v52, v192, v52
	v_mul_f32_e32 v53, v192, v53
	v_mul_f32_e32 v50, v192, v50
	v_mul_f32_e32 v51, v192, v51
	v_mul_f32_e32 v48, v192, v48
	v_mul_f32_e32 v49, v192, v49
	v_mul_f32_e32 v46, v192, v46
	v_mul_f32_e32 v47, v192, v47
	v_mul_f32_e32 v44, v192, v44
	v_mul_f32_e32 v45, v192, v45
	v_mul_f32_e32 v42, v192, v42
	v_mul_f32_e32 v43, v192, v43
	v_mul_f32_e32 v40, v192, v40
	v_mul_f32_e32 v41, v192, v41
	v_mul_f32_e32 v38, v192, v38
	v_mul_f32_e32 v39, v192, v39
	v_mul_f32_e32 v36, v192, v36
	v_mul_f32_e32 v37, v192, v37
	v_mul_f32_e32 v34, v192, v34
	v_mul_f32_e32 v35, v192, v35
	v_mul_f32_e32 v32, v192, v32
	v_mul_f32_e32 v33, v192, v33
	v_mul_f32_e32 v30, v192, v30
	v_mul_f32_e32 v31, v192, v31
	v_mul_f32_e32 v28, v192, v28
	v_mul_f32_e32 v29, v192, v29
	v_mul_f32_e32 v26, v192, v26
	v_mul_f32_e32 v27, v192, v27
	v_mul_f32_e32 v24, v192, v24
	v_mul_f32_e32 v25, v192, v25
	v_mul_f32_e32 v22, v192, v22
	v_mul_f32_e32 v23, v192, v23
	v_mul_f32_e32 v20, v192, v20
	v_mul_f32_e32 v21, v192, v21
	v_mul_f32_e32 v18, v192, v18
	v_mul_f32_e32 v19, v192, v19
.LBB0_153:
	v_sub_f32_e32 v98, v98, v234
	v_exp_f32_e32 v208, v98
	v_sub_f32_e32 v98, v115, v234
	v_exp_f32_e32 v115, v98
	v_sub_f32_e32 v98, v99, v234
	v_exp_f32_e32 v209, v98
	v_sub_f32_e32 v98, v116, v234
	v_exp_f32_e32 v116, v98
	v_sub_f32_e32 v98, v100, v234
	v_exp_f32_e32 v220, v98
	v_sub_f32_e32 v98, v117, v234
	v_exp_f32_e32 v117, v98
	v_sub_f32_e32 v98, v101, v234
	v_exp_f32_e32 v221, v98
	v_sub_f32_e32 v98, v118, v234
	v_exp_f32_e32 v118, v98
	v_sub_f32_e32 v98, v102, v234
	v_exp_f32_e32 v222, v98
	v_sub_f32_e32 v98, v119, v234
	v_exp_f32_e32 v119, v98
	v_sub_f32_e32 v98, v103, v234
	v_exp_f32_e32 v223, v98
	v_sub_f32_e32 v98, v120, v234
	v_exp_f32_e32 v120, v98
	v_sub_f32_e32 v98, v104, v234
	v_exp_f32_e32 v224, v98
	v_sub_f32_e32 v98, v121, v234
	v_exp_f32_e32 v121, v98
	v_sub_f32_e32 v98, v105, v234
	v_exp_f32_e32 v225, v98
	v_sub_f32_e32 v98, v122, v234
	v_exp_f32_e32 v122, v98
	v_sub_f32_e32 v98, v106, v234
	v_exp_f32_e32 v226, v98
	v_sub_f32_e32 v98, v123, v234
	v_exp_f32_e32 v123, v98
	v_sub_f32_e32 v98, v107, v234
	v_exp_f32_e32 v227, v98
	v_sub_f32_e32 v98, v124, v234
	v_exp_f32_e32 v124, v98
	v_sub_f32_e32 v98, v108, v234
	v_exp_f32_e32 v228, v98
	v_sub_f32_e32 v98, v125, v234
	v_exp_f32_e32 v125, v98
	v_sub_f32_e32 v98, v109, v234
	v_exp_f32_e32 v229, v98
	v_sub_f32_e32 v98, v126, v234
	v_exp_f32_e32 v126, v98
	v_sub_f32_e32 v98, v110, v234
	v_exp_f32_e32 v230, v98
	v_sub_f32_e32 v98, v127, v234
	v_exp_f32_e32 v127, v98
	v_sub_f32_e32 v98, v111, v234
	v_exp_f32_e32 v231, v98
	v_sub_f32_e32 v98, v128, v234
	v_exp_f32_e32 v128, v98
	v_sub_f32_e32 v98, v112, v234
	v_exp_f32_e32 v232, v98
	v_sub_f32_e32 v98, v129, v234
	v_sub_f32_e32 v114, v114, v234
	v_exp_f32_e32 v129, v98
	v_sub_f32_e32 v98, v113, v234
	v_exp_f32_e32 v207, v114
	v_exp_f32_e32 v233, v98
	v_cvt_pk_bf16_f32 v98, v226, v227
	v_cvt_pk_bf16_f32 v99, v228, v229
	v_cvt_pk_bf16_f32 v100, v230, v231
	v_cvt_pk_bf16_f32 v101, v232, v233
	v_cvt_pk_bf16_f32 v102, v208, v209
	v_cvt_pk_bf16_f32 v103, v220, v221
	v_cvt_pk_bf16_f32 v104, v222, v223
	v_cvt_pk_bf16_f32 v105, v224, v225
	v_cvt_pk_bf16_f32 v106, v122, v123
	v_cvt_pk_bf16_f32 v107, v124, v125
	v_cvt_pk_bf16_f32 v108, v126, v127
	v_cvt_pk_bf16_f32 v109, v128, v129
	v_cvt_pk_bf16_f32 v110, v207, v115
	v_cvt_pk_bf16_f32 v111, v116, v117
	v_cvt_pk_bf16_f32 v112, v118, v119
	v_cvt_pk_bf16_f32 v113, v120, v121
	s_waitcnt lgkmcnt(3)
	s_nop 0
	v_mfma_f32_32x32x16_bf16 v[2:17], v[182:185], v[110:113], v[2:17]
	s_waitcnt lgkmcnt(2)
	v_mfma_f32_32x32x16_bf16 v[2:17], v[178:181], v[106:109], v[2:17]
	s_waitcnt lgkmcnt(1)
	v_mfma_f32_32x32x16_bf16 v[2:17], v[170:173], v[102:105], v[2:17]
	s_waitcnt lgkmcnt(0)
	v_mfma_f32_32x32x16_bf16 v[2:17], v[174:177], v[98:101], v[2:17]
	ds_read_b128 v[170:173], v205 offset:45664
	ds_read_b128 v[174:177], v205 offset:45632
	ds_read_b128 v[178:181], v205 offset:45568
	ds_read_b128 v[182:185], v205 offset:45600
	s_waitcnt lgkmcnt(1)
	v_mfma_f32_32x32x16_bf16 v[50:65], v[178:181], v[110:113], v[50:65]
	s_waitcnt lgkmcnt(0)
	v_mfma_f32_32x32x16_bf16 v[50:65], v[182:185], v[106:109], v[50:65]
	v_mfma_f32_32x32x16_bf16 v[50:65], v[174:177], v[102:105], v[50:65]
	v_mfma_f32_32x32x16_bf16 v[50:65], v[170:173], v[98:101], v[50:65]
	ds_read_b128 v[170:173], v205 offset:54368
	ds_read_b128 v[174:177], v205 offset:54336
	ds_read_b128 v[178:181], v205 offset:54272
	ds_read_b128 v[182:185], v205 offset:54304
	s_waitcnt lgkmcnt(1)
	v_mfma_f32_32x32x16_bf16 v[34:49], v[178:181], v[110:113], v[34:49]
	s_waitcnt lgkmcnt(0)
	v_mfma_f32_32x32x16_bf16 v[34:49], v[182:185], v[106:109], v[34:49]
	v_mfma_f32_32x32x16_bf16 v[34:49], v[174:177], v[102:105], v[34:49]
	v_mfma_f32_32x32x16_bf16 v[34:49], v[170:173], v[98:101], v[34:49]
	ds_read_b128 v[170:173], v205 offset:63072
	ds_read_b128 v[174:177], v205 offset:63040
	ds_read_b128 v[178:181], v205 offset:62976
	ds_read_b128 v[182:185], v205 offset:63008
	s_waitcnt lgkmcnt(1)
	v_mfma_f32_32x32x16_bf16 v[18:33], v[178:181], v[110:113], v[18:33]
	s_waitcnt lgkmcnt(0)
	v_mfma_f32_32x32x16_bf16 v[18:33], v[182:185], v[106:109], v[18:33]
	v_mfma_f32_32x32x16_bf16 v[18:33], v[174:177], v[102:105], v[18:33]
	v_mfma_f32_32x32x16_bf16 v[18:33], v[170:173], v[98:101], v[18:33]
	ds_read_b128 v[110:113], v205 offset:36992
	ds_read_b128 v[106:109], v205 offset:37024
	ds_read_b128 v[98:101], v205 offset:37056
	ds_read_b128 v[102:105], v205 offset:37088
	v_max3_f32 v114, v82, v66, v83
	v_max_f32_e32 v170, v81, v81
	v_max3_f32 v114, v114, v67, v84
	v_max3_f32 v114, v114, v68, v85
	v_max3_f32 v114, v114, v69, v86
	v_max3_f32 v114, v114, v70, v87
	v_max3_f32 v114, v114, v71, v88
	v_max3_f32 v114, v114, v72, v89
	v_max3_f32 v114, v114, v73, v90
	v_max3_f32 v114, v114, v74, v91
	v_max3_f32 v114, v114, v75, v92
	v_max3_f32 v114, v114, v76, v93
	v_max3_f32 v114, v114, v77, v94
	v_max3_f32 v114, v114, v78, v95
	v_max3_f32 v114, v114, v79, v96
	v_max3_f32 v114, v114, v80, v97
	s_nop 0
	v_max_f32_e32 v114, v114, v114
	v_max_f32_e32 v114, v114, v170
	v_mov_b32_e32 v170, v114
	v_nop
	v_nop
	v_permlane32_swap_b32 v114, v170
	s_nop 0
	v_max3_f32 v206, v234, v114, v170
	v_sub_f32_e32 v114, v234, v206
	v_exp_f32_e32 v114, v114
	s_nop 0
	v_cmp_neq_f32_e32 vcc, 1.0, v114
	s_cbranch_vccz .LBB0_155
	v_mul_f32_e32 v16, v114, v16
	v_mul_f32_e32 v17, v114, v17
	v_mul_f32_e32 v14, v114, v14
	v_mul_f32_e32 v15, v114, v15
	v_mul_f32_e32 v12, v114, v12
	v_mul_f32_e32 v13, v114, v13
	v_mul_f32_e32 v10, v114, v10
	v_mul_f32_e32 v11, v114, v11
	v_mul_f32_e32 v8, v114, v8
	v_mul_f32_e32 v9, v114, v9
	v_mul_f32_e32 v6, v114, v6
	v_mul_f32_e32 v7, v114, v7
	v_mul_f32_e32 v4, v114, v4
	v_mul_f32_e32 v5, v114, v5
	v_mul_f32_e32 v2, v114, v2
	v_mul_f32_e32 v3, v114, v3
	v_mul_f32_e32 v64, v114, v64
	v_mul_f32_e32 v65, v114, v65
	v_mul_f32_e32 v62, v114, v62
	v_mul_f32_e32 v63, v114, v63
	v_mul_f32_e32 v60, v114, v60
	v_mul_f32_e32 v61, v114, v61
	v_mul_f32_e32 v58, v114, v58
	v_mul_f32_e32 v59, v114, v59
	v_mul_f32_e32 v56, v114, v56
	v_mul_f32_e32 v57, v114, v57
	v_mul_f32_e32 v54, v114, v54
	v_mul_f32_e32 v55, v114, v55
	v_mul_f32_e32 v52, v114, v52
	v_mul_f32_e32 v53, v114, v53
	v_mul_f32_e32 v50, v114, v50
	v_mul_f32_e32 v51, v114, v51
	v_mul_f32_e32 v48, v114, v48
	v_mul_f32_e32 v49, v114, v49
	v_mul_f32_e32 v46, v114, v46
	v_mul_f32_e32 v47, v114, v47
	v_mul_f32_e32 v44, v114, v44
	v_mul_f32_e32 v45, v114, v45
	v_mul_f32_e32 v42, v114, v42
	v_mul_f32_e32 v43, v114, v43
	v_mul_f32_e32 v40, v114, v40
	v_mul_f32_e32 v41, v114, v41
	v_mul_f32_e32 v38, v114, v38
	v_mul_f32_e32 v39, v114, v39
	v_mul_f32_e32 v36, v114, v36
	v_mul_f32_e32 v37, v114, v37
	v_mul_f32_e32 v34, v114, v34
	v_mul_f32_e32 v35, v114, v35
	v_mul_f32_e32 v32, v114, v32
	v_mul_f32_e32 v33, v114, v33
	v_mul_f32_e32 v30, v114, v30
	v_mul_f32_e32 v31, v114, v31
	v_mul_f32_e32 v28, v114, v28
	v_mul_f32_e32 v29, v114, v29
	v_mul_f32_e32 v26, v114, v26
	v_mul_f32_e32 v27, v114, v27
	v_mul_f32_e32 v24, v114, v24
	v_mul_f32_e32 v25, v114, v25
	v_mul_f32_e32 v22, v114, v22
	v_mul_f32_e32 v23, v114, v23
	v_mul_f32_e32 v20, v114, v20
	v_mul_f32_e32 v21, v114, v21
	v_mul_f32_e32 v18, v114, v18
	v_mul_f32_e32 v19, v114, v19

.LBB0_158:
	v_add_f32_e32 v131, v160, v161
	v_add_f32_e32 v131, 0, v131
	v_add_f32_e32 v132, v162, v163
	v_add_f32_e32 v131, v132, v131
	v_add_f32_e32 v132, v164, v165
	v_add_f32_e32 v131, v132, v131
	v_add_f32_e32 v132, v166, v167
	v_add_f32_e32 v131, v132, v131
	v_add_f32_e32 v132, v168, v169
	v_add_f32_e32 v131, v132, v131
	v_add_f32_e32 v132, v170, v171
	v_add_f32_e32 v131, v132, v131
	v_add_f32_e32 v132, v172, v173
	v_add_f32_e32 v131, v132, v131
	v_add_f32_e32 v132, v174, v175
	v_add_f32_e32 v131, v132, v131
	v_add_f32_e32 v132, v176, v177
	v_add_f32_e32 v131, v132, v131
	v_add_f32_e32 v132, v178, v179
	v_add_f32_e32 v131, v132, v131
	v_add_f32_e32 v132, v180, v181
	v_add_f32_e32 v131, v132, v131
	v_add_f32_e32 v132, v182, v183
	v_add_f32_e32 v131, v132, v131
	v_add_f32_e32 v132, v184, v185
	v_add_f32_e32 v131, v132, v131
	v_add_f32_e32 v132, v186, v187
	v_add_f32_e32 v131, v132, v131
	v_add_f32_e32 v132, v188, v189
	v_add_f32_e32 v131, v132, v131
	v_add_f32_e32 v132, v190, v192
	v_add_f32_e32 v131, v132, v131
	v_add_f32_e32 v132, v204, v205
	v_add_f32_e32 v132, 0, v132
	v_add_f32_e32 v133, v206, v207
	v_add_f32_e32 v132, v133, v132
	v_add_f32_e32 v133, v208, v209
	v_add_f32_e32 v132, v133, v132
	v_add_f32_e32 v133, v220, v221
	v_add_f32_e32 v132, v133, v132
	v_add_f32_e32 v133, v222, v223
	v_add_f32_e32 v132, v133, v132
	v_add_f32_e32 v133, v224, v225
	v_add_f32_e32 v132, v133, v132
	v_add_f32_e32 v133, v226, v227
	v_add_f32_e32 v132, v133, v132
	v_add_f32_e32 v133, v228, v229
	v_add_f32_e32 v132, v133, v132
	v_add_f32_e32 v133, v230, v231
	v_add_f32_e32 v132, v133, v132
	v_add_f32_e32 v133, v232, v233
	v_add_f32_e32 v132, v133, v132
	v_add_f32_e32 v133, v234, v235
	v_add_f32_e32 v132, v133, v132
	v_add_f32_e32 v133, v236, v237
	v_add_f32_e32 v132, v133, v132
	v_add_f32_e32 v133, v238, v239
	v_add_f32_e32 v132, v133, v132
	v_add_f32_e32 v133, v240, v241
	v_add_f32_e32 v132, v133, v132
	v_add_f32_e32 v133, v242, v243
	v_add_f32_e32 v132, v133, v132
	v_add_f32_e32 v133, v244, v245
	v_add_f32_e32 v131, v191, v131
	v_add_f32_e32 v132, v133, v132
	v_fmac_f32_e32 v132, v131, v158
	v_add_f32_e32 v131, v147, v148
	v_add_f32_e32 v131, 0, v131
	v_add_f32_e32 v133, v149, v150
	v_add_f32_e32 v131, v133, v131
	v_add_f32_e32 v133, v151, v152
	v_add_f32_e32 v131, v133, v131
	v_add_f32_e32 v117, v117, v153
	v_add_f32_e32 v117, v117, v131
	v_add_f32_e32 v118, v118, v194
	v_add_f32_e32 v117, v118, v117
	v_add_f32_e32 v118, v119, v195
	v_add_f32_e32 v117, v118, v117
	v_add_f32_e32 v118, v120, v202
	v_add_f32_e32 v117, v118, v117
	v_add_f32_e32 v118, v121, v203
	v_add_f32_e32 v117, v118, v117
	v_add_f32_e32 v118, v122, v246
	v_add_f32_e32 v117, v118, v117
	v_add_f32_e32 v118, v123, v247
	v_add_f32_e32 v117, v118, v117
	v_add_f32_e32 v118, v124, v248
	v_add_f32_e32 v117, v118, v117
	v_add_f32_e32 v118, v125, v249
	v_add_f32_e32 v117, v118, v117
	v_add_f32_e32 v118, v126, v250
	v_sub_f32_e32 v68, v68, v130
	v_add_f32_e32 v117, v118, v117
	v_add_f32_e32 v118, v127, v251
	v_exp_f32_e32 v120, v68
	v_sub_f32_e32 v68, v85, v130
	v_add_f32_e32 v117, v118, v117
	v_add_f32_e32 v118, v128, v252
	v_exp_f32_e32 v85, v68
	v_sub_f32_e32 v68, v69, v130
	v_add_f32_e32 v117, v118, v117
	v_add_f32_e32 v118, v129, v253
	v_sub_f32_e32 v66, v66, v130
	v_exp_f32_e32 v121, v68
	v_sub_f32_e32 v68, v86, v130
	v_add_f32_e32 v117, v118, v117
	v_sub_f32_e32 v82, v82, v130
	v_exp_f32_e32 v118, v66
	v_sub_f32_e32 v66, v83, v130
	v_exp_f32_e32 v86, v68
	v_sub_f32_e32 v68, v70, v130
	v_exp_f32_e32 v82, v82
	v_exp_f32_e32 v83, v66
	v_sub_f32_e32 v66, v67, v130
	v_exp_f32_e32 v122, v68
	v_sub_f32_e32 v68, v87, v130
	v_exp_f32_e32 v119, v66
	v_sub_f32_e32 v84, v84, v130
	v_exp_f32_e32 v87, v68
	v_sub_f32_e32 v68, v71, v130
	v_exp_f32_e32 v84, v84
	v_exp_f32_e32 v123, v68
	v_sub_f32_e32 v68, v88, v130
	v_exp_f32_e32 v88, v68
	v_sub_f32_e32 v68, v72, v130
	v_add_f32_e32 v66, v82, v118
	v_exp_f32_e32 v124, v68
	v_sub_f32_e32 v68, v89, v130
	v_add_f32_e32 v66, 0, v66
	v_add_f32_e32 v67, v83, v119
	v_exp_f32_e32 v89, v68
	v_sub_f32_e32 v68, v73, v130
	v_add_f32_e32 v66, v67, v66
	v_add_f32_e32 v67, v84, v120
	v_exp_f32_e32 v73, v68
	v_sub_f32_e32 v68, v90, v130
	v_add_f32_e32 v66, v67, v66
	v_add_f32_e32 v67, v85, v121
	v_exp_f32_e32 v90, v68
	v_sub_f32_e32 v68, v74, v130
	v_sub_f32_e32 v69, v91, v130
	v_add_f32_e32 v66, v67, v66
	v_add_f32_e32 v67, v86, v122
	v_exp_f32_e32 v68, v68
	v_exp_f32_e32 v74, v69
	v_sub_f32_e32 v69, v75, v130
	v_sub_f32_e32 v70, v92, v130
	v_add_f32_e32 v66, v67, v66
	v_add_f32_e32 v67, v87, v123
	v_exp_f32_e32 v69, v69
	v_exp_f32_e32 v75, v70
	v_sub_f32_e32 v70, v76, v130
	v_sub_f32_e32 v71, v93, v130
	v_add_f32_e32 v66, v67, v66
	v_add_f32_e32 v67, v88, v124
	v_exp_f32_e32 v70, v70
	v_exp_f32_e32 v76, v71
	v_sub_f32_e32 v71, v77, v130
	v_sub_f32_e32 v72, v94, v130
	v_add_f32_e32 v66, v67, v66
	v_add_f32_e32 v67, v89, v73
	v_exp_f32_e32 v71, v71
	v_exp_f32_e32 v77, v72
	v_sub_f32_e32 v72, v78, v130
	v_add_f32_e32 v66, v67, v66
	v_add_f32_e32 v67, v90, v68
	v_exp_f32_e32 v72, v72
	v_sub_f32_e32 v78, v95, v130
	v_sub_f32_e32 v79, v79, v130
	v_add_f32_e32 v66, v67, v66
	v_add_f32_e32 v67, v74, v69
	v_exp_f32_e32 v78, v78
	v_exp_f32_e32 v79, v79
	v_sub_f32_e32 v91, v96, v130
	v_sub_f32_e32 v80, v80, v130
	v_add_f32_e32 v66, v67, v66
	v_add_f32_e32 v67, v75, v70
	v_exp_f32_e32 v91, v91
	v_exp_f32_e32 v80, v80
	v_sub_f32_e32 v92, v97, v130
	v_sub_f32_e32 v81, v81, v130
	v_add_f32_e32 v66, v67, v66
	v_add_f32_e32 v67, v76, v71
	v_exp_f32_e32 v92, v92
	v_exp_f32_e32 v81, v81
	v_add_f32_e32 v66, v67, v66
	v_add_f32_e32 v67, v77, v72
	v_add_f32_e32 v66, v67, v66
	v_add_f32_e32 v67, v78, v79
	v_add_f32_e32 v66, v67, v66
	v_add_f32_e32 v67, v91, v80
	v_add_f32_e32 v66, v67, v66
	v_add_f32_e32 v67, v92, v81
	v_fmac_f32_e32 v117, v132, v146
	v_add_f32_e32 v125, v67, v66
	v_lshlrev_b64 v[114:115], 10, v[156:157]
	v_fmac_f32_e32 v125, v117, v116
	v_cvt_pk_bf16_f32 v66, v68, v69
	v_cvt_pk_bf16_f32 v67, v70, v71
	v_cvt_pk_bf16_f32 v68, v72, v79
	v_cvt_pk_bf16_f32 v69, v80, v81
	v_cvt_pk_bf16_f32 v70, v118, v119
	v_cvt_pk_bf16_f32 v71, v120, v121
	v_cvt_pk_bf16_f32 v72, v122, v123
	v_cvt_pk_bf16_f32 v73, v124, v73
	v_cvt_pk_bf16_f32 v74, v90, v74
	v_cvt_pk_bf16_f32 v75, v75, v76
	v_cvt_pk_bf16_f32 v76, v77, v78
	v_cvt_pk_bf16_f32 v77, v91, v92
	v_cvt_pk_bf16_f32 v78, v82, v83
	v_cvt_pk_bf16_f32 v79, v84, v85
	v_cvt_pk_bf16_f32 v80, v86, v87
	v_cvt_pk_bf16_f32 v81, v88, v89
	s_waitcnt lgkmcnt(3)
	s_nop 0
	v_mfma_f32_32x32x16_bf16 v[2:17], v[110:113], v[78:81], v[2:17]
	ds_read_b128 v[82:85], v193 offset:43744
	ds_read_b128 v[86:89], v193 offset:43712
	ds_read_b128 v[90:93], v193 offset:43648
	ds_read_b128 v[94:97], v193 offset:43680
	s_waitcnt lgkmcnt(6)
	v_mfma_f32_32x32x16_bf16 v[2:17], v[106:109], v[74:77], v[2:17]
	s_waitcnt lgkmcnt(5)
	v_mfma_f32_32x32x16_bf16 v[2:17], v[98:101], v[70:73], v[2:17]
	s_waitcnt lgkmcnt(4)
	v_mfma_f32_32x32x16_bf16 v[2:17], v[102:105], v[66:69], v[2:17]
	s_waitcnt lgkmcnt(1)
	v_mfma_f32_32x32x16_bf16 v[50:65], v[90:93], v[78:81], v[50:65]
	s_waitcnt lgkmcnt(0)
	v_mfma_f32_32x32x16_bf16 v[50:65], v[94:97], v[74:77], v[50:65]
	v_mfma_f32_32x32x16_bf16 v[50:65], v[86:89], v[70:73], v[50:65]
	v_mfma_f32_32x32x16_bf16 v[50:65], v[82:85], v[66:69], v[50:65]
	ds_read_b128 v[82:85], v193 offset:52448
	ds_read_b128 v[86:89], v193 offset:52416
	ds_read_b128 v[90:93], v193 offset:52352
	ds_read_b128 v[94:97], v193 offset:52384
	s_waitcnt lgkmcnt(1)
	v_mfma_f32_32x32x16_bf16 v[34:49], v[90:93], v[78:81], v[34:49]
	s_waitcnt lgkmcnt(0)
	v_mfma_f32_32x32x16_bf16 v[34:49], v[94:97], v[74:77], v[34:49]
	v_mfma_f32_32x32x16_bf16 v[34:49], v[86:89], v[70:73], v[34:49]
	v_mfma_f32_32x32x16_bf16 v[34:49], v[82:85], v[66:69], v[34:49]
	ds_read_b128 v[82:85], v193 offset:61152
	ds_read_b128 v[86:89], v193 offset:61120
	ds_read_b128 v[90:93], v193 offset:61056
	ds_read_b128 v[94:97], v193 offset:61088
	s_waitcnt lgkmcnt(1)
	v_mfma_f32_32x32x16_bf16 v[18:33], v[90:93], v[78:81], v[18:33]
	s_waitcnt lgkmcnt(0)
	v_mfma_f32_32x32x16_bf16 v[18:33], v[94:97], v[74:77], v[18:33]
	v_mfma_f32_32x32x16_bf16 v[18:33], v[86:89], v[70:73], v[18:33]
	v_mfma_f32_32x32x16_bf16 v[18:33], v[82:85], v[66:69], v[18:33]
	v_mov_b32_e32 v66, v125
	s_barrier
	v_nop
	v_nop
	v_permlane32_swap_b32 v66, v125
	v_lshlrev_b32_e32 v84, 3, v159
	v_add_f32_e32 v66, v66, v125
	v_div_scale_f32 v67, s[2:3], v66, v66, 1.0
	v_rcp_f32_e32 v68, v67
	v_mov_b32_e32 v85, v1
	s_waitcnt vmcnt(0)
	v_mov_b32_e32 v87, v56
	v_fma_f32 v69, -v67, v68, 1.0
	v_fmac_f32_e32 v68, v69, v68
	v_div_scale_f32 v69, vcc, 1.0, v66, 1.0
	v_mul_f32_e32 v70, v69, v68
	v_fma_f32 v71, -v67, v70, v69
	v_fmac_f32_e32 v70, v71, v68
	v_fma_f32 v67, -v67, v70, v69
	v_div_fmas_f32 v67, v67, v68, v70
	v_div_fixup_f32 v70, v67, v66, 1.0
	v_lshl_add_u64 v[66:67], v[114:115], 1, s[18:19]
	v_lshl_add_u64 v[66:67], v[66:67], 0, s[80:81]
	v_lshl_add_u64 v[94:95], v[66:67], 0, v[84:85]
	global_load_dwordx2 v[72:73], v1, s[50:51]
	global_load_dwordx2 v[82:83], v[94:95], off
	global_load_dwordx2 v[80:81], v[94:95], off offset:16
	global_load_dwordx2 v[76:77], v[94:95], off offset:32
	global_load_dwordx2 v[74:75], v[94:95], off offset:48
	global_load_dwordx2 v[66:67], v[94:95], off offset:64
	v_mov_b32_e32 v56, v55
	v_mov_b32_e32 v86, v54
	v_pk_mul_f32 v[54:55], v[56:57], v[70:71] op_sel_hi:[1,0]
	v_mul_f32_e32 v86, v70, v86
	v_mul_f32_e32 v87, v70, v87
	v_mov_b32_e32 v89, v60
	v_mov_b32_e32 v60, v59
	v_mov_b32_e32 v88, v58
	v_pk_mul_f32 v[58:59], v[60:61], v[70:71] op_sel_hi:[1,0]
	v_mul_f32_e32 v88, v70, v88
	v_mul_f32_e32 v89, v70, v89
	v_mov_b32_e32 v91, v64
	v_mov_b32_e32 v64, v63
	v_mov_b32_e32 v90, v62
	v_pk_mul_f32 v[62:63], v[64:65], v[70:71] op_sel_hi:[1,0]
	v_mul_f32_e32 v90, v70, v90
	v_mul_f32_e32 v91, v70, v91
	v_mov_b32_e32 v97, v40
	v_mov_b32_e32 v40, v39
	v_mov_b32_e32 v96, v38
	v_pk_mul_f32 v[38:39], v[40:41], v[70:71] op_sel_hi:[1,0]
	v_mul_f32_e32 v96, v70, v96
	v_mul_f32_e32 v97, v70, v97
	v_mov_b32_e32 v99, v44
	v_mov_b32_e32 v44, v43
	v_mov_b32_e32 v98, v42
	v_pk_mul_f32 v[42:43], v[44:45], v[70:71] op_sel_hi:[1,0]
	v_mul_f32_e32 v98, v70, v98
	v_mul_f32_e32 v99, v70, v99
	v_mov_b32_e32 v101, v48
	v_mov_b32_e32 v48, v47
	v_mov_b32_e32 v100, v46
	v_pk_mul_f32 v[46:47], v[48:49], v[70:71] op_sel_hi:[1,0]
	v_mul_f32_e32 v100, v70, v100
	v_mul_f32_e32 v101, v70, v101
	v_mov_b32_e32 v105, v24
	v_mov_b32_e32 v24, v23
	v_mov_b32_e32 v104, v22
	v_pk_mul_f32 v[22:23], v[24:25], v[70:71] op_sel_hi:[1,0]
	v_mul_f32_e32 v104, v70, v104
	v_mul_f32_e32 v105, v70, v105
	v_mov_b32_e32 v107, v28
	v_mov_b32_e32 v28, v27
	v_mov_b32_e32 v106, v26
	v_pk_mul_f32 v[26:27], v[28:29], v[70:71] op_sel_hi:[1,0]
	v_mul_f32_e32 v106, v70, v106
	v_mul_f32_e32 v107, v70, v107
	v_readlane_b32 s2, v254, 63
	v_readlane_b32 s3, v255, 0
	v_mov_b32_e32 v252, 0x358637bd
	s_add_i32 s17, s17, s20
	s_add_i32 s0, s0, s1
	s_add_i32 s4, s4, s5
	s_cmpk_gt_i32 s17, 0xff
	s_waitcnt vmcnt(0)
	v_lshlrev_b32_e32 v69, 16, v67
	v_and_b32_e32 v79, 0xffff0000, v67
	v_mov_b32_e32 v67, v52
	v_mov_b32_e32 v52, v51
	v_lshlrev_b32_e32 v68, 16, v66
	v_and_b32_e32 v78, 0xffff0000, v66
	v_mov_b32_e32 v66, v50
	v_pk_mul_f32 v[50:51], v[52:53], v[70:71] op_sel_hi:[1,0]
	v_mul_f32_e32 v66, v70, v66
	v_mul_f32_e32 v67, v70, v67
	v_pk_fma_f32 v[50:51], v[72:73], v[50:51], v[78:79] op_sel_hi:[0,1,1] neg_lo:[1,0,0] neg_hi:[1,0,0]
	v_pk_fma_f32 v[66:67], v[72:73], v[66:67], v[68:69] op_sel_hi:[0,1,1] neg_lo:[1,0,0] neg_hi:[1,0,0]
	v_pk_mul_f32 v[52:53], v[50:51], v[50:51]
	s_nop 0
	v_pk_fma_f32 v[52:53], v[66:67], v[66:67], v[52:53]
	s_nop 0
	v_pk_add_f32 v[78:79], v[52:53], v[52:53] op_sel:[0,1] op_sel_hi:[1,0]
	global_load_dwordx2 v[52:53], v[94:95], off offset:80
	s_waitcnt vmcnt(0)
	v_lshlrev_b32_e32 v69, 16, v53
	v_lshlrev_b32_e32 v68, 16, v52
	v_and_b32_e32 v53, 0xffff0000, v53
	v_and_b32_e32 v52, 0xffff0000, v52
	v_pk_fma_f32 v[52:53], v[72:73], v[54:55], v[52:53] op_sel_hi:[0,1,1] neg_lo:[1,0,0] neg_hi:[1,0,0]
	v_pk_fma_f32 v[68:69], v[72:73], v[86:87], v[68:69] op_sel_hi:[0,1,1] neg_lo:[1,0,0] neg_hi:[1,0,0]
	v_pk_mul_f32 v[54:55], v[52:53], v[52:53]
	s_nop 0
	v_pk_fma_f32 v[54:55], v[68:69], v[68:69], v[54:55]
	s_nop 0
	v_pk_add_f32 v[86:87], v[54:55], v[54:55] op_sel:[0,1] op_sel_hi:[1,0]
	global_load_dwordx2 v[54:55], v[94:95], off offset:96
	s_waitcnt vmcnt(0)
	v_lshlrev_b32_e32 v57, 16, v55
	v_lshlrev_b32_e32 v56, 16, v54
	v_and_b32_e32 v55, 0xffff0000, v55
	v_and_b32_e32 v54, 0xffff0000, v54
	v_pk_fma_f32 v[54:55], v[72:73], v[58:59], v[54:55] op_sel_hi:[0,1,1] neg_lo:[1,0,0] neg_hi:[1,0,0]
	v_pk_fma_f32 v[56:57], v[72:73], v[88:89], v[56:57] op_sel_hi:[0,1,1] neg_lo:[1,0,0] neg_hi:[1,0,0]
	v_pk_mul_f32 v[58:59], v[54:55], v[54:55]
	s_nop 0
	v_pk_fma_f32 v[58:59], v[56:57], v[56:57], v[58:59]
	s_nop 0
	v_pk_add_f32 v[88:89], v[58:59], v[58:59] op_sel:[0,1] op_sel_hi:[1,0]
	global_load_dwordx2 v[58:59], v[94:95], off offset:112
	s_waitcnt vmcnt(0)
	v_lshlrev_b32_e32 v61, 16, v59
	v_lshlrev_b32_e32 v60, 16, v58
	v_and_b32_e32 v59, 0xffff0000, v59
	v_and_b32_e32 v58, 0xffff0000, v58
	v_pk_fma_f32 v[58:59], v[72:73], v[62:63], v[58:59] op_sel_hi:[0,1,1] neg_lo:[1,0,0] neg_hi:[1,0,0]
	v_pk_fma_f32 v[60:61], v[72:73], v[90:91], v[60:61] op_sel_hi:[0,1,1] neg_lo:[1,0,0] neg_hi:[1,0,0]
	v_pk_mul_f32 v[62:63], v[58:59], v[58:59]
	s_nop 0
	v_pk_fma_f32 v[62:63], v[60:61], v[60:61], v[62:63]
	s_nop 0
	v_pk_add_f32 v[90:91], v[62:63], v[62:63] op_sel:[0,1] op_sel_hi:[1,0]
	global_load_dwordx2 v[62:63], v[94:95], off offset:128
	s_waitcnt vmcnt(0)
	v_lshlrev_b32_e32 v65, 16, v63
	v_and_b32_e32 v93, 0xffff0000, v63
	v_mov_b32_e32 v63, v36
	v_mov_b32_e32 v36, v35
	v_lshlrev_b32_e32 v64, 16, v62
	v_and_b32_e32 v92, 0xffff0000, v62
	v_mov_b32_e32 v62, v34
	v_pk_mul_f32 v[34:35], v[36:37], v[70:71] op_sel_hi:[1,0]
	v_mul_f32_e32 v62, v70, v62
	v_mul_f32_e32 v63, v70, v63
	v_pk_fma_f32 v[34:35], v[72:73], v[34:35], v[92:93] op_sel_hi:[0,1,1] neg_lo:[1,0,0] neg_hi:[1,0,0]
	v_pk_fma_f32 v[62:63], v[72:73], v[62:63], v[64:65] op_sel_hi:[0,1,1] neg_lo:[1,0,0] neg_hi:[1,0,0]
	v_pk_mul_f32 v[36:37], v[34:35], v[34:35]
	s_nop 0
	v_pk_fma_f32 v[36:37], v[62:63], v[62:63], v[36:37]
	s_nop 0
	v_pk_add_f32 v[92:93], v[36:37], v[36:37] op_sel:[0,1] op_sel_hi:[1,0]
	global_load_dwordx2 v[36:37], v[94:95], off offset:144
	s_waitcnt vmcnt(0)
	v_lshlrev_b32_e32 v65, 16, v37
	v_lshlrev_b32_e32 v64, 16, v36
	v_and_b32_e32 v37, 0xffff0000, v37
	v_and_b32_e32 v36, 0xffff0000, v36
	v_pk_fma_f32 v[36:37], v[72:73], v[38:39], v[36:37] op_sel_hi:[0,1,1] neg_lo:[1,0,0] neg_hi:[1,0,0]
	v_pk_fma_f32 v[64:65], v[72:73], v[96:97], v[64:65] op_sel_hi:[0,1,1] neg_lo:[1,0,0] neg_hi:[1,0,0]
	v_pk_mul_f32 v[38:39], v[36:37], v[36:37]
	s_nop 0
	v_pk_fma_f32 v[38:39], v[64:65], v[64:65], v[38:39]
	s_nop 0
	v_pk_add_f32 v[96:97], v[38:39], v[38:39] op_sel:[0,1] op_sel_hi:[1,0]
	global_load_dwordx2 v[38:39], v[94:95], off offset:160
	s_waitcnt vmcnt(0)
	v_lshlrev_b32_e32 v41, 16, v39
	v_lshlrev_b32_e32 v40, 16, v38
	v_and_b32_e32 v39, 0xffff0000, v39
	v_and_b32_e32 v38, 0xffff0000, v38
	v_pk_fma_f32 v[38:39], v[72:73], v[42:43], v[38:39] op_sel_hi:[0,1,1] neg_lo:[1,0,0] neg_hi:[1,0,0]
	v_pk_fma_f32 v[40:41], v[72:73], v[98:99], v[40:41] op_sel_hi:[0,1,1] neg_lo:[1,0,0] neg_hi:[1,0,0]
	v_pk_mul_f32 v[42:43], v[38:39], v[38:39]
	s_nop 0
	v_pk_fma_f32 v[42:43], v[40:41], v[40:41], v[42:43]
	s_nop 0
	v_pk_add_f32 v[98:99], v[42:43], v[42:43] op_sel:[0,1] op_sel_hi:[1,0]
	global_load_dwordx2 v[42:43], v[94:95], off offset:176
	s_waitcnt vmcnt(0)
	v_lshlrev_b32_e32 v45, 16, v43
	v_lshlrev_b32_e32 v44, 16, v42
	v_and_b32_e32 v43, 0xffff0000, v43
	v_and_b32_e32 v42, 0xffff0000, v42
	v_pk_fma_f32 v[42:43], v[72:73], v[46:47], v[42:43] op_sel_hi:[0,1,1] neg_lo:[1,0,0] neg_hi:[1,0,0]
	v_pk_fma_f32 v[44:45], v[72:73], v[100:101], v[44:45] op_sel_hi:[0,1,1] neg_lo:[1,0,0] neg_hi:[1,0,0]
	v_pk_mul_f32 v[46:47], v[42:43], v[42:43]
	s_nop 0
	v_pk_fma_f32 v[46:47], v[44:45], v[44:45], v[46:47]
	s_nop 0
	v_pk_add_f32 v[100:101], v[46:47], v[46:47] op_sel:[0,1] op_sel_hi:[1,0]
	global_load_dwordx2 v[46:47], v[94:95], off offset:192
	s_waitcnt vmcnt(0)
	v_lshlrev_b32_e32 v49, 16, v47
	v_and_b32_e32 v103, 0xffff0000, v47
	v_mov_b32_e32 v47, v20
	v_mov_b32_e32 v20, v19
	v_lshlrev_b32_e32 v48, 16, v46
	v_and_b32_e32 v102, 0xffff0000, v46
	v_mov_b32_e32 v46, v18
	v_pk_mul_f32 v[18:19], v[20:21], v[70:71] op_sel_hi:[1,0]
	v_mul_f32_e32 v46, v70, v46
	v_mul_f32_e32 v47, v70, v47
	v_pk_fma_f32 v[18:19], v[72:73], v[18:19], v[102:103] op_sel_hi:[0,1,1] neg_lo:[1,0,0] neg_hi:[1,0,0]
	v_pk_fma_f32 v[46:47], v[72:73], v[46:47], v[48:49] op_sel_hi:[0,1,1] neg_lo:[1,0,0] neg_hi:[1,0,0]
	v_pk_mul_f32 v[20:21], v[18:19], v[18:19]
	s_nop 0
	v_pk_fma_f32 v[20:21], v[46:47], v[46:47], v[20:21]
	s_nop 0
	v_pk_add_f32 v[102:103], v[20:21], v[20:21] op_sel:[0,1] op_sel_hi:[1,0]
	global_load_dwordx2 v[20:21], v[94:95], off offset:208
	s_waitcnt vmcnt(0)
	v_lshlrev_b32_e32 v49, 16, v21
	v_lshlrev_b32_e32 v48, 16, v20
	v_and_b32_e32 v21, 0xffff0000, v21
	v_and_b32_e32 v20, 0xffff0000, v20
	v_pk_fma_f32 v[20:21], v[72:73], v[22:23], v[20:21] op_sel_hi:[0,1,1] neg_lo:[1,0,0] neg_hi:[1,0,0]
	v_pk_fma_f32 v[48:49], v[72:73], v[104:105], v[48:49] op_sel_hi:[0,1,1] neg_lo:[1,0,0] neg_hi:[1,0,0]
	v_pk_mul_f32 v[22:23], v[20:21], v[20:21]
	s_nop 0
	v_pk_fma_f32 v[22:23], v[48:49], v[48:49], v[22:23]
	s_nop 0
	v_pk_add_f32 v[104:105], v[22:23], v[22:23] op_sel:[0,1] op_sel_hi:[1,0]
	global_load_dwordx2 v[22:23], v[94:95], off offset:224
	s_waitcnt vmcnt(0)
	v_lshlrev_b32_e32 v25, 16, v23
	v_lshlrev_b32_e32 v24, 16, v22
	v_and_b32_e32 v23, 0xffff0000, v23
	v_and_b32_e32 v22, 0xffff0000, v22
	v_pk_fma_f32 v[22:23], v[72:73], v[26:27], v[22:23] op_sel_hi:[0,1,1] neg_lo:[1,0,0] neg_hi:[1,0,0]
	v_pk_fma_f32 v[24:25], v[72:73], v[106:107], v[24:25] op_sel_hi:[0,1,1] neg_lo:[1,0,0] neg_hi:[1,0,0]
	v_pk_mul_f32 v[26:27], v[22:23], v[22:23]
	s_nop 0
	v_pk_fma_f32 v[26:27], v[24:25], v[24:25], v[26:27]
	s_nop 0
	v_pk_add_f32 v[106:107], v[26:27], v[26:27] op_sel:[0,1] op_sel_hi:[1,0]
	global_load_dwordx2 v[26:27], v[94:95], off offset:240
	s_waitcnt vmcnt(0)
	v_lshlrev_b32_e32 v29, 16, v27
	v_lshlrev_b32_e32 v28, 16, v26
	v_and_b32_e32 v95, 0xffff0000, v27
	v_and_b32_e32 v94, 0xffff0000, v26
	v_mov_b32_e32 v26, v30
	v_mov_b32_e32 v27, v32
	v_mul_f32_e32 v26, v70, v26
	v_mul_f32_e32 v27, v70, v27
	v_mov_b32_e32 v32, v31
	v_pk_fma_f32 v[26:27], v[72:73], v[26:27], v[28:29] op_sel_hi:[0,1,1] neg_lo:[1,0,0] neg_hi:[1,0,0]
	v_pk_mul_f32 v[28:29], v[32:33], v[70:71] op_sel_hi:[1,0]
	v_sub_f32_e32 v71, 1.0, v73
	v_pk_fma_f32 v[28:29], v[72:73], v[28:29], v[94:95] op_sel_hi:[0,1,1] neg_lo:[1,0,0] neg_hi:[1,0,0]
	v_pk_mul_f32 v[30:31], v[28:29], v[28:29]
	v_mul_f32_e32 v4, v70, v4
	v_mul_f32_e32 v5, v70, v5
	v_pk_fma_f32 v[32:33], v[26:27], v[26:27], v[30:31]
	v_lshl_add_u64 v[30:31], s[2:3], 0, v[154:155]
	v_lshl_add_u64 v[30:31], v[30:31], 0, s[80:81]
	v_lshl_add_u64 v[30:31], v[30:31], 0, v[84:85]
	v_and_b32_e32 v85, 0xffff0000, v83
	v_lshlrev_b32_e32 v84, 16, v83
	v_and_b32_e32 v83, 0xffff0000, v82
	v_lshlrev_b32_e32 v82, 16, v82
	v_mul_f32_e32 v2, v70, v2
	v_mul_f32_e32 v3, v70, v3
	v_pk_fma_f32 v[84:85], v[72:73], v[4:5], v[84:85] op_sel_hi:[0,1,1] neg_lo:[1,0,0] neg_hi:[1,0,0]
	v_pk_fma_f32 v[82:83], v[72:73], v[2:3], v[82:83] op_sel_hi:[0,1,1] neg_lo:[1,0,0] neg_hi:[1,0,0]
	v_mul_f32_e32 v4, v85, v85
	v_mul_f32_e32 v2, v83, v83
	v_pk_fma_f32 v[4:5], v[84:85], v[84:85], v[4:5] op_sel_hi:[1,1,0]
	v_pk_fma_f32 v[2:3], v[82:83], v[82:83], v[2:3] op_sel_hi:[1,1,0]
	v_mul_f32_e32 v8, v70, v8
	v_mul_f32_e32 v9, v70, v9
	v_pk_add_f32 v[2:3], v[2:3], v[4:5]
	v_and_b32_e32 v5, 0xffff0000, v81
	v_lshlrev_b32_e32 v4, 16, v81
	v_and_b32_e32 v81, 0xffff0000, v80
	v_lshlrev_b32_e32 v80, 16, v80
	v_mul_f32_e32 v6, v70, v6
	v_mul_f32_e32 v7, v70, v7
	v_pk_fma_f32 v[8:9], v[72:73], v[8:9], v[4:5] op_sel_hi:[0,1,1] neg_lo:[1,0,0] neg_hi:[1,0,0]
	v_pk_fma_f32 v[80:81], v[72:73], v[6:7], v[80:81] op_sel_hi:[0,1,1] neg_lo:[1,0,0] neg_hi:[1,0,0]
	v_mul_f32_e32 v4, v9, v9
	v_mul_f32_e32 v6, v81, v81
	v_pk_fma_f32 v[4:5], v[8:9], v[8:9], v[4:5] op_sel_hi:[1,1,0]
	v_pk_fma_f32 v[6:7], v[80:81], v[80:81], v[6:7] op_sel_hi:[1,1,0]
	v_mul_f32_e32 v10, v70, v10
	v_mul_f32_e32 v11, v70, v11
	v_pk_add_f32 v[4:5], v[6:7], v[4:5]
	v_pk_mul_f32 v[6:7], v[12:13], v[70:71] op_sel_hi:[1,0]
	v_pk_add_f32 v[2:3], v[2:3], v[4:5]
	v_and_b32_e32 v5, 0xffff0000, v77
	v_lshlrev_b32_e32 v4, 16, v77
	v_pk_fma_f32 v[12:13], v[72:73], v[6:7], v[4:5] op_sel_hi:[0,1,1] neg_lo:[1,0,0] neg_hi:[1,0,0]
	v_and_b32_e32 v7, 0xffff0000, v76
	v_lshlrev_b32_e32 v6, 16, v76
	v_pk_fma_f32 v[10:11], v[72:73], v[10:11], v[6:7] op_sel_hi:[0,1,1] neg_lo:[1,0,0] neg_hi:[1,0,0]
	v_mul_f32_e32 v4, v13, v13
	v_mul_f32_e32 v6, v11, v11
	v_pk_fma_f32 v[4:5], v[12:13], v[12:13], v[4:5] op_sel_hi:[1,1,0]
	v_pk_fma_f32 v[6:7], v[10:11], v[10:11], v[6:7] op_sel_hi:[1,1,0]
	v_mul_f32_e32 v14, v70, v14
	v_mul_f32_e32 v15, v70, v15
	v_pk_add_f32 v[4:5], v[6:7], v[4:5]
	v_pk_mul_f32 v[6:7], v[16:17], v[70:71] op_sel_hi:[1,0]
	v_pk_add_f32 v[2:3], v[2:3], v[4:5]
	v_and_b32_e32 v5, 0xffff0000, v75
	v_lshlrev_b32_e32 v4, 16, v75
	v_pk_fma_f32 v[16:17], v[72:73], v[6:7], v[4:5] op_sel_hi:[0,1,1] neg_lo:[1,0,0] neg_hi:[1,0,0]
	v_and_b32_e32 v7, 0xffff0000, v74
	v_lshlrev_b32_e32 v6, 16, v74
	v_pk_fma_f32 v[14:15], v[72:73], v[14:15], v[6:7] op_sel_hi:[0,1,1] neg_lo:[1,0,0] neg_hi:[1,0,0]
	v_mul_f32_e32 v4, v17, v17
	v_mul_f32_e32 v6, v15, v15
	v_pk_fma_f32 v[4:5], v[16:17], v[16:17], v[4:5] op_sel_hi:[1,1,0]
	v_pk_fma_f32 v[6:7], v[14:15], v[14:15], v[6:7] op_sel_hi:[1,1,0]
	v_mov_b32_e32 v107, v33
	v_pk_add_f32 v[4:5], v[6:7], v[4:5]
	s_nop 0
	v_pk_add_f32 v[2:3], v[2:3], v[4:5]
	s_nop 0
	v_pk_add_f32 v[2:3], v[2:3], v[78:79]
	s_nop 0
	v_pk_add_f32 v[2:3], v[2:3], v[86:87]
	s_nop 0
	v_pk_add_f32 v[2:3], v[2:3], v[88:89]
	s_nop 0
	v_pk_add_f32 v[2:3], v[2:3], v[90:91]
	s_nop 0
	v_pk_add_f32 v[2:3], v[2:3], v[92:93]
	s_nop 0
	v_pk_add_f32 v[2:3], v[2:3], v[96:97]
	s_nop 0
	v_pk_add_f32 v[2:3], v[2:3], v[98:99]
	s_nop 0
	v_pk_add_f32 v[2:3], v[2:3], v[100:101]
	s_nop 0
	v_pk_add_f32 v[2:3], v[2:3], v[102:103]
	s_nop 0
	v_pk_add_f32 v[2:3], v[2:3], v[104:105]
	s_nop 0
	v_mov_b32_e32 v3, v32
	v_pk_add_f32 v[2:3], v[2:3], v[106:107]
	s_nop 0
	v_add_f32_e32 v2, v2, v3
	v_mov_b32_e32 v3, v2
	v_nop
	v_nop
	v_permlane32_swap_b32 v3, v2
	global_load_dwordx4 v[4:7], v0, s[6:7]
	v_add_f32_e32 v2, v3, v2
	v_fmamk_f32 v2, v2, 0x3c000000, v252
	v_cmp_gt_f32_e32 vcc, s67, v2
	v_mul_f32_e32 v3, 0x4b800000, v2
	s_nop 0
	v_cndmask_b32_e32 v2, v2, v3, vcc
	v_rsq_f32_e32 v2, v2
	s_nop 0
	v_mul_f32_e32 v3, 0x45800000, v2
	v_cndmask_b32_e32 v2, v2, v3, vcc
	v_mul_f32_e32 v2, v71, v2
	v_pk_mul_f32 v[32:33], v[82:83], v[2:3] op_sel_hi:[1,0]
	v_mul_f32_e32 v8, v2, v8
	v_mul_f32_e32 v9, v2, v9
	s_waitcnt vmcnt(0)
	v_pk_mul_f32 v[4:5], v[4:5], v[32:33]
	v_pk_mul_f32 v[32:33], v[84:85], v[2:3] op_sel_hi:[1,0]
	v_cvt_pk_bf16_f32 v4, v4, v5
	v_pk_mul_f32 v[6:7], v[6:7], v[32:33]
	v_pk_mul_f32 v[32:33], v[80:81], v[2:3] op_sel_hi:[1,0]
	v_cvt_pk_bf16_f32 v5, v6, v7
	global_store_dwordx2 v[30:31], v[4:5], off
	global_load_dwordx4 v[4:7], v0, s[6:7] offset:32
	s_waitcnt vmcnt(0)
	v_pk_mul_f32 v[4:5], v[4:5], v[32:33]
	v_pk_mul_f32 v[6:7], v[6:7], v[8:9]
	v_cvt_pk_bf16_f32 v4, v4, v5
	v_cvt_pk_bf16_f32 v5, v6, v7
	global_store_dwordx2 v[30:31], v[4:5], off offset:16
	global_load_dwordx4 v[4:7], v0, s[6:7] offset:64
	v_pk_mul_f32 v[8:9], v[10:11], v[2:3] op_sel_hi:[1,0]
	s_waitcnt vmcnt(0)
	v_pk_mul_f32 v[4:5], v[4:5], v[8:9]
	v_pk_mul_f32 v[8:9], v[12:13], v[2:3] op_sel_hi:[1,0]
	v_cvt_pk_bf16_f32 v4, v4, v5
	v_pk_mul_f32 v[6:7], v[6:7], v[8:9]
	v_pk_mul_f32 v[8:9], v[14:15], v[2:3] op_sel_hi:[1,0]
	v_cvt_pk_bf16_f32 v5, v6, v7
	global_store_dwordx2 v[30:31], v[4:5], off offset:32
	global_load_dwordx4 v[4:7], v0, s[6:7] offset:96
	s_waitcnt vmcnt(0)
	v_pk_mul_f32 v[4:5], v[4:5], v[8:9]
	v_pk_mul_f32 v[8:9], v[16:17], v[2:3] op_sel_hi:[1,0]
	v_cvt_pk_bf16_f32 v4, v4, v5
	v_pk_mul_f32 v[6:7], v[6:7], v[8:9]
	v_mov_b32_e32 v8, v66
	v_cvt_pk_bf16_f32 v5, v6, v7
	global_store_dwordx2 v[30:31], v[4:5], off offset:48
	global_load_dwordx4 v[4:7], v0, s[6:7] offset:128
	v_mov_b32_e32 v9, v50
	v_mul_f32_e32 v8, v2, v8
	v_mul_f32_e32 v9, v2, v9
	v_mov_b32_e32 v50, v67
	s_waitcnt vmcnt(0)
	v_pk_mul_f32 v[4:5], v[4:5], v[8:9]
	v_pk_mul_f32 v[8:9], v[50:51], v[2:3] op_sel_hi:[1,0]
	v_cvt_pk_bf16_f32 v4, v4, v5
	v_pk_mul_f32 v[6:7], v[6:7], v[8:9]
	v_mov_b32_e32 v8, v68
	v_cvt_pk_bf16_f32 v5, v6, v7
	global_store_dwordx2 v[30:31], v[4:5], off offset:64
	global_load_dwordx4 v[4:7], v0, s[6:7] offset:160
	v_mov_b32_e32 v9, v52
	v_mul_f32_e32 v8, v2, v8
	v_mul_f32_e32 v9, v2, v9
	v_mov_b32_e32 v52, v69
	s_waitcnt vmcnt(0)
	v_pk_mul_f32 v[4:5], v[8:9], v[4:5]
	v_pk_mul_f32 v[8:9], v[52:53], v[2:3] op_sel_hi:[1,0]
	v_cvt_pk_bf16_f32 v4, v4, v5
	v_pk_mul_f32 v[6:7], v[8:9], v[6:7]
	v_mov_b32_e32 v8, v56
	v_cvt_pk_bf16_f32 v5, v6, v7
	global_store_dwordx2 v[30:31], v[4:5], off offset:80
	global_load_dwordx4 v[4:7], v0, s[6:7] offset:192
	v_mov_b32_e32 v9, v54
	v_mul_f32_e32 v8, v2, v8
	v_mul_f32_e32 v9, v2, v9
	v_mov_b32_e32 v54, v57
	s_waitcnt vmcnt(0)
	v_pk_mul_f32 v[4:5], v[8:9], v[4:5]
	v_pk_mul_f32 v[8:9], v[54:55], v[2:3] op_sel_hi:[1,0]
	v_cvt_pk_bf16_f32 v4, v4, v5
	v_pk_mul_f32 v[6:7], v[8:9], v[6:7]
	v_mov_b32_e32 v8, v60
	v_cvt_pk_bf16_f32 v5, v6, v7
	global_store_dwordx2 v[30:31], v[4:5], off offset:96
	global_load_dwordx4 v[4:7], v0, s[6:7] offset:224
	v_mov_b32_e32 v9, v58
	v_mul_f32_e32 v8, v2, v8
	v_mul_f32_e32 v9, v2, v9
	v_mov_b32_e32 v58, v61
	s_waitcnt vmcnt(0)
	v_pk_mul_f32 v[4:5], v[8:9], v[4:5]
	v_pk_mul_f32 v[8:9], v[58:59], v[2:3] op_sel_hi:[1,0]
	v_cvt_pk_bf16_f32 v4, v4, v5
	v_pk_mul_f32 v[6:7], v[8:9], v[6:7]
	v_mov_b32_e32 v8, v62
	v_cvt_pk_bf16_f32 v5, v6, v7
	global_store_dwordx2 v[30:31], v[4:5], off offset:112
	global_load_dwordx4 v[4:7], v0, s[6:7] offset:256
	v_mov_b32_e32 v9, v34
	v_mul_f32_e32 v8, v2, v8
	v_mul_f32_e32 v9, v2, v9
	v_mov_b32_e32 v34, v63
	s_waitcnt vmcnt(0)
	v_pk_mul_f32 v[4:5], v[8:9], v[4:5]
	v_pk_mul_f32 v[8:9], v[34:35], v[2:3] op_sel_hi:[1,0]
	v_cvt_pk_bf16_f32 v4, v4, v5
	v_pk_mul_f32 v[6:7], v[8:9], v[6:7]
	v_mov_b32_e32 v8, v64
	v_cvt_pk_bf16_f32 v5, v6, v7
	global_store_dwordx2 v[30:31], v[4:5], off offset:128
	global_load_dwordx4 v[4:7], v0, s[6:7] offset:288
	v_mov_b32_e32 v9, v36
	v_mul_f32_e32 v8, v2, v8
	v_mul_f32_e32 v9, v2, v9
	v_mov_b32_e32 v36, v65
	s_waitcnt vmcnt(0)
	v_pk_mul_f32 v[4:5], v[8:9], v[4:5]
	v_pk_mul_f32 v[8:9], v[36:37], v[2:3] op_sel_hi:[1,0]
	v_cvt_pk_bf16_f32 v4, v4, v5
	v_pk_mul_f32 v[6:7], v[8:9], v[6:7]
	v_mov_b32_e32 v8, v40
	v_cvt_pk_bf16_f32 v5, v6, v7
	global_store_dwordx2 v[30:31], v[4:5], off offset:144
	global_load_dwordx4 v[4:7], v0, s[6:7] offset:320
	v_mov_b32_e32 v9, v38
	v_mul_f32_e32 v8, v2, v8
	v_mul_f32_e32 v9, v2, v9
	v_mov_b32_e32 v38, v41
	s_waitcnt vmcnt(0)
	v_pk_mul_f32 v[4:5], v[8:9], v[4:5]
	v_pk_mul_f32 v[8:9], v[38:39], v[2:3] op_sel_hi:[1,0]
	v_cvt_pk_bf16_f32 v4, v4, v5
	v_pk_mul_f32 v[6:7], v[8:9], v[6:7]
	v_mov_b32_e32 v8, v44
	v_cvt_pk_bf16_f32 v5, v6, v7
	global_store_dwordx2 v[30:31], v[4:5], off offset:160
	global_load_dwordx4 v[4:7], v0, s[6:7] offset:352
	v_mov_b32_e32 v9, v42
	v_mul_f32_e32 v8, v2, v8
	v_mul_f32_e32 v9, v2, v9
	v_mov_b32_e32 v42, v45
	s_waitcnt vmcnt(0)
	v_pk_mul_f32 v[4:5], v[8:9], v[4:5]
	v_pk_mul_f32 v[8:9], v[42:43], v[2:3] op_sel_hi:[1,0]
	v_cvt_pk_bf16_f32 v4, v4, v5
	v_pk_mul_f32 v[6:7], v[8:9], v[6:7]
	v_mov_b32_e32 v8, v46
	v_cvt_pk_bf16_f32 v5, v6, v7
	global_store_dwordx2 v[30:31], v[4:5], off offset:176
	global_load_dwordx4 v[4:7], v0, s[6:7] offset:384
	v_mov_b32_e32 v9, v18
	v_mul_f32_e32 v8, v2, v8
	v_mul_f32_e32 v9, v2, v9
	v_mov_b32_e32 v18, v47
	s_waitcnt vmcnt(0)
	v_pk_mul_f32 v[4:5], v[8:9], v[4:5]
	v_pk_mul_f32 v[8:9], v[18:19], v[2:3] op_sel_hi:[1,0]
	v_cvt_pk_bf16_f32 v4, v4, v5
	v_pk_mul_f32 v[6:7], v[8:9], v[6:7]
	v_mov_b32_e32 v8, v48
	v_cvt_pk_bf16_f32 v5, v6, v7
	global_store_dwordx2 v[30:31], v[4:5], off offset:192
	global_load_dwordx4 v[4:7], v0, s[6:7] offset:416
	v_mov_b32_e32 v9, v20
	v_mul_f32_e32 v8, v2, v8
	v_mul_f32_e32 v9, v2, v9
	v_mov_b32_e32 v20, v49
	s_waitcnt vmcnt(0)
	v_pk_mul_f32 v[4:5], v[8:9], v[4:5]
	v_pk_mul_f32 v[8:9], v[20:21], v[2:3] op_sel_hi:[1,0]
	v_cvt_pk_bf16_f32 v4, v4, v5
	v_pk_mul_f32 v[6:7], v[8:9], v[6:7]
	v_mov_b32_e32 v8, v24
	v_cvt_pk_bf16_f32 v5, v6, v7
	global_store_dwordx2 v[30:31], v[4:5], off offset:208
	global_load_dwordx4 v[4:7], v0, s[6:7] offset:448
	v_mov_b32_e32 v9, v22
	v_mul_f32_e32 v8, v2, v8
	v_mul_f32_e32 v9, v2, v9
	v_mov_b32_e32 v22, v25
	s_waitcnt vmcnt(0)
	v_pk_mul_f32 v[4:5], v[8:9], v[4:5]
	v_pk_mul_f32 v[8:9], v[22:23], v[2:3] op_sel_hi:[1,0]
	v_cvt_pk_bf16_f32 v4, v4, v5
	v_pk_mul_f32 v[6:7], v[8:9], v[6:7]
	v_mov_b32_e32 v8, v26
	v_cvt_pk_bf16_f32 v5, v6, v7
	global_store_dwordx2 v[30:31], v[4:5], off offset:224
	global_load_dwordx4 v[4:7], v0, s[6:7] offset:480
	v_mov_b32_e32 v9, v28
	v_mov_b32_e32 v28, v27
	v_mul_f32_e32 v8, v2, v8
	v_mul_f32_e32 v9, v2, v9
	v_pk_mul_f32 v[2:3], v[28:29], v[2:3] op_sel_hi:[1,0]
	s_waitcnt vmcnt(0)
	v_pk_mul_f32 v[4:5], v[8:9], v[4:5]
	v_pk_mul_f32 v[2:3], v[2:3], v[6:7]
	v_cvt_pk_bf16_f32 v4, v4, v5
	v_cvt_pk_bf16_f32 v5, v2, v3
	global_store_dwordx2 v[30:31], v[4:5], off offset:240
	s_cbranch_scc1 .LBB0_171
.LBB0_159:
	v_mov_b32_e32 v7, v197
	s_and_b32 s2, s4, 0xffffff00
	s_and_b32 s21, s0, 0x380
	v_and_b32_e32 v6, 31, v7
	v_ashrrev_i32_e32 v0, 1, v7
	v_and_b32_e32 v0, 0xffffffe0, v0
	v_or_b32_e32 v2, s2, v6
	v_add_u32_e32 v154, v2, v0
	v_ashrrev_i32_e32 v155, 31, v154
	v_lshlrev_b64 v[2:3], 11, v[154:155]
	v_bfe_u32 v156, v7, 5, 1
	v_lshl_add_u64 v[2:3], s[48:49], 0, v[2:3]
	s_lshl_b32 s80, s21, 1
	v_lshl_add_u64 v[2:3], v[2:3], 0, s[80:81]
	v_lshlrev_b32_e32 v0, 4, v156
	v_lshl_add_u64 v[16:17], v[2:3], 0, v[0:1]
	global_load_dwordx4 v[2:5], v[16:17], off
	global_load_dwordx4 v[8:11], v[16:17], off offset:32
	global_load_dwordx4 v[12:15], v[16:17], off offset:64
	s_nop 0
	global_load_dwordx4 v[16:19], v[16:17], off offset:96
	s_mov_b32 s28, 0x3e38aa3b
	s_ashr_i32 s3, s2, 31
	s_waitcnt vmcnt(3)
	v_and_b32_e32 v21, 0xffff0000, v2
	v_lshlrev_b32_e32 v20, 16, v2
	v_pk_mul_f32 v[20:21], v[20:21], s[28:29] op_sel_hi:[1,0]
	s_nop 0
	v_cvt_pk_bf16_f32 v130, v20, v21
	v_and_b32_e32 v21, 0xffff0000, v3
	v_lshlrev_b32_e32 v20, 16, v3
	v_pk_mul_f32 v[2:3], v[20:21], s[28:29] op_sel_hi:[1,0]
	s_nop 0
	v_cvt_pk_bf16_f32 v131, v2, v3
	v_and_b32_e32 v3, 0xffff0000, v4
	v_lshlrev_b32_e32 v2, 16, v4
	v_pk_mul_f32 v[2:3], v[2:3], s[28:29] op_sel_hi:[1,0]
	s_nop 0
	v_cvt_pk_bf16_f32 v132, v2, v3
	v_and_b32_e32 v3, 0xffff0000, v5
	v_lshlrev_b32_e32 v2, 16, v5
	v_pk_mul_f32 v[2:3], v[2:3], s[28:29] op_sel_hi:[1,0]
	v_ashrrev_i32_e32 v5, 3, v7
	v_cvt_pk_bf16_f32 v133, v2, v3
	s_waitcnt vmcnt(2)
	v_and_b32_e32 v3, 0xffff0000, v8
	v_lshlrev_b32_e32 v2, 16, v8
	v_pk_mul_f32 v[2:3], v[2:3], s[28:29] op_sel_hi:[1,0]
	s_nop 0
	v_cvt_pk_bf16_f32 v134, v2, v3
	v_and_b32_e32 v3, 0xffff0000, v9
	v_lshlrev_b32_e32 v2, 16, v9
	v_pk_mul_f32 v[2:3], v[2:3], s[28:29] op_sel_hi:[1,0]
	v_and_b32_e32 v9, 15, v7
	v_cvt_pk_bf16_f32 v135, v2, v3
	v_and_b32_e32 v3, 0xffff0000, v10
	v_lshlrev_b32_e32 v2, 16, v10
	v_pk_mul_f32 v[2:3], v[2:3], s[28:29] op_sel_hi:[1,0]
	v_ashrrev_i32_e32 v10, 4, v7
	v_cvt_pk_bf16_f32 v136, v2, v3
	v_and_b32_e32 v3, 0xffff0000, v11
	v_lshlrev_b32_e32 v2, 16, v11
	v_pk_mul_f32 v[2:3], v[2:3], s[28:29] op_sel_hi:[1,0]
	v_lshlrev_b32_e32 v11, 4, v7
	v_cvt_pk_bf16_f32 v137, v2, v3
	s_waitcnt vmcnt(1)
	v_and_b32_e32 v3, 0xffff0000, v12
	v_lshlrev_b32_e32 v2, 16, v12
	v_pk_mul_f32 v[2:3], v[2:3], s[28:29] op_sel_hi:[1,0]
	v_and_b32_e32 v4, 0x70, v11
	v_cvt_pk_bf16_f32 v138, v2, v3
	v_and_b32_e32 v3, 0xffff0000, v13
	v_lshlrev_b32_e32 v2, 16, v13
	v_pk_mul_f32 v[2:3], v[2:3], s[28:29] op_sel_hi:[1,0]
	v_add_u32_e32 v8, s21, v10
	v_cvt_pk_bf16_f32 v139, v2, v3
	v_and_b32_e32 v3, 0xffff0000, v14
	v_lshlrev_b32_e32 v2, 16, v14
	v_pk_mul_f32 v[2:3], v[2:3], s[28:29] op_sel_hi:[1,0]
	v_mul_lo_u32 v40, v10, s43
	v_cvt_pk_bf16_f32 v140, v2, v3
	v_and_b32_e32 v3, 0xffff0000, v15
	v_lshlrev_b32_e32 v2, 16, v15
	v_pk_mul_f32 v[2:3], v[2:3], s[28:29] op_sel_hi:[1,0]
	s_nop 0
	v_cvt_pk_bf16_f32 v141, v2, v3
	s_waitcnt vmcnt(0)
	v_and_b32_e32 v3, 0xffff0000, v16
	v_lshlrev_b32_e32 v2, 16, v16
	v_pk_mul_f32 v[2:3], v[2:3], s[28:29] op_sel_hi:[1,0]
	s_nop 0
	v_cvt_pk_bf16_f32 v142, v2, v3
	v_and_b32_e32 v3, 0xffff0000, v17
	v_lshlrev_b32_e32 v2, 16, v17
	v_pk_mul_f32 v[2:3], v[2:3], s[28:29] op_sel_hi:[1,0]
	s_nop 0
	v_cvt_pk_bf16_f32 v143, v2, v3
	v_and_b32_e32 v3, 0xffff0000, v18
	v_lshlrev_b32_e32 v2, 16, v18
	v_pk_mul_f32 v[2:3], v[2:3], s[28:29] op_sel_hi:[1,0]
	s_nop 0
	v_cvt_pk_bf16_f32 v144, v2, v3
	v_and_b32_e32 v3, 0xffff0000, v19
	v_lshlrev_b32_e32 v2, 16, v19
	v_pk_mul_f32 v[2:3], v[2:3], s[28:29] op_sel_hi:[1,0]
	v_mad_u64_u32 v[32:33], s[28:29], v5, s42, v[4:5]
	v_cvt_pk_bf16_f32 v145, v2, v3
	v_add_u32_e32 v2, s2, v5
	v_ashrrev_i32_e32 v3, 31, v2
	v_lshlrev_b64 v[2:3], 11, v[2:3]
	v_lshl_add_u64 v[2:3], s[8:9], 0, v[2:3]
	v_lshlrev_b32_e32 v5, 3, v7
	v_and_b32_e32 v7, 8, v5
	v_lshl_add_u64 v[2:3], v[2:3], 0, s[80:81]
	v_mov_b32_e32 v5, v1
	v_lshl_add_u64 v[2:3], v[2:3], 0, v[4:5]
	v_mov_b64_e32 v[4:5], s[10:11]
	v_mad_i64_i32 v[4:5], s[28:29], v8, s68, v[4:5]
	s_mov_b32 s28, 0x20000
	v_lshl_add_u64 v[4:5], s[2:3], 1, v[4:5]
	v_lshlrev_b32_e32 v8, 4, v9
	v_mov_b32_e32 v9, v1
	v_add_co_u32_e32 v12, vcc, s28, v2
	v_lshl_add_u64 v[4:5], v[4:5], 0, v[8:9]
	s_nop 0
	v_addc_co_u32_e32 v13, vcc, 0, v3, vcc
	v_add_co_u32_e32 v34, vcc, s41, v4
	s_mov_b32 s28, 0x220000
	s_nop 0
	v_addc_co_u32_e32 v35, vcc, 0, v5, vcc
	v_and_b32_e32 v33, 0xe0, v11
	global_load_dwordx4 v[8:11], v[2:3], off
	v_add_co_u32_e32 v36, vcc, s28, v4
	global_load_dwordx4 v[12:15], v[12:13], off
	s_nop 0
	global_load_dwordx4 v[16:19], v[4:5], off
	v_addc_co_u32_e32 v37, vcc, 0, v5, vcc
	s_mov_b32 s28, 0x330000
	v_add_co_u32_e32 v38, vcc, s28, v4
	global_load_dwordx4 v[20:23], v[34:35], off
	global_load_dwordx4 v[24:27], v[36:37], off
	v_addc_co_u32_e32 v39, vcc, 0, v5, vcc
	global_load_dwordx4 v[28:31], v[38:39], off
	v_add_u32_e32 v190, 0, v32
	s_waitcnt vmcnt(5)
	ds_write_b128 v190, v[8:11]
	s_waitcnt vmcnt(4)
	ds_write_b128 v190, v[12:15] offset:9216
	v_add_u32_e32 v8, 0, v33
	v_add3_u32 v7, v8, v7, v40
	v_add_u32_e32 v8, 0xb000, v7
	v_add_u32_e32 v193, 0x9000, v7
	s_mov_b32 s28, 0x40000
	s_waitcnt vmcnt(3)
	ds_write2_b64 v193, v[16:17], v[18:19] offset1:2
	s_waitcnt vmcnt(2)
	ds_write2_b64 v8, v[20:21], v[22:23] offset0:64 offset1:66
	v_add_u32_e32 v8, 0xd000, v7
	v_add_u32_e32 v7, 0xf000, v7
	s_waitcnt vmcnt(1)
	ds_write2_b64 v8, v[24:25], v[26:27] offset0:128 offset1:130
	s_waitcnt vmcnt(0)
	ds_write2_b64 v7, v[28:29], v[30:31] offset0:192 offset1:194
	v_mad_u32_u24 v7, v6, s42, 0
	v_add_u32_e32 v192, v7, v0
	v_lshl_add_u32 v194, v6, 7, v192
	v_add_co_u32_e32 v6, vcc, s28, v2
	s_mov_b32 s28, 0x60000
	s_nop 0
	v_addc_co_u32_e32 v7, vcc, 0, v3, vcc
	v_add_co_u32_e32 v2, vcc, s28, v2
	s_waitcnt lgkmcnt(0)
	s_nop 0
	v_addc_co_u32_e32 v3, vcc, 0, v3, vcc
	s_barrier
	global_load_dwordx4 v[98:101], v[6:7], off
	global_load_dwordx4 v[118:121], v[2:3], off
	global_load_dwordx4 v[114:117], v[4:5], off offset:256
	global_load_dwordx4 v[110:113], v[34:35], off offset:256
	global_load_dwordx4 v[106:109], v[36:37], off offset:256
	global_load_dwordx4 v[102:105], v[38:39], off offset:256
	ds_read_b128 v[2:5], v192 offset:4608
	ds_read_b128 v[6:9], v192
	ds_read_b128 v[34:37], v192 offset:32
	ds_read_b128 v[38:41], v192 offset:4640
	ds_read_b128 v[42:45], v192 offset:64
	ds_read_b128 v[46:49], v192 offset:4672
	ds_read_b128 v[50:53], v192 offset:96
	ds_read_b128 v[54:57], v192 offset:4704
	s_waitcnt lgkmcnt(6)
	v_mfma_f32_32x32x16_bf16 v[18:33], v[6:9], v[130:133], 0
	v_mfma_f32_32x32x16_bf16 v[2:17], v[2:5], v[130:133], 0
	s_waitcnt lgkmcnt(5)
	v_mfma_f32_32x32x16_bf16 v[18:33], v[34:37], v[134:137], v[18:33]
	s_waitcnt lgkmcnt(4)
	v_mfma_f32_32x32x16_bf16 v[2:17], v[38:41], v[134:137], v[2:17]
	s_waitcnt lgkmcnt(3)
	v_mfma_f32_32x32x16_bf16 v[18:33], v[42:45], v[138:141], v[18:33]
	s_waitcnt lgkmcnt(2)
	v_mfma_f32_32x32x16_bf16 v[2:17], v[46:49], v[138:141], v[2:17]
	s_waitcnt lgkmcnt(1)
	v_mfma_f32_32x32x16_bf16 v[18:33], v[50:53], v[142:145], v[18:33]
	s_waitcnt lgkmcnt(0)
	v_mfma_f32_32x32x16_bf16 v[2:17], v[54:57], v[142:145], v[2:17]
	ds_read_b128 v[34:37], v192 offset:9216
	ds_read_b128 v[38:41], v192 offset:9248
	ds_read_b128 v[42:45], v192 offset:13824
	ds_read_b128 v[46:49], v192 offset:13856
	ds_read_b128 v[50:53], v192 offset:9280
	ds_read_b128 v[54:57], v192 offset:9312
	ds_read_b128 v[58:61], v192 offset:13888
	ds_read_b128 v[62:65], v192 offset:13920
	s_waitcnt lgkmcnt(7)
	v_mfma_f32_32x32x16_bf16 v[82:97], v[34:37], v[130:133], 0
	s_waitcnt lgkmcnt(5)
	v_mfma_f32_32x32x16_bf16 v[66:81], v[42:45], v[130:133], 0
	v_mfma_f32_32x32x16_bf16 v[82:97], v[38:41], v[134:137], v[82:97]
	s_waitcnt lgkmcnt(4)
	v_mfma_f32_32x32x16_bf16 v[66:81], v[46:49], v[134:137], v[66:81]
	s_waitcnt lgkmcnt(3)
	v_mfma_f32_32x32x16_bf16 v[82:97], v[50:53], v[138:141], v[82:97]
	s_waitcnt lgkmcnt(1)
	v_mfma_f32_32x32x16_bf16 v[66:81], v[58:61], v[138:141], v[66:81]
	v_mfma_f32_32x32x16_bf16 v[82:97], v[54:57], v[142:145], v[82:97]
	s_waitcnt lgkmcnt(0)
	v_mfma_f32_32x32x16_bf16 v[66:81], v[62:65], v[142:145], v[66:81]
	ds_read_b128 v[34:37], v194 offset:36864
	ds_read_b128 v[38:41], v194 offset:36896
	ds_read_b128 v[42:45], v194 offset:36928
	ds_read_b128 v[46:49], v194 offset:36960
	v_max3_f32 v0, v18, v2, v19
	v_max_f32_e32 v50, v17, v17
	v_max3_f32 v0, v0, v3, v20
	s_mov_b32 s28, 0xf149f2ca
	v_max3_f32 v0, v0, v4, v21
	v_max3_f32 v0, v0, v5, v22
	v_max3_f32 v0, v0, v6, v23
	v_max3_f32 v0, v0, v7, v24
	v_max3_f32 v0, v0, v8, v25
	v_max3_f32 v0, v0, v9, v26
	v_max3_f32 v0, v0, v10, v27
	v_max3_f32 v0, v0, v11, v28
	v_max3_f32 v0, v0, v12, v29
	v_max3_f32 v0, v0, v13, v30
	v_max3_f32 v0, v0, v14, v31
	v_max3_f32 v0, v0, v15, v32
	v_max3_f32 v0, v0, v16, v33
	s_nop 0
	v_max_f32_e32 v0, v0, v0
	v_max_f32_e32 v0, v0, v50
	v_mov_b32_e32 v50, v0
	v_nop
	v_nop
	v_permlane32_swap_b32 v50, v0
	s_nop 0
	v_max3_f32 v0, v50, v0, s28
	v_sub_f32_e32 v2, v2, v0
	v_exp_f32_e32 v158, v2
	v_sub_f32_e32 v2, v19, v0
	v_exp_f32_e32 v159, v2
	v_sub_f32_e32 v2, v3, v0
	v_exp_f32_e32 v160, v2
	v_sub_f32_e32 v2, v20, v0
	v_exp_f32_e32 v161, v2
	v_sub_f32_e32 v2, v4, v0
	v_exp_f32_e32 v162, v2
	v_sub_f32_e32 v2, v21, v0
	v_exp_f32_e32 v163, v2
	v_sub_f32_e32 v2, v5, v0
	v_exp_f32_e32 v164, v2
	v_sub_f32_e32 v2, v22, v0
	v_exp_f32_e32 v165, v2
	v_sub_f32_e32 v2, v6, v0
	v_exp_f32_e32 v166, v2
	v_sub_f32_e32 v2, v23, v0
	v_exp_f32_e32 v167, v2
	v_sub_f32_e32 v2, v7, v0
	v_exp_f32_e32 v168, v2
	v_sub_f32_e32 v2, v24, v0
	v_exp_f32_e32 v169, v2
	v_sub_f32_e32 v2, v8, v0
	v_exp_f32_e32 v170, v2
	v_sub_f32_e32 v2, v25, v0
	v_exp_f32_e32 v171, v2
	v_sub_f32_e32 v2, v9, v0
	v_exp_f32_e32 v172, v2
	v_sub_f32_e32 v2, v26, v0
	v_exp_f32_e32 v173, v2
	v_sub_f32_e32 v2, v10, v0
	v_exp_f32_e32 v174, v2
	v_sub_f32_e32 v2, v27, v0
	v_exp_f32_e32 v175, v2
	v_sub_f32_e32 v2, v11, v0
	v_exp_f32_e32 v176, v2
	v_sub_f32_e32 v2, v28, v0
	v_exp_f32_e32 v177, v2
	v_sub_f32_e32 v2, v12, v0
	v_exp_f32_e32 v178, v2
	v_sub_f32_e32 v2, v29, v0
	v_exp_f32_e32 v179, v2
	v_sub_f32_e32 v2, v13, v0
	v_exp_f32_e32 v180, v2
	v_sub_f32_e32 v2, v30, v0
	v_exp_f32_e32 v181, v2
	v_sub_f32_e32 v2, v14, v0
	v_exp_f32_e32 v182, v2
	v_sub_f32_e32 v2, v31, v0
	v_sub_f32_e32 v50, 0xf149f2ca, v0
	v_exp_f32_e32 v183, v2
	v_sub_f32_e32 v2, v15, v0
	v_exp_f32_e32 v184, v2
	v_sub_f32_e32 v2, v32, v0
	v_exp_f32_e32 v3, v50
	v_exp_f32_e32 v185, v2
	v_sub_f32_e32 v2, v16, v0
	v_exp_f32_e32 v186, v2
	v_sub_f32_e32 v2, v33, v0
	v_sub_f32_e32 v18, v18, v0
	v_exp_f32_e32 v187, v2
	v_sub_f32_e32 v2, v17, v0
	v_exp_f32_e32 v157, v18
	v_exp_f32_e32 v189, v2
	v_cmp_neq_f32_e32 vcc, 1.0, v3
	s_cmp_lg_u64 vcc, 0
	v_mul_f32_e32 v188, 0, v3
	s_cselect_b64 vcc, -1, 0
	v_cndmask_b32_e32 v2, 0, v188, vcc
	v_mov_b32_e32 v3, v2
	v_mov_b32_e32 v4, v2
	v_mov_b32_e32 v5, v2
	v_mov_b32_e32 v6, v2
	v_mov_b32_e32 v7, v2
	v_mov_b32_e32 v8, v2
	v_mov_b32_e32 v9, v2
	v_mov_b32_e32 v10, v2
	v_mov_b32_e32 v11, v2
	v_mov_b32_e32 v12, v2
	v_mov_b32_e32 v13, v2
	v_mov_b32_e32 v14, v2
	v_mov_b32_e32 v15, v2
	v_mov_b32_e32 v16, v2
	v_mov_b32_e32 v17, v2
	v_cvt_pk_bf16_f32 v122, v174, v176
	v_cvt_pk_bf16_f32 v123, v178, v180
	v_cvt_pk_bf16_f32 v124, v182, v184
	v_cvt_pk_bf16_f32 v125, v186, v189
	v_cvt_pk_bf16_f32 v126, v158, v160
	v_cvt_pk_bf16_f32 v127, v162, v164
	v_cvt_pk_bf16_f32 v128, v166, v168
	v_cvt_pk_bf16_f32 v129, v170, v172
	v_cvt_pk_bf16_f32 v146, v173, v175
	v_cvt_pk_bf16_f32 v147, v177, v179
	v_cvt_pk_bf16_f32 v148, v181, v183
	v_cvt_pk_bf16_f32 v149, v185, v187
	v_cvt_pk_bf16_f32 v150, v157, v159
	v_cvt_pk_bf16_f32 v151, v161, v163
	v_cvt_pk_bf16_f32 v152, v165, v167
	v_cvt_pk_bf16_f32 v153, v169, v171
	s_waitcnt lgkmcnt(3)
	s_nop 0
	v_mfma_f32_32x32x16_bf16 v[50:65], v[34:37], v[150:153], v[2:17]
	ds_read_b128 v[18:21], v194 offset:45664
	ds_read_b128 v[22:25], v194 offset:45632
	ds_read_b128 v[26:29], v194 offset:45568
	ds_read_b128 v[30:33], v194 offset:45600
	s_waitcnt lgkmcnt(6)
	v_mfma_f32_32x32x16_bf16 v[50:65], v[38:41], v[146:149], v[50:65]
	s_waitcnt lgkmcnt(5)
	v_mfma_f32_32x32x16_bf16 v[50:65], v[42:45], v[126:129], v[50:65]
	s_waitcnt lgkmcnt(4)
	v_mfma_f32_32x32x16_bf16 v[50:65], v[46:49], v[122:125], v[50:65]
	s_waitcnt lgkmcnt(1)
	v_mfma_f32_32x32x16_bf16 v[34:49], v[26:29], v[150:153], v[2:17]
	ds_read_b128 v[198:201], v194 offset:54368
	ds_read_b128 v[202:205], v194 offset:54336
	ds_read_b128 v[206:209], v194 offset:54272
	ds_read_b128 v[210:213], v194 offset:54304
	s_waitcnt lgkmcnt(4)
	v_mfma_f32_32x32x16_bf16 v[34:49], v[30:33], v[146:149], v[34:49]
	v_mfma_f32_32x32x16_bf16 v[34:49], v[22:25], v[126:129], v[34:49]
	v_mfma_f32_32x32x16_bf16 v[34:49], v[18:21], v[122:125], v[34:49]
	s_waitcnt lgkmcnt(1)
	v_mfma_f32_32x32x16_bf16 v[18:33], v[206:209], v[150:153], v[2:17]
	s_waitcnt lgkmcnt(0)
	v_mfma_f32_32x32x16_bf16 v[18:33], v[210:213], v[146:149], v[18:33]
	v_mfma_f32_32x32x16_bf16 v[18:33], v[202:205], v[126:129], v[18:33]
	v_mfma_f32_32x32x16_bf16 v[18:33], v[198:201], v[122:125], v[18:33]
	ds_read_b128 v[198:201], v194 offset:63072
	ds_read_b128 v[202:205], v194 offset:63040
	ds_read_b128 v[206:209], v194 offset:62976
	ds_read_b128 v[210:213], v194 offset:63008
	s_waitcnt lgkmcnt(1)
	v_mfma_f32_32x32x16_bf16 v[2:17], v[206:209], v[150:153], v[2:17]
	s_waitcnt lgkmcnt(0)
	v_mfma_f32_32x32x16_bf16 v[2:17], v[210:213], v[146:149], v[2:17]
	v_mfma_f32_32x32x16_bf16 v[2:17], v[202:205], v[126:129], v[2:17]
	v_mfma_f32_32x32x16_bf16 v[2:17], v[198:201], v[122:125], v[2:17]
	ds_read_b128 v[150:153], v194 offset:36992
	ds_read_b128 v[146:149], v194 offset:37024
	ds_read_b128 v[122:125], v194 offset:37056
	ds_read_b128 v[126:129], v194 offset:37088
	v_max3_f32 v191, v82, v66, v83
	v_max_f32_e32 v195, v81, v81
	v_max3_f32 v191, v191, v67, v84
	v_max3_f32 v191, v191, v68, v85
	v_max3_f32 v191, v191, v69, v86
	v_max3_f32 v191, v191, v70, v87
	v_max3_f32 v191, v191, v71, v88
	v_max3_f32 v191, v191, v72, v89
	v_max3_f32 v191, v191, v73, v90
	v_max3_f32 v191, v191, v74, v91
	v_max3_f32 v191, v191, v75, v92
	v_max3_f32 v191, v191, v76, v93
	v_max3_f32 v191, v191, v77, v94
	v_max3_f32 v191, v191, v78, v95
	v_max3_f32 v191, v191, v79, v96
	v_max3_f32 v191, v191, v80, v97
	s_nop 0
	v_max_f32_e32 v191, v191, v191
	v_max_f32_e32 v191, v191, v195
	v_mov_b32_e32 v195, v191
	v_nop
	v_nop
	v_permlane32_swap_b32 v195, v191
	s_nop 0
	v_max3_f32 v243, v0, v195, v191
	v_sub_f32_e32 v0, v0, v243
	v_exp_f32_e32 v0, v0
	s_nop 0
	v_cmp_neq_f32_e32 vcc, 1.0, v0
	s_cbranch_vccz .LBB0_161
	v_mul_f32_e32 v64, v0, v64
	v_mul_f32_e32 v65, v0, v65
	v_mul_f32_e32 v62, v0, v62
	v_mul_f32_e32 v63, v0, v63
	v_mul_f32_e32 v60, v0, v60
	v_mul_f32_e32 v61, v0, v61
	v_mul_f32_e32 v58, v0, v58
	v_mul_f32_e32 v59, v0, v59
	v_mul_f32_e32 v56, v0, v56
	v_mul_f32_e32 v57, v0, v57
	v_mul_f32_e32 v54, v0, v54
	v_mul_f32_e32 v55, v0, v55
	v_mul_f32_e32 v52, v0, v52
	v_mul_f32_e32 v53, v0, v53
	v_mul_f32_e32 v50, v0, v50
	v_mul_f32_e32 v51, v0, v51
	v_mul_f32_e32 v48, v0, v48
	v_mul_f32_e32 v49, v0, v49
	v_mul_f32_e32 v46, v0, v46
	v_mul_f32_e32 v47, v0, v47
	v_mul_f32_e32 v44, v0, v44
	v_mul_f32_e32 v45, v0, v45
	v_mul_f32_e32 v42, v0, v42
	v_mul_f32_e32 v43, v0, v43
	v_mul_f32_e32 v40, v0, v40
	v_mul_f32_e32 v41, v0, v41
	v_mul_f32_e32 v38, v0, v38
	v_mul_f32_e32 v39, v0, v39
	v_mul_f32_e32 v36, v0, v36
	v_mul_f32_e32 v37, v0, v37
	v_mul_f32_e32 v34, v0, v34
	v_mul_f32_e32 v35, v0, v35
	v_mul_f32_e32 v32, v0, v32
	v_mul_f32_e32 v33, v0, v33
	v_mul_f32_e32 v30, v0, v30
	v_mul_f32_e32 v31, v0, v31
	v_mul_f32_e32 v28, v0, v28
	v_mul_f32_e32 v29, v0, v29
	v_mul_f32_e32 v26, v0, v26
	v_mul_f32_e32 v27, v0, v27
	v_mul_f32_e32 v24, v0, v24
	v_mul_f32_e32 v25, v0, v25
	v_mul_f32_e32 v22, v0, v22
	v_mul_f32_e32 v23, v0, v23
	v_mul_f32_e32 v20, v0, v20
	v_mul_f32_e32 v21, v0, v21
	v_mul_f32_e32 v18, v0, v18
	v_mul_f32_e32 v19, v0, v19
	v_mul_f32_e32 v16, v0, v16
	v_mul_f32_e32 v17, v0, v17
	v_mul_f32_e32 v14, v0, v14
	v_mul_f32_e32 v15, v0, v15
	v_mul_f32_e32 v12, v0, v12
	v_mul_f32_e32 v13, v0, v13
	v_mul_f32_e32 v10, v0, v10
	v_mul_f32_e32 v11, v0, v11
	v_mul_f32_e32 v8, v0, v8
	v_mul_f32_e32 v9, v0, v9
	v_mul_f32_e32 v6, v0, v6
	v_mul_f32_e32 v7, v0, v7
	v_mul_f32_e32 v4, v0, v4
	v_mul_f32_e32 v5, v0, v5
	v_mul_f32_e32 v2, v0, v2
	v_mul_f32_e32 v3, v0, v3
.LBB0_161:
	v_sub_f32_e32 v66, v66, v243
	v_exp_f32_e32 v202, v66
	v_sub_f32_e32 v66, v83, v243
	v_exp_f32_e32 v203, v66
	v_sub_f32_e32 v66, v67, v243
	v_exp_f32_e32 v204, v66
	v_sub_f32_e32 v66, v84, v243
	v_exp_f32_e32 v205, v66
	v_sub_f32_e32 v66, v68, v243
	v_exp_f32_e32 v206, v66
	v_sub_f32_e32 v66, v85, v243
	v_exp_f32_e32 v207, v66
	v_sub_f32_e32 v66, v69, v243
	v_exp_f32_e32 v208, v66
	v_sub_f32_e32 v66, v86, v243
	v_exp_f32_e32 v209, v66
	v_sub_f32_e32 v66, v70, v243
	v_exp_f32_e32 v220, v66
	v_sub_f32_e32 v66, v87, v243
	v_exp_f32_e32 v221, v66
	v_sub_f32_e32 v66, v71, v243
	v_exp_f32_e32 v222, v66
	v_sub_f32_e32 v66, v88, v243
	v_exp_f32_e32 v223, v66
	v_sub_f32_e32 v66, v72, v243
	v_exp_f32_e32 v224, v66
	v_sub_f32_e32 v66, v89, v243
	v_exp_f32_e32 v225, v66
	v_sub_f32_e32 v66, v73, v243
	v_exp_f32_e32 v226, v66
	v_sub_f32_e32 v66, v90, v243
	v_exp_f32_e32 v227, v66
	v_sub_f32_e32 v66, v74, v243
	v_exp_f32_e32 v228, v66
	v_sub_f32_e32 v66, v91, v243
	v_exp_f32_e32 v229, v66
	v_sub_f32_e32 v66, v75, v243
	v_exp_f32_e32 v230, v66
	v_sub_f32_e32 v66, v92, v243
	v_exp_f32_e32 v231, v66
	v_sub_f32_e32 v66, v76, v243
	v_exp_f32_e32 v232, v66
	v_sub_f32_e32 v66, v93, v243
	v_exp_f32_e32 v233, v66
	v_sub_f32_e32 v66, v77, v243
	v_exp_f32_e32 v234, v66
	v_sub_f32_e32 v66, v94, v243
	v_exp_f32_e32 v235, v66
	v_sub_f32_e32 v66, v78, v243
	v_exp_f32_e32 v236, v66
	v_sub_f32_e32 v66, v95, v243
	v_exp_f32_e32 v237, v66
	v_sub_f32_e32 v66, v79, v243
	v_exp_f32_e32 v238, v66
	v_sub_f32_e32 v66, v96, v243
	v_exp_f32_e32 v239, v66
	v_sub_f32_e32 v66, v80, v243
	v_exp_f32_e32 v240, v66
	v_sub_f32_e32 v66, v97, v243
	v_sub_f32_e32 v82, v82, v243
	v_exp_f32_e32 v241, v66
	v_sub_f32_e32 v66, v81, v243
	v_exp_f32_e32 v195, v82
	v_exp_f32_e32 v242, v66
	v_add_u32_e32 v191, 0x9000, v194
	v_cvt_pk_bf16_f32 v66, v228, v230
	v_cvt_pk_bf16_f32 v67, v232, v234
	v_cvt_pk_bf16_f32 v68, v236, v238
	v_cvt_pk_bf16_f32 v69, v240, v242
	v_cvt_pk_bf16_f32 v70, v202, v204
	v_cvt_pk_bf16_f32 v71, v206, v208
	v_cvt_pk_bf16_f32 v72, v220, v222
	v_cvt_pk_bf16_f32 v73, v224, v226
	v_cvt_pk_bf16_f32 v74, v227, v229
	v_cvt_pk_bf16_f32 v75, v231, v233
	v_cvt_pk_bf16_f32 v76, v235, v237
	v_cvt_pk_bf16_f32 v77, v239, v241
	v_cvt_pk_bf16_f32 v78, v195, v203
	v_cvt_pk_bf16_f32 v79, v205, v207
	v_cvt_pk_bf16_f32 v80, v209, v221
	v_cvt_pk_bf16_f32 v81, v223, v225
	s_waitcnt lgkmcnt(3)
	s_nop 0
	v_mfma_f32_32x32x16_bf16 v[50:65], v[150:153], v[78:81], v[50:65]
	ds_read_b128 v[82:85], v194 offset:45792
	ds_read_b128 v[86:89], v194 offset:45760
	ds_read_b128 v[90:93], v194 offset:45696
	ds_read_b128 v[94:97], v194 offset:45728
	s_waitcnt lgkmcnt(6)
	v_mfma_f32_32x32x16_bf16 v[50:65], v[146:149], v[74:77], v[50:65]
	s_waitcnt lgkmcnt(5)
	v_mfma_f32_32x32x16_bf16 v[50:65], v[122:125], v[70:73], v[50:65]
	s_waitcnt lgkmcnt(4)
	v_mfma_f32_32x32x16_bf16 v[50:65], v[126:129], v[66:69], v[50:65]
	s_waitcnt lgkmcnt(1)
	v_mfma_f32_32x32x16_bf16 v[34:49], v[90:93], v[78:81], v[34:49]
	s_waitcnt lgkmcnt(0)
	v_mfma_f32_32x32x16_bf16 v[34:49], v[94:97], v[74:77], v[34:49]
	v_mfma_f32_32x32x16_bf16 v[34:49], v[86:89], v[70:73], v[34:49]
	v_mfma_f32_32x32x16_bf16 v[34:49], v[82:85], v[66:69], v[34:49]
	ds_read_b128 v[82:85], v194 offset:54496
	ds_read_b128 v[86:89], v194 offset:54464
	ds_read_b128 v[90:93], v194 offset:54400
	ds_read_b128 v[94:97], v194 offset:54432
	s_waitcnt lgkmcnt(1)
	v_mfma_f32_32x32x16_bf16 v[18:33], v[90:93], v[78:81], v[18:33]
	s_waitcnt lgkmcnt(0)
	v_mfma_f32_32x32x16_bf16 v[18:33], v[94:97], v[74:77], v[18:33]
	v_mfma_f32_32x32x16_bf16 v[18:33], v[86:89], v[70:73], v[18:33]
	v_mfma_f32_32x32x16_bf16 v[18:33], v[82:85], v[66:69], v[18:33]
	ds_read_b128 v[82:85], v194 offset:63200
	ds_read_b128 v[86:89], v194 offset:63168
	ds_read_b128 v[90:93], v194 offset:63104
	ds_read_b128 v[94:97], v194 offset:63136
	s_waitcnt lgkmcnt(1)
	v_mfma_f32_32x32x16_bf16 v[2:17], v[90:93], v[78:81], v[2:17]
	s_waitcnt lgkmcnt(0)
	v_mfma_f32_32x32x16_bf16 v[2:17], v[94:97], v[74:77], v[2:17]
	v_mfma_f32_32x32x16_bf16 v[2:17], v[86:89], v[70:73], v[2:17]
	v_mfma_f32_32x32x16_bf16 v[2:17], v[82:85], v[66:69], v[2:17]
	v_add_u32_e32 v66, 0x8800, v193
	s_waitcnt vmcnt(5)
	ds_write_b128 v190, v[98:101] offset:18432
	s_waitcnt vmcnt(4)
	ds_write_b128 v190, v[118:121] offset:27648
	s_waitcnt vmcnt(3)
	ds_write2_b64 v66, v[114:115], v[116:117] offset1:2
	v_add_u32_e32 v66, 0xa800, v193
	s_waitcnt vmcnt(2)
	ds_write2_b64 v66, v[110:111], v[112:113] offset0:64 offset1:66
	v_add_u32_e32 v66, 0xc800, v193
	s_waitcnt vmcnt(1)
	ds_write2_b64 v66, v[106:107], v[108:109] offset0:128 offset1:130
	v_add_u32_e32 v66, 0xe800, v193
	s_waitcnt vmcnt(0)
	ds_write2_b64 v66, v[102:103], v[104:105] offset0:192 offset1:194
	s_waitcnt lgkmcnt(0)
	s_barrier
	ds_read_b128 v[66:69], v192 offset:18432
	ds_read_b128 v[70:73], v192 offset:18464
	ds_read_b128 v[74:77], v192 offset:23040
	ds_read_b128 v[78:81], v192 offset:23072
	ds_read_b128 v[82:85], v192 offset:18496
	ds_read_b128 v[86:89], v192 offset:18528
	ds_read_b128 v[90:93], v192 offset:23104
	ds_read_b128 v[94:97], v192 offset:23136
	s_waitcnt lgkmcnt(7)
	v_mfma_f32_32x32x16_bf16 v[114:129], v[66:69], v[130:133], 0
	s_waitcnt lgkmcnt(5)
	v_mfma_f32_32x32x16_bf16 v[98:113], v[74:77], v[130:133], 0
	v_mfma_f32_32x32x16_bf16 v[114:129], v[70:73], v[134:137], v[114:129]
	s_waitcnt lgkmcnt(4)
	v_mfma_f32_32x32x16_bf16 v[98:113], v[78:81], v[134:137], v[98:113]
	s_waitcnt lgkmcnt(3)
	v_mfma_f32_32x32x16_bf16 v[114:129], v[82:85], v[138:141], v[114:129]
	s_waitcnt lgkmcnt(1)
	v_mfma_f32_32x32x16_bf16 v[98:113], v[90:93], v[138:141], v[98:113]
	v_mfma_f32_32x32x16_bf16 v[114:129], v[86:89], v[142:145], v[114:129]
	s_waitcnt lgkmcnt(0)
	v_mfma_f32_32x32x16_bf16 v[98:113], v[94:97], v[142:145], v[98:113]
	ds_read_b128 v[66:69], v192 offset:27648
	ds_read_b128 v[146:149], v192 offset:27680
	ds_read_b128 v[70:73], v192 offset:32256
	ds_read_b128 v[150:153], v192 offset:32288
	ds_read_b128 v[198:201], v192 offset:27712
	ds_read_b128 v[210:213], v192 offset:27744
	ds_read_b128 v[214:217], v192 offset:32320
	ds_read_b128 v[244:247], v192 offset:32352
	s_waitcnt lgkmcnt(7)
	v_mfma_f32_32x32x16_bf16 v[82:97], v[66:69], v[130:133], 0
	s_waitcnt lgkmcnt(5)
	v_mfma_f32_32x32x16_bf16 v[66:81], v[70:73], v[130:133], 0
	v_mfma_f32_32x32x16_bf16 v[82:97], v[146:149], v[134:137], v[82:97]
	s_waitcnt lgkmcnt(4)
	v_mfma_f32_32x32x16_bf16 v[66:81], v[150:153], v[134:137], v[66:81]
	s_waitcnt lgkmcnt(3)
	v_mfma_f32_32x32x16_bf16 v[82:97], v[198:201], v[138:141], v[82:97]
	s_waitcnt lgkmcnt(1)
	v_mfma_f32_32x32x16_bf16 v[66:81], v[214:217], v[138:141], v[66:81]
	v_mfma_f32_32x32x16_bf16 v[82:97], v[210:213], v[142:145], v[82:97]
	s_waitcnt lgkmcnt(0)
	v_mfma_f32_32x32x16_bf16 v[66:81], v[244:247], v[142:145], v[66:81]
	ds_read_b128 v[142:145], v191 offset:34816
	ds_read_b128 v[138:141], v191 offset:34848
	ds_read_b128 v[130:133], v191 offset:34880
	ds_read_b128 v[134:137], v191 offset:34912
	v_max3_f32 v146, v114, v98, v115
	v_max_f32_e32 v147, v113, v113
	v_max3_f32 v146, v146, v99, v116
	v_max3_f32 v146, v146, v100, v117
	v_max3_f32 v146, v146, v101, v118
	v_max3_f32 v146, v146, v102, v119
	v_max3_f32 v146, v146, v103, v120
	v_max3_f32 v146, v146, v104, v121
	v_max3_f32 v146, v146, v105, v122
	v_max3_f32 v146, v146, v106, v123
	v_max3_f32 v146, v146, v107, v124
	v_max3_f32 v146, v146, v108, v125
	v_max3_f32 v146, v146, v109, v126
	v_max3_f32 v146, v146, v110, v127
	v_max3_f32 v146, v146, v111, v128
	v_max3_f32 v146, v146, v112, v129
	s_nop 0
	v_max_f32_e32 v146, v146, v146
	v_max_f32_e32 v146, v146, v147
	v_mov_b32_e32 v147, v146
	v_nop
	v_nop
	v_permlane32_swap_b32 v146, v147
	s_nop 0
	v_max3_f32 v251, v243, v146, v147
	v_sub_f32_e32 v146, v243, v251
	v_exp_f32_e32 v146, v146
	s_nop 0
	v_cmp_neq_f32_e32 vcc, 1.0, v146
	s_cbranch_vccz .LBB0_163
	v_mul_f32_e32 v64, v146, v64
	v_mul_f32_e32 v65, v146, v65
	v_mul_f32_e32 v62, v146, v62
	v_mul_f32_e32 v63, v146, v63
	v_mul_f32_e32 v60, v146, v60
	v_mul_f32_e32 v61, v146, v61
	v_mul_f32_e32 v58, v146, v58
	v_mul_f32_e32 v59, v146, v59
	v_mul_f32_e32 v56, v146, v56
	v_mul_f32_e32 v57, v146, v57
	v_mul_f32_e32 v54, v146, v54
	v_mul_f32_e32 v55, v146, v55
	v_mul_f32_e32 v52, v146, v52
	v_mul_f32_e32 v53, v146, v53
	v_mul_f32_e32 v50, v146, v50
	v_mul_f32_e32 v51, v146, v51
	v_mul_f32_e32 v48, v146, v48
	v_mul_f32_e32 v49, v146, v49
	v_mul_f32_e32 v46, v146, v46
	v_mul_f32_e32 v47, v146, v47
	v_mul_f32_e32 v44, v146, v44
	v_mul_f32_e32 v45, v146, v45
	v_mul_f32_e32 v42, v146, v42
	v_mul_f32_e32 v43, v146, v43
	v_mul_f32_e32 v40, v146, v40
	v_mul_f32_e32 v41, v146, v41
	v_mul_f32_e32 v38, v146, v38
	v_mul_f32_e32 v39, v146, v39
	v_mul_f32_e32 v36, v146, v36
	v_mul_f32_e32 v37, v146, v37
	v_mul_f32_e32 v34, v146, v34
	v_mul_f32_e32 v35, v146, v35
	v_mul_f32_e32 v32, v146, v32
	v_mul_f32_e32 v33, v146, v33
	v_mul_f32_e32 v30, v146, v30
	v_mul_f32_e32 v31, v146, v31
	v_mul_f32_e32 v28, v146, v28
	v_mul_f32_e32 v29, v146, v29
	v_mul_f32_e32 v26, v146, v26
	v_mul_f32_e32 v27, v146, v27
	v_mul_f32_e32 v24, v146, v24
	v_mul_f32_e32 v25, v146, v25
	v_mul_f32_e32 v22, v146, v22
	v_mul_f32_e32 v23, v146, v23
	v_mul_f32_e32 v20, v146, v20
	v_mul_f32_e32 v21, v146, v21
	v_mul_f32_e32 v18, v146, v18
	v_mul_f32_e32 v19, v146, v19
	v_mul_f32_e32 v16, v146, v16
	v_mul_f32_e32 v17, v146, v17
	v_mul_f32_e32 v14, v146, v14
	v_mul_f32_e32 v15, v146, v15
	v_mul_f32_e32 v12, v146, v12
	v_mul_f32_e32 v13, v146, v13
	v_mul_f32_e32 v10, v146, v10
	v_mul_f32_e32 v11, v146, v11
	v_mul_f32_e32 v8, v146, v8
	v_mul_f32_e32 v9, v146, v9
	v_mul_f32_e32 v6, v146, v6
	v_mul_f32_e32 v7, v146, v7
	v_mul_f32_e32 v4, v146, v4
	v_mul_f32_e32 v5, v146, v5
	v_mul_f32_e32 v2, v146, v2
	v_mul_f32_e32 v3, v146, v3
.LBB0_163:
	v_sub_f32_e32 v98, v98, v251
	v_exp_f32_e32 v148, v98
	v_sub_f32_e32 v98, v115, v251
	v_exp_f32_e32 v115, v98
	v_sub_f32_e32 v98, v99, v251
	v_exp_f32_e32 v149, v98
	v_sub_f32_e32 v98, v116, v251
	v_exp_f32_e32 v150, v98
	v_sub_f32_e32 v98, v100, v251
	v_exp_f32_e32 v151, v98
	v_sub_f32_e32 v98, v117, v251
	v_exp_f32_e32 v152, v98
	v_sub_f32_e32 v98, v101, v251
	v_exp_f32_e32 v153, v98
	v_sub_f32_e32 v98, v118, v251
	v_exp_f32_e32 v118, v98
	v_sub_f32_e32 v98, v102, v251
	v_exp_f32_e32 v190, v98
	v_sub_f32_e32 v98, v119, v251
	v_exp_f32_e32 v119, v98
	v_sub_f32_e32 v98, v103, v251
	v_exp_f32_e32 v192, v98
	v_sub_f32_e32 v98, v120, v251
	v_exp_f32_e32 v120, v98
	v_sub_f32_e32 v98, v104, v251
	v_exp_f32_e32 v193, v98
	v_sub_f32_e32 v98, v121, v251
	v_exp_f32_e32 v121, v98
	v_sub_f32_e32 v98, v105, v251
	v_exp_f32_e32 v194, v98
	v_sub_f32_e32 v98, v122, v251
	v_exp_f32_e32 v122, v98
	v_sub_f32_e32 v98, v106, v251
	v_exp_f32_e32 v243, v98
	v_sub_f32_e32 v98, v123, v251
	v_exp_f32_e32 v123, v98
	v_sub_f32_e32 v98, v107, v251
	v_exp_f32_e32 v244, v98
	v_sub_f32_e32 v98, v124, v251
	v_exp_f32_e32 v124, v98
	v_sub_f32_e32 v98, v108, v251
	v_exp_f32_e32 v245, v98
	v_sub_f32_e32 v98, v125, v251
	v_exp_f32_e32 v125, v98
	v_sub_f32_e32 v98, v109, v251
	v_exp_f32_e32 v246, v98
	v_sub_f32_e32 v98, v126, v251
	v_exp_f32_e32 v126, v98
	v_sub_f32_e32 v98, v110, v251
	v_exp_f32_e32 v247, v98
	v_sub_f32_e32 v98, v127, v251
	v_exp_f32_e32 v127, v98
	v_sub_f32_e32 v98, v111, v251
	v_exp_f32_e32 v248, v98
	v_sub_f32_e32 v98, v128, v251
	v_exp_f32_e32 v128, v98
	v_sub_f32_e32 v98, v112, v251
	v_exp_f32_e32 v249, v98
	v_sub_f32_e32 v98, v129, v251
	v_sub_f32_e32 v114, v114, v251
	v_exp_f32_e32 v129, v98
	v_sub_f32_e32 v98, v113, v251
	v_exp_f32_e32 v147, v114
	v_exp_f32_e32 v250, v98
	v_cvt_pk_bf16_f32 v98, v243, v244
	v_cvt_pk_bf16_f32 v99, v245, v246
	v_cvt_pk_bf16_f32 v100, v247, v248
	v_cvt_pk_bf16_f32 v101, v249, v250
	v_cvt_pk_bf16_f32 v102, v148, v149
	v_cvt_pk_bf16_f32 v103, v151, v153
	v_cvt_pk_bf16_f32 v104, v190, v192
	v_cvt_pk_bf16_f32 v105, v193, v194
	v_cvt_pk_bf16_f32 v106, v122, v123
	v_cvt_pk_bf16_f32 v107, v124, v125
	v_cvt_pk_bf16_f32 v108, v126, v127
	v_cvt_pk_bf16_f32 v109, v128, v129
	v_cvt_pk_bf16_f32 v110, v147, v115
	v_cvt_pk_bf16_f32 v111, v150, v152
	v_cvt_pk_bf16_f32 v112, v118, v119
	v_cvt_pk_bf16_f32 v113, v120, v121
	s_waitcnt lgkmcnt(3)
	s_nop 0
	v_mfma_f32_32x32x16_bf16 v[50:65], v[142:145], v[110:113], v[50:65]
	s_waitcnt lgkmcnt(2)
	v_mfma_f32_32x32x16_bf16 v[50:65], v[138:141], v[106:109], v[50:65]
	s_waitcnt lgkmcnt(1)
	v_mfma_f32_32x32x16_bf16 v[50:65], v[130:133], v[102:105], v[50:65]
	s_waitcnt lgkmcnt(0)
	v_mfma_f32_32x32x16_bf16 v[50:65], v[134:137], v[98:101], v[50:65]
	ds_read_b128 v[130:133], v191 offset:43616
	ds_read_b128 v[134:137], v191 offset:43584
	ds_read_b128 v[138:141], v191 offset:43520
	ds_read_b128 v[142:145], v191 offset:43552
	s_waitcnt lgkmcnt(1)
	v_mfma_f32_32x32x16_bf16 v[34:49], v[138:141], v[110:113], v[34:49]
	s_waitcnt lgkmcnt(0)
	v_mfma_f32_32x32x16_bf16 v[34:49], v[142:145], v[106:109], v[34:49]
	v_mfma_f32_32x32x16_bf16 v[34:49], v[134:137], v[102:105], v[34:49]
	v_mfma_f32_32x32x16_bf16 v[34:49], v[130:133], v[98:101], v[34:49]
	ds_read_b128 v[130:133], v191 offset:52320
	ds_read_b128 v[134:137], v191 offset:52288
	ds_read_b128 v[138:141], v191 offset:52224
	ds_read_b128 v[142:145], v191 offset:52256
	s_waitcnt lgkmcnt(1)
	v_mfma_f32_32x32x16_bf16 v[18:33], v[138:141], v[110:113], v[18:33]
	s_waitcnt lgkmcnt(0)
	v_mfma_f32_32x32x16_bf16 v[18:33], v[142:145], v[106:109], v[18:33]
	v_mfma_f32_32x32x16_bf16 v[18:33], v[134:137], v[102:105], v[18:33]
	v_mfma_f32_32x32x16_bf16 v[18:33], v[130:133], v[98:101], v[18:33]
	ds_read_b128 v[130:133], v191 offset:61024
	ds_read_b128 v[134:137], v191 offset:60992
	ds_read_b128 v[138:141], v191 offset:60928
	ds_read_b128 v[142:145], v191 offset:60960
	s_waitcnt lgkmcnt(1)
	v_mfma_f32_32x32x16_bf16 v[2:17], v[138:141], v[110:113], v[2:17]
	s_waitcnt lgkmcnt(0)
	v_mfma_f32_32x32x16_bf16 v[2:17], v[142:145], v[106:109], v[2:17]
	v_mfma_f32_32x32x16_bf16 v[2:17], v[134:137], v[102:105], v[2:17]
	v_mfma_f32_32x32x16_bf16 v[2:17], v[130:133], v[98:101], v[2:17]
	ds_read_b128 v[110:113], v191 offset:34944
	ds_read_b128 v[106:109], v191 offset:34976
	ds_read_b128 v[98:101], v191 offset:35008
	ds_read_b128 v[102:105], v191 offset:35040
	v_max3_f32 v114, v82, v66, v83
	v_max_f32_e32 v116, v81, v81
	v_max3_f32 v114, v114, v67, v84
	v_max3_f32 v114, v114, v68, v85
	v_max3_f32 v114, v114, v69, v86
	v_max3_f32 v114, v114, v70, v87
	v_max3_f32 v114, v114, v71, v88
	v_max3_f32 v114, v114, v72, v89
	v_max3_f32 v114, v114, v73, v90
	v_max3_f32 v114, v114, v74, v91
	v_max3_f32 v114, v114, v75, v92
	v_max3_f32 v114, v114, v76, v93
	v_max3_f32 v114, v114, v77, v94
	v_max3_f32 v114, v114, v78, v95
	v_max3_f32 v114, v114, v79, v96
	v_max3_f32 v114, v114, v80, v97
	s_nop 0
	v_max_f32_e32 v114, v114, v114
	v_max_f32_e32 v114, v114, v116
	v_mov_b32_e32 v116, v114
	v_nop
	v_nop
	v_permlane32_swap_b32 v114, v116
	s_nop 0
	v_max3_f32 v130, v251, v114, v116
	v_sub_f32_e32 v114, v251, v130
	v_exp_f32_e32 v114, v114
	s_nop 0
	v_cmp_neq_f32_e32 vcc, 1.0, v114
	s_cbranch_vccz .LBB0_165
	v_mul_f32_e32 v64, v114, v64
	v_mul_f32_e32 v65, v114, v65
	v_mul_f32_e32 v62, v114, v62
	v_mul_f32_e32 v63, v114, v63
	v_mul_f32_e32 v60, v114, v60
	v_mul_f32_e32 v61, v114, v61
	v_mul_f32_e32 v58, v114, v58
	v_mul_f32_e32 v59, v114, v59
	v_mul_f32_e32 v56, v114, v56
	v_mul_f32_e32 v57, v114, v57
	v_mul_f32_e32 v54, v114, v54
	v_mul_f32_e32 v55, v114, v55
	v_mul_f32_e32 v52, v114, v52
	v_mul_f32_e32 v53, v114, v53
	v_mul_f32_e32 v50, v114, v50
	v_mul_f32_e32 v51, v114, v51
	v_mul_f32_e32 v48, v114, v48
	v_mul_f32_e32 v49, v114, v49
	v_mul_f32_e32 v46, v114, v46
	v_mul_f32_e32 v47, v114, v47
	v_mul_f32_e32 v44, v114, v44
	v_mul_f32_e32 v45, v114, v45
	v_mul_f32_e32 v42, v114, v42
	v_mul_f32_e32 v43, v114, v43
	v_mul_f32_e32 v40, v114, v40
	v_mul_f32_e32 v41, v114, v41
	v_mul_f32_e32 v38, v114, v38
	v_mul_f32_e32 v39, v114, v39
	v_mul_f32_e32 v36, v114, v36
	v_mul_f32_e32 v37, v114, v37
	v_mul_f32_e32 v34, v114, v34
	v_mul_f32_e32 v35, v114, v35
	v_mul_f32_e32 v32, v114, v32
	v_mul_f32_e32 v33, v114, v33
	v_mul_f32_e32 v30, v114, v30
	v_mul_f32_e32 v31, v114, v31
	v_mul_f32_e32 v28, v114, v28
	v_mul_f32_e32 v29, v114, v29
	v_mul_f32_e32 v26, v114, v26
	v_mul_f32_e32 v27, v114, v27
	v_mul_f32_e32 v24, v114, v24
	v_mul_f32_e32 v25, v114, v25
	v_mul_f32_e32 v22, v114, v22
	v_mul_f32_e32 v23, v114, v23
	v_mul_f32_e32 v20, v114, v20
	v_mul_f32_e32 v21, v114, v21
	v_mul_f32_e32 v18, v114, v18
	v_mul_f32_e32 v19, v114, v19
	v_mul_f32_e32 v16, v114, v16
	v_mul_f32_e32 v17, v114, v17
	v_mul_f32_e32 v14, v114, v14
	v_mul_f32_e32 v15, v114, v15
	v_mul_f32_e32 v12, v114, v12
	v_mul_f32_e32 v13, v114, v13
	v_mul_f32_e32 v10, v114, v10
	v_mul_f32_e32 v11, v114, v11
	v_mul_f32_e32 v8, v114, v8
	v_mul_f32_e32 v9, v114, v9
	v_mul_f32_e32 v6, v114, v6
	v_mul_f32_e32 v7, v114, v7
	v_mul_f32_e32 v4, v114, v4
	v_mul_f32_e32 v5, v114, v5
	v_mul_f32_e32 v2, v114, v2
	v_mul_f32_e32 v3, v114, v3
.LBB0_165:
	v_add_f32_e32 v131, v157, v158
	v_add_f32_e32 v131, 0, v131
	v_add_f32_e32 v132, v159, v160
	v_add_f32_e32 v131, v132, v131
	v_add_f32_e32 v132, v161, v162
	v_add_f32_e32 v131, v132, v131
	v_add_f32_e32 v132, v163, v164
	v_add_f32_e32 v131, v132, v131
	v_add_f32_e32 v132, v165, v166
	v_add_f32_e32 v131, v132, v131
	v_add_f32_e32 v132, v167, v168
	v_add_f32_e32 v131, v132, v131
	v_add_f32_e32 v132, v169, v170
	v_add_f32_e32 v131, v132, v131
	v_add_f32_e32 v132, v171, v172
	v_add_f32_e32 v131, v132, v131
	v_add_f32_e32 v132, v173, v174
	v_add_f32_e32 v131, v132, v131
	v_add_f32_e32 v132, v175, v176
	v_add_f32_e32 v131, v132, v131
	v_add_f32_e32 v132, v177, v178
	v_add_f32_e32 v131, v132, v131
	v_add_f32_e32 v132, v179, v180
	v_add_f32_e32 v131, v132, v131
	v_add_f32_e32 v132, v181, v182
	v_add_f32_e32 v131, v132, v131
	v_add_f32_e32 v132, v183, v184
	v_add_f32_e32 v131, v132, v131
	v_add_f32_e32 v132, v185, v186
	v_add_f32_e32 v131, v132, v131
	v_add_f32_e32 v132, v187, v189
	v_add_f32_e32 v131, v132, v131
	v_add_f32_e32 v132, v195, v202
	v_add_f32_e32 v132, 0, v132
	v_add_f32_e32 v133, v203, v204
	v_add_f32_e32 v132, v133, v132
	v_add_f32_e32 v133, v205, v206
	v_add_f32_e32 v132, v133, v132
	v_add_f32_e32 v133, v207, v208
	v_add_f32_e32 v132, v133, v132
	v_add_f32_e32 v133, v209, v220
	v_add_f32_e32 v132, v133, v132
	v_add_f32_e32 v133, v221, v222
	v_add_f32_e32 v132, v133, v132
	v_add_f32_e32 v133, v223, v224
	v_add_f32_e32 v132, v133, v132
	v_add_f32_e32 v133, v225, v226
	v_add_f32_e32 v132, v133, v132
	v_add_f32_e32 v133, v227, v228
	v_add_f32_e32 v132, v133, v132
	v_add_f32_e32 v133, v229, v230
	v_add_f32_e32 v132, v133, v132
	v_add_f32_e32 v133, v231, v232
	v_add_f32_e32 v132, v133, v132
	v_add_f32_e32 v133, v233, v234
	v_add_f32_e32 v132, v133, v132
	v_add_f32_e32 v133, v235, v236
	v_add_f32_e32 v132, v133, v132
	v_add_f32_e32 v133, v237, v238
	v_add_f32_e32 v132, v133, v132
	v_add_f32_e32 v133, v239, v240
	v_add_f32_e32 v132, v133, v132
	v_add_f32_e32 v133, v241, v242
	v_add_f32_e32 v131, v188, v131
	v_add_f32_e32 v132, v133, v132
	v_fmac_f32_e32 v132, v131, v0
	v_add_f32_e32 v0, v147, v148
	v_add_f32_e32 v0, 0, v0
	v_add_f32_e32 v115, v115, v149
	v_add_f32_e32 v0, v115, v0
	v_add_f32_e32 v115, v150, v151
	v_add_f32_e32 v0, v115, v0
	v_add_f32_e32 v115, v152, v153
	v_add_f32_e32 v0, v115, v0
	v_add_f32_e32 v115, v118, v190
	v_add_f32_e32 v0, v115, v0
	v_add_f32_e32 v115, v119, v192
	v_add_f32_e32 v0, v115, v0
	v_add_f32_e32 v115, v120, v193
	v_add_f32_e32 v0, v115, v0
	v_add_f32_e32 v115, v121, v194
	v_add_f32_e32 v0, v115, v0
	v_add_f32_e32 v115, v122, v243
	v_add_f32_e32 v0, v115, v0
	v_add_f32_e32 v115, v123, v244
	v_add_f32_e32 v0, v115, v0
	v_add_f32_e32 v115, v124, v245
	v_add_f32_e32 v0, v115, v0
	v_add_f32_e32 v115, v125, v246
	v_add_f32_e32 v0, v115, v0
	v_add_f32_e32 v115, v126, v247
	v_sub_f32_e32 v68, v68, v130
	v_add_f32_e32 v0, v115, v0
	v_add_f32_e32 v115, v127, v248
	v_exp_f32_e32 v119, v68
	v_sub_f32_e32 v68, v85, v130
	v_add_f32_e32 v0, v115, v0
	v_add_f32_e32 v115, v128, v249
	v_exp_f32_e32 v85, v68
	v_sub_f32_e32 v68, v69, v130
	v_add_f32_e32 v0, v115, v0
	v_add_f32_e32 v115, v129, v250
	v_sub_f32_e32 v66, v66, v130
	v_exp_f32_e32 v120, v68
	v_sub_f32_e32 v68, v86, v130
	v_add_f32_e32 v0, v115, v0
	v_sub_f32_e32 v82, v82, v130
	v_exp_f32_e32 v115, v66
	v_sub_f32_e32 v66, v83, v130
	v_exp_f32_e32 v86, v68
	v_sub_f32_e32 v68, v70, v130
	v_exp_f32_e32 v82, v82
	v_exp_f32_e32 v83, v66
	v_sub_f32_e32 v66, v67, v130
	v_exp_f32_e32 v121, v68
	v_sub_f32_e32 v68, v87, v130
	v_exp_f32_e32 v118, v66
	v_sub_f32_e32 v84, v84, v130
	v_exp_f32_e32 v87, v68
	v_sub_f32_e32 v68, v71, v130
	v_exp_f32_e32 v84, v84
	v_exp_f32_e32 v122, v68
	v_sub_f32_e32 v68, v88, v130
	v_exp_f32_e32 v88, v68
	v_sub_f32_e32 v68, v72, v130
	v_add_f32_e32 v66, v82, v115
	v_exp_f32_e32 v123, v68
	v_sub_f32_e32 v68, v89, v130
	v_add_f32_e32 v66, 0, v66
	v_add_f32_e32 v67, v83, v118
	v_exp_f32_e32 v89, v68
	v_sub_f32_e32 v68, v73, v130
	v_add_f32_e32 v66, v67, v66
	v_add_f32_e32 v67, v84, v119
	v_exp_f32_e32 v73, v68
	v_sub_f32_e32 v68, v90, v130
	v_add_f32_e32 v66, v67, v66
	v_add_f32_e32 v67, v85, v120
	v_exp_f32_e32 v90, v68
	v_sub_f32_e32 v68, v74, v130
	v_sub_f32_e32 v69, v91, v130
	v_add_f32_e32 v66, v67, v66
	v_add_f32_e32 v67, v86, v121
	v_exp_f32_e32 v68, v68
	v_exp_f32_e32 v74, v69
	v_sub_f32_e32 v69, v75, v130
	v_sub_f32_e32 v70, v92, v130
	v_add_f32_e32 v66, v67, v66
	v_add_f32_e32 v67, v87, v122
	v_exp_f32_e32 v69, v69
	v_exp_f32_e32 v75, v70
	v_sub_f32_e32 v70, v76, v130
	v_sub_f32_e32 v71, v93, v130
	v_add_f32_e32 v66, v67, v66
	v_add_f32_e32 v67, v88, v123
	v_exp_f32_e32 v70, v70
	v_exp_f32_e32 v76, v71
	v_sub_f32_e32 v71, v77, v130
	v_sub_f32_e32 v72, v94, v130
	v_add_f32_e32 v66, v67, v66
	v_add_f32_e32 v67, v89, v73
	v_exp_f32_e32 v71, v71
	v_exp_f32_e32 v77, v72
	v_sub_f32_e32 v72, v78, v130
	v_add_f32_e32 v66, v67, v66
	v_add_f32_e32 v67, v90, v68
	v_exp_f32_e32 v72, v72
	v_sub_f32_e32 v78, v95, v130
	v_sub_f32_e32 v79, v79, v130
	v_add_f32_e32 v66, v67, v66
	v_add_f32_e32 v67, v74, v69
	v_exp_f32_e32 v78, v78
	v_exp_f32_e32 v79, v79
	v_sub_f32_e32 v91, v96, v130
	v_sub_f32_e32 v80, v80, v130
	v_add_f32_e32 v66, v67, v66
	v_add_f32_e32 v67, v75, v70
	v_exp_f32_e32 v91, v91
	v_exp_f32_e32 v80, v80
	v_sub_f32_e32 v92, v97, v130
	v_sub_f32_e32 v81, v81, v130
	v_add_f32_e32 v66, v67, v66
	v_add_f32_e32 v67, v76, v71
	v_exp_f32_e32 v92, v92
	v_exp_f32_e32 v81, v81
	v_add_f32_e32 v66, v67, v66
	v_add_f32_e32 v67, v77, v72
	v_add_f32_e32 v66, v67, v66
	v_add_f32_e32 v67, v78, v79
	v_add_f32_e32 v66, v67, v66
	v_add_f32_e32 v67, v91, v80
	v_add_f32_e32 v66, v67, v66
	v_add_f32_e32 v67, v92, v81
	v_fmac_f32_e32 v0, v132, v146
	v_add_f32_e32 v124, v67, v66
	v_lshlrev_b64 v[116:117], 10, v[154:155]
	v_fmac_f32_e32 v124, v0, v114
	v_cvt_pk_bf16_f32 v66, v68, v69
	v_cvt_pk_bf16_f32 v67, v70, v71
	v_cvt_pk_bf16_f32 v68, v72, v79
	v_cvt_pk_bf16_f32 v69, v80, v81
	v_cvt_pk_bf16_f32 v70, v115, v118
	v_cvt_pk_bf16_f32 v71, v119, v120
	v_cvt_pk_bf16_f32 v72, v121, v122
	v_cvt_pk_bf16_f32 v73, v123, v73
	v_cvt_pk_bf16_f32 v74, v90, v74
	v_cvt_pk_bf16_f32 v75, v75, v76
	v_cvt_pk_bf16_f32 v76, v77, v78
	v_cvt_pk_bf16_f32 v77, v91, v92
	v_cvt_pk_bf16_f32 v78, v82, v83
	v_cvt_pk_bf16_f32 v79, v84, v85
	v_cvt_pk_bf16_f32 v80, v86, v87
	v_cvt_pk_bf16_f32 v81, v88, v89
	s_waitcnt lgkmcnt(3)
	s_nop 0
	v_mfma_f32_32x32x16_bf16 v[50:65], v[110:113], v[78:81], v[50:65]
	ds_read_b128 v[82:85], v191 offset:43744
	ds_read_b128 v[86:89], v191 offset:43712
	ds_read_b128 v[90:93], v191 offset:43648
	ds_read_b128 v[94:97], v191 offset:43680
	s_waitcnt lgkmcnt(6)
	v_mfma_f32_32x32x16_bf16 v[50:65], v[106:109], v[74:77], v[50:65]
	s_waitcnt lgkmcnt(5)
	v_mfma_f32_32x32x16_bf16 v[50:65], v[98:101], v[70:73], v[50:65]
	s_waitcnt lgkmcnt(4)
	v_mfma_f32_32x32x16_bf16 v[50:65], v[102:105], v[66:69], v[50:65]
	s_waitcnt lgkmcnt(1)
	v_mfma_f32_32x32x16_bf16 v[34:49], v[90:93], v[78:81], v[34:49]
	s_waitcnt lgkmcnt(0)
	v_mfma_f32_32x32x16_bf16 v[34:49], v[94:97], v[74:77], v[34:49]
	v_mfma_f32_32x32x16_bf16 v[34:49], v[86:89], v[70:73], v[34:49]
	v_mfma_f32_32x32x16_bf16 v[34:49], v[82:85], v[66:69], v[34:49]
	ds_read_b128 v[82:85], v191 offset:52448
	ds_read_b128 v[86:89], v191 offset:52416
	ds_read_b128 v[90:93], v191 offset:52352
	ds_read_b128 v[94:97], v191 offset:52384
	s_waitcnt lgkmcnt(1)
	v_mfma_f32_32x32x16_bf16 v[18:33], v[90:93], v[78:81], v[18:33]
	s_waitcnt lgkmcnt(0)
	v_mfma_f32_32x32x16_bf16 v[18:33], v[94:97], v[74:77], v[18:33]
	v_mfma_f32_32x32x16_bf16 v[18:33], v[86:89], v[70:73], v[18:33]
	v_mfma_f32_32x32x16_bf16 v[18:33], v[82:85], v[66:69], v[18:33]
	ds_read_b128 v[82:85], v191 offset:61152
	ds_read_b128 v[86:89], v191 offset:61120
	ds_read_b128 v[90:93], v191 offset:61056
	ds_read_b128 v[94:97], v191 offset:61088
	s_waitcnt lgkmcnt(1)
	v_mfma_f32_32x32x16_bf16 v[2:17], v[90:93], v[78:81], v[2:17]
	s_waitcnt lgkmcnt(0)
	v_mfma_f32_32x32x16_bf16 v[2:17], v[94:97], v[74:77], v[2:17]
	v_mfma_f32_32x32x16_bf16 v[2:17], v[86:89], v[70:73], v[2:17]
	v_mfma_f32_32x32x16_bf16 v[2:17], v[82:85], v[66:69], v[2:17]
	v_mov_b32_e32 v0, v124
	s_barrier
	v_nop
	v_nop
	v_permlane32_swap_b32 v124, v0
	s_nop 0
	v_add_f32_e32 v0, v124, v0
	v_div_scale_f32 v66, s[28:29], v0, v0, 1.0
	v_rcp_f32_e32 v67, v66
	s_mov_b32 s28, 0x3e38aa3b
	v_fma_f32 v68, -v66, v67, 1.0
	v_fmac_f32_e32 v67, v68, v67
	v_div_scale_f32 v68, vcc, 1.0, v0, 1.0
	v_mul_f32_e32 v69, v68, v67
	v_fma_f32 v70, -v66, v69, v68
	v_fmac_f32_e32 v69, v70, v67
	v_fma_f32 v66, -v66, v69, v68
	v_div_fmas_f32 v66, v66, v67, v69
	v_div_fixup_f32 v66, v66, v0, 1.0
	v_lshl_add_u64 v[68:69], v[116:117], 1, s[18:19]
	v_lshl_add_u64 v[68:69], v[68:69], 0, s[80:81]
	v_lshlrev_b32_e32 v0, 3, v156
	v_mul_f32_e32 v2, v66, v2
	v_mul_f32_e32 v3, v66, v3
	v_mul_f32_e32 v4, v66, v4
	v_mul_f32_e32 v5, v66, v5
	v_lshl_add_u64 v[68:69], v[68:69], 0, v[0:1]
	v_mul_f32_e32 v50, v66, v50
	v_mul_f32_e32 v51, v66, v51
	v_mul_f32_e32 v52, v66, v52
	v_mul_f32_e32 v53, v66, v53
	v_mul_f32_e32 v34, v66, v34
	v_mul_f32_e32 v35, v66, v35
	v_mul_f32_e32 v36, v66, v36
	v_mul_f32_e32 v37, v66, v37
	v_mul_f32_e32 v18, v66, v18
	v_mul_f32_e32 v19, v66, v19
	v_mul_f32_e32 v20, v66, v20
	v_mul_f32_e32 v21, v66, v21
	v_cvt_pk_bf16_f32 v2, v2, v3
	v_cvt_pk_bf16_f32 v3, v4, v5
	v_cvt_pk_bf16_f32 v50, v50, v51
	v_cvt_pk_bf16_f32 v51, v52, v53
	v_cvt_pk_bf16_f32 v34, v34, v35
	v_cvt_pk_bf16_f32 v35, v36, v37
	v_cvt_pk_bf16_f32 v18, v18, v19
	v_cvt_pk_bf16_f32 v19, v20, v21
	global_store_dwordx2 v[68:69], v[2:3], off offset:192
	v_pk_mul_f32 v[2:3], v[6:7], v[66:67] op_sel_hi:[1,0]
	v_pk_mul_f32 v[4:5], v[8:9], v[66:67] op_sel_hi:[1,0]
	global_store_dwordx2 v[68:69], v[50:51], off
	v_pk_mul_f32 v[50:51], v[54:55], v[66:67] op_sel_hi:[1,0]
	v_pk_mul_f32 v[52:53], v[56:57], v[66:67] op_sel_hi:[1,0]
	global_store_dwordx2 v[68:69], v[34:35], off offset:64
	v_pk_mul_f32 v[34:35], v[38:39], v[66:67] op_sel_hi:[1,0]
	v_pk_mul_f32 v[36:37], v[40:41], v[66:67] op_sel_hi:[1,0]
	global_store_dwordx2 v[68:69], v[18:19], off offset:128
	v_pk_mul_f32 v[18:19], v[22:23], v[66:67] op_sel_hi:[1,0]
	v_pk_mul_f32 v[20:21], v[24:25], v[66:67] op_sel_hi:[1,0]
	v_cvt_pk_bf16_f32 v2, v2, v3
	v_cvt_pk_bf16_f32 v3, v4, v5
	v_cvt_pk_bf16_f32 v50, v50, v51
	v_cvt_pk_bf16_f32 v51, v52, v53
	v_cvt_pk_bf16_f32 v34, v34, v35
	v_cvt_pk_bf16_f32 v35, v36, v37
	v_cvt_pk_bf16_f32 v18, v18, v19
	v_cvt_pk_bf16_f32 v19, v20, v21
	global_store_dwordx2 v[68:69], v[2:3], off offset:208
	v_pk_mul_f32 v[2:3], v[10:11], v[66:67] op_sel_hi:[1,0]
	v_pk_mul_f32 v[4:5], v[12:13], v[66:67] op_sel_hi:[1,0]
	global_store_dwordx2 v[68:69], v[50:51], off offset:16
	v_pk_mul_f32 v[50:51], v[58:59], v[66:67] op_sel_hi:[1,0]
	v_pk_mul_f32 v[52:53], v[60:61], v[66:67] op_sel_hi:[1,0]
	global_store_dwordx2 v[68:69], v[34:35], off offset:80
	v_pk_mul_f32 v[34:35], v[42:43], v[66:67] op_sel_hi:[1,0]
	v_pk_mul_f32 v[36:37], v[44:45], v[66:67] op_sel_hi:[1,0]
	global_store_dwordx2 v[68:69], v[18:19], off offset:144
	v_pk_mul_f32 v[18:19], v[26:27], v[66:67] op_sel_hi:[1,0]
	v_pk_mul_f32 v[20:21], v[28:29], v[66:67] op_sel_hi:[1,0]
	v_cvt_pk_bf16_f32 v2, v2, v3
	v_cvt_pk_bf16_f32 v3, v4, v5
	v_cvt_pk_bf16_f32 v50, v50, v51
	v_cvt_pk_bf16_f32 v51, v52, v53
	v_cvt_pk_bf16_f32 v34, v34, v35
	v_cvt_pk_bf16_f32 v35, v36, v37
	v_cvt_pk_bf16_f32 v18, v18, v19
	v_cvt_pk_bf16_f32 v19, v20, v21
	global_store_dwordx2 v[68:69], v[2:3], off offset:224
	v_pk_mul_f32 v[2:3], v[14:15], v[66:67] op_sel_hi:[1,0]
	v_pk_mul_f32 v[4:5], v[16:17], v[66:67] op_sel_hi:[1,0]
	global_store_dwordx2 v[68:69], v[50:51], off offset:32
	v_pk_mul_f32 v[50:51], v[62:63], v[66:67] op_sel_hi:[1,0]
	v_pk_mul_f32 v[52:53], v[64:65], v[66:67] op_sel_hi:[1,0]
	global_store_dwordx2 v[68:69], v[34:35], off offset:96
	v_pk_mul_f32 v[34:35], v[46:47], v[66:67] op_sel_hi:[1,0]
	v_pk_mul_f32 v[36:37], v[48:49], v[66:67] op_sel_hi:[1,0]
	global_store_dwordx2 v[68:69], v[18:19], off offset:160
	v_pk_mul_f32 v[18:19], v[30:31], v[66:67] op_sel_hi:[1,0]
	v_pk_mul_f32 v[20:21], v[32:33], v[66:67] op_sel_hi:[1,0]
	v_cvt_pk_bf16_f32 v2, v2, v3
	v_cvt_pk_bf16_f32 v3, v4, v5
	v_cvt_pk_bf16_f32 v50, v50, v51
	v_cvt_pk_bf16_f32 v51, v52, v53
	v_cvt_pk_bf16_f32 v34, v34, v35
	v_cvt_pk_bf16_f32 v35, v36, v37
	v_cvt_pk_bf16_f32 v18, v18, v19
	v_cvt_pk_bf16_f32 v19, v20, v21
	global_store_dwordx2 v[68:69], v[2:3], off offset:240
	v_mov_b32_e32 v3, v197
	global_store_dwordx2 v[68:69], v[50:51], off offset:48
	global_store_dwordx2 v[68:69], v[34:35], off offset:112
	global_store_dwordx2 v[68:69], v[18:19], off offset:176
	s_nop 0
	v_and_b32_e32 v2, 31, v3
	v_ashrrev_i32_e32 v0, 1, v3
	v_and_b32_e32 v0, 0xffffffe0, v0
	v_or_b32_e32 v4, s2, v2
	v_add_u32_e32 v156, v4, v0
	v_ashrrev_i32_e32 v157, 31, v156
	v_lshlrev_b64 v[154:155], 11, v[156:157]
	v_bfe_u32 v159, v3, 5, 1
	v_lshl_add_u64 v[4:5], s[48:49], 0, v[154:155]
	v_lshl_add_u64 v[4:5], v[4:5], 0, s[80:81]
	v_lshlrev_b32_e32 v0, 4, v159
	v_lshl_add_u64 v[16:17], v[4:5], 0, v[0:1]
	global_load_dwordx4 v[4:7], v[16:17], off offset:128
	global_load_dwordx4 v[8:11], v[16:17], off offset:160
	global_load_dwordx4 v[12:15], v[16:17], off offset:192
	s_nop 0
	global_load_dwordx4 v[16:19], v[16:17], off offset:224
	s_waitcnt vmcnt(3)
	v_and_b32_e32 v21, 0xffff0000, v4
	v_lshlrev_b32_e32 v20, 16, v4
	v_pk_mul_f32 v[20:21], v[20:21], s[28:29] op_sel_hi:[1,0]
	s_nop 0
	v_cvt_pk_bf16_f32 v130, v20, v21
	v_and_b32_e32 v21, 0xffff0000, v5
	v_lshlrev_b32_e32 v20, 16, v5
	v_pk_mul_f32 v[4:5], v[20:21], s[28:29] op_sel_hi:[1,0]
	s_nop 0
	v_cvt_pk_bf16_f32 v131, v4, v5
	v_and_b32_e32 v5, 0xffff0000, v6
	v_lshlrev_b32_e32 v4, 16, v6
	v_pk_mul_f32 v[4:5], v[4:5], s[28:29] op_sel_hi:[1,0]
	s_nop 0
	v_cvt_pk_bf16_f32 v132, v4, v5
	v_and_b32_e32 v5, 0xffff0000, v7
	v_lshlrev_b32_e32 v4, 16, v7
	v_pk_mul_f32 v[4:5], v[4:5], s[28:29] op_sel_hi:[1,0]
	v_ashrrev_i32_e32 v7, 3, v3
	v_cvt_pk_bf16_f32 v133, v4, v5
	s_waitcnt vmcnt(2)
	v_and_b32_e32 v5, 0xffff0000, v8
	v_lshlrev_b32_e32 v4, 16, v8
	v_pk_mul_f32 v[4:5], v[4:5], s[28:29] op_sel_hi:[1,0]
	v_ashrrev_i32_e32 v8, 4, v3
	v_cvt_pk_bf16_f32 v134, v4, v5
	v_and_b32_e32 v5, 0xffff0000, v9
	v_lshlrev_b32_e32 v4, 16, v9
	v_pk_mul_f32 v[4:5], v[4:5], s[28:29] op_sel_hi:[1,0]
	v_add_u32_e32 v9, s21, v8
	v_cvt_pk_bf16_f32 v135, v4, v5
	v_and_b32_e32 v5, 0xffff0000, v10
	v_lshlrev_b32_e32 v4, 16, v10
	v_pk_mul_f32 v[4:5], v[4:5], s[28:29] op_sel_hi:[1,0]
	v_and_b32_e32 v10, 15, v3
	v_cvt_pk_bf16_f32 v136, v4, v5
	v_and_b32_e32 v5, 0xffff0000, v11
	v_lshlrev_b32_e32 v4, 16, v11
	v_pk_mul_f32 v[4:5], v[4:5], s[28:29] op_sel_hi:[1,0]
	v_lshlrev_b32_e32 v11, 4, v3
	v_cvt_pk_bf16_f32 v137, v4, v5
	s_waitcnt vmcnt(1)
	v_and_b32_e32 v5, 0xffff0000, v12
	v_lshlrev_b32_e32 v4, 16, v12
	v_pk_mul_f32 v[4:5], v[4:5], s[28:29] op_sel_hi:[1,0]
	v_and_b32_e32 v6, 0x70, v11
	v_cvt_pk_bf16_f32 v138, v4, v5
	v_and_b32_e32 v5, 0xffff0000, v13
	v_lshlrev_b32_e32 v4, 16, v13
	v_pk_mul_f32 v[4:5], v[4:5], s[28:29] op_sel_hi:[1,0]
	v_mul_lo_u32 v40, v8, s43
	v_cvt_pk_bf16_f32 v139, v4, v5
	v_and_b32_e32 v5, 0xffff0000, v14
	v_lshlrev_b32_e32 v4, 16, v14
	v_pk_mul_f32 v[4:5], v[4:5], s[28:29] op_sel_hi:[1,0]
	v_lshlrev_b32_e32 v3, 3, v3
	v_cvt_pk_bf16_f32 v140, v4, v5
	v_and_b32_e32 v5, 0xffff0000, v15
	v_lshlrev_b32_e32 v4, 16, v15
	v_pk_mul_f32 v[4:5], v[4:5], s[28:29] op_sel_hi:[1,0]
	v_and_b32_e32 v3, 8, v3
	v_cvt_pk_bf16_f32 v141, v4, v5
	s_waitcnt vmcnt(0)
	v_and_b32_e32 v5, 0xffff0000, v16
	v_lshlrev_b32_e32 v4, 16, v16
	v_pk_mul_f32 v[4:5], v[4:5], s[28:29] op_sel_hi:[1,0]
	s_nop 0
	v_cvt_pk_bf16_f32 v142, v4, v5
	v_and_b32_e32 v5, 0xffff0000, v17
	v_lshlrev_b32_e32 v4, 16, v17
	v_pk_mul_f32 v[4:5], v[4:5], s[28:29] op_sel_hi:[1,0]
	s_nop 0
	v_cvt_pk_bf16_f32 v143, v4, v5
	v_and_b32_e32 v5, 0xffff0000, v18
	v_lshlrev_b32_e32 v4, 16, v18
	v_pk_mul_f32 v[4:5], v[4:5], s[28:29] op_sel_hi:[1,0]
	s_nop 0
	v_cvt_pk_bf16_f32 v144, v4, v5
	v_and_b32_e32 v5, 0xffff0000, v19
	v_lshlrev_b32_e32 v4, 16, v19
	v_pk_mul_f32 v[4:5], v[4:5], s[28:29] op_sel_hi:[1,0]
	v_mad_u64_u32 v[28:29], s[28:29], v7, s42, v[6:7]
	v_cvt_pk_bf16_f32 v145, v4, v5
	v_add_u32_e32 v4, s2, v7
	v_ashrrev_i32_e32 v5, 31, v4
	v_lshlrev_b64 v[4:5], 11, v[4:5]
	v_lshl_add_u64 v[4:5], s[8:9], 0, v[4:5]
	v_lshl_add_u64 v[4:5], v[4:5], 0, s[80:81]
	v_mov_b32_e32 v7, v1
	v_lshl_add_u64 v[30:31], v[4:5], 0, v[6:7]
	v_mov_b64_e32 v[4:5], s[10:11]
	v_mad_i64_i32 v[4:5], s[28:29], v9, s68, v[4:5]
	v_lshl_add_u64 v[4:5], s[2:3], 1, v[4:5]
	s_mov_b32 s2, 0x20000
	v_lshlrev_b32_e32 v6, 4, v10
	v_add_co_u32_e32 v8, vcc, s2, v30
	v_lshl_add_u64 v[32:33], v[4:5], 0, v[6:7]
	s_nop 0
	v_addc_co_u32_e32 v9, vcc, 0, v31, vcc
	v_add_co_u32_e32 v34, vcc, s41, v32
	s_mov_b32 s2, 0x220000
	s_nop 0
	v_addc_co_u32_e32 v35, vcc, 0, v33, vcc
	global_load_dwordx4 v[4:7], v[30:31], off offset:128
	v_add_co_u32_e32 v36, vcc, s2, v32
	v_and_b32_e32 v29, 0xe0, v11
	global_load_dwordx4 v[8:11], v[8:9], off offset:128
	s_nop 0
	global_load_dwordx4 v[12:15], v[32:33], off
	v_addc_co_u32_e32 v37, vcc, 0, v33, vcc
	s_mov_b32 s2, 0x330000
	v_add_co_u32_e32 v38, vcc, s2, v32
	global_load_dwordx4 v[16:19], v[34:35], off
	global_load_dwordx4 v[20:23], v[36:37], off
	v_addc_co_u32_e32 v39, vcc, 0, v33, vcc
	global_load_dwordx4 v[24:27], v[38:39], off
	v_add_u32_e32 v202, 0, v28
	s_waitcnt vmcnt(5)
	ds_write_b128 v202, v[4:7]
	s_waitcnt vmcnt(4)
	ds_write_b128 v202, v[8:11] offset:9216
	v_add_u32_e32 v4, 0, v29
	v_add3_u32 v3, v4, v3, v40
	v_add_u32_e32 v4, 0xb000, v3
	v_add_u32_e32 v195, 0x9000, v3
	s_mov_b32 s2, 0x40000
	s_waitcnt vmcnt(3)
	ds_write2_b64 v195, v[12:13], v[14:15] offset1:2
	s_waitcnt vmcnt(2)
	ds_write2_b64 v4, v[16:17], v[18:19] offset0:64 offset1:66
	v_add_u32_e32 v4, 0xd000, v3
	v_add_u32_e32 v3, 0xf000, v3
	s_waitcnt vmcnt(1)
	ds_write2_b64 v4, v[20:21], v[22:23] offset0:128 offset1:130
	s_waitcnt vmcnt(0)
	ds_write2_b64 v3, v[24:25], v[26:27] offset0:192 offset1:194
	v_mad_u32_u24 v3, v2, s42, 0
	v_add_u32_e32 v194, v3, v0
	v_lshl_add_u32 v203, v2, 7, v194
	v_add_co_u32_e32 v2, vcc, s2, v30
	s_mov_b32 s2, 0x60000
	s_nop 0
	v_addc_co_u32_e32 v3, vcc, 0, v31, vcc
	s_waitcnt lgkmcnt(0)
	s_barrier
	global_load_dwordx4 v[106:109], v[2:3], off offset:128
	v_add_co_u32_e32 v2, vcc, s2, v30
	s_nop 1
	v_addc_co_u32_e32 v3, vcc, 0, v31, vcc
	global_load_dwordx4 v[118:121], v[2:3], off offset:128
	global_load_dwordx4 v[114:117], v[32:33], off offset:256
	global_load_dwordx4 v[110:113], v[34:35], off offset:256
	global_load_dwordx4 v[102:105], v[36:37], off offset:256
	global_load_dwordx4 v[98:101], v[38:39], off offset:256
	ds_read_b128 v[2:5], v194 offset:4608
	ds_read_b128 v[6:9], v194
	ds_read_b128 v[34:37], v194 offset:32
	ds_read_b128 v[38:41], v194 offset:4640
	ds_read_b128 v[42:45], v194 offset:64
	ds_read_b128 v[46:49], v194 offset:4672
	ds_read_b128 v[50:53], v194 offset:96
	ds_read_b128 v[54:57], v194 offset:4704
	s_waitcnt lgkmcnt(6)
	v_mfma_f32_32x32x16_bf16 v[18:33], v[6:9], v[130:133], 0
	v_mfma_f32_32x32x16_bf16 v[2:17], v[2:5], v[130:133], 0
	s_waitcnt lgkmcnt(5)
	v_mfma_f32_32x32x16_bf16 v[18:33], v[34:37], v[134:137], v[18:33]
	s_waitcnt lgkmcnt(4)
	v_mfma_f32_32x32x16_bf16 v[2:17], v[38:41], v[134:137], v[2:17]
	s_waitcnt lgkmcnt(3)
	v_mfma_f32_32x32x16_bf16 v[18:33], v[42:45], v[138:141], v[18:33]
	s_waitcnt lgkmcnt(2)
	v_mfma_f32_32x32x16_bf16 v[2:17], v[46:49], v[138:141], v[2:17]
	s_waitcnt lgkmcnt(1)
	v_mfma_f32_32x32x16_bf16 v[18:33], v[50:53], v[142:145], v[18:33]
	s_waitcnt lgkmcnt(0)
	v_mfma_f32_32x32x16_bf16 v[2:17], v[54:57], v[142:145], v[2:17]
	ds_read_b128 v[34:37], v194 offset:9216
	ds_read_b128 v[38:41], v194 offset:9248
	ds_read_b128 v[42:45], v194 offset:13824
	ds_read_b128 v[46:49], v194 offset:13856
	ds_read_b128 v[50:53], v194 offset:9280
	ds_read_b128 v[54:57], v194 offset:9312
	ds_read_b128 v[58:61], v194 offset:13888
	ds_read_b128 v[62:65], v194 offset:13920
	s_waitcnt lgkmcnt(7)
	v_mfma_f32_32x32x16_bf16 v[82:97], v[34:37], v[130:133], 0
	s_waitcnt lgkmcnt(5)
	v_mfma_f32_32x32x16_bf16 v[66:81], v[42:45], v[130:133], 0
	v_mfma_f32_32x32x16_bf16 v[82:97], v[38:41], v[134:137], v[82:97]
	s_waitcnt lgkmcnt(4)
	v_mfma_f32_32x32x16_bf16 v[66:81], v[46:49], v[134:137], v[66:81]
	s_waitcnt lgkmcnt(3)
	v_mfma_f32_32x32x16_bf16 v[82:97], v[50:53], v[138:141], v[82:97]
	s_waitcnt lgkmcnt(1)
	v_mfma_f32_32x32x16_bf16 v[66:81], v[58:61], v[138:141], v[66:81]
	v_mfma_f32_32x32x16_bf16 v[82:97], v[54:57], v[142:145], v[82:97]
	s_waitcnt lgkmcnt(0)
	v_mfma_f32_32x32x16_bf16 v[66:81], v[62:65], v[142:145], v[66:81]
	ds_read_b128 v[34:37], v203 offset:36864
	ds_read_b128 v[38:41], v203 offset:36896
	ds_read_b128 v[42:45], v203 offset:36928
	ds_read_b128 v[46:49], v203 offset:36960
	v_max3_f32 v50, v18, v2, v19
	v_max_f32_e32 v51, v17, v17
	v_max3_f32 v50, v50, v3, v20
	s_mov_b32 s2, 0xf149f2ca
	v_max3_f32 v50, v50, v4, v21
	v_max3_f32 v50, v50, v5, v22
	v_max3_f32 v50, v50, v6, v23
	v_max3_f32 v50, v50, v7, v24
	v_max3_f32 v50, v50, v8, v25
	v_max3_f32 v50, v50, v9, v26
	v_max3_f32 v50, v50, v10, v27
	v_max3_f32 v50, v50, v11, v28
	v_max3_f32 v50, v50, v12, v29
	v_max3_f32 v50, v50, v13, v30
	v_max3_f32 v50, v50, v14, v31
	v_max3_f32 v50, v50, v15, v32
	v_max3_f32 v50, v50, v16, v33
	s_nop 0
	v_max_f32_e32 v50, v50, v50
	v_max_f32_e32 v50, v50, v51
	v_mov_b32_e32 v51, v50
	v_nop
	v_nop
	v_permlane32_swap_b32 v50, v51
	s_nop 0
	v_max3_f32 v158, v50, v51, s2
	v_sub_f32_e32 v2, v2, v158
	v_exp_f32_e32 v161, v2
	v_sub_f32_e32 v2, v19, v158
	v_exp_f32_e32 v162, v2
	v_sub_f32_e32 v2, v3, v158
	v_exp_f32_e32 v163, v2
	v_sub_f32_e32 v2, v20, v158
	v_exp_f32_e32 v164, v2
	v_sub_f32_e32 v2, v4, v158
	v_exp_f32_e32 v165, v2
	v_sub_f32_e32 v2, v21, v158
	v_exp_f32_e32 v166, v2
	v_sub_f32_e32 v2, v5, v158
	v_exp_f32_e32 v167, v2
	v_sub_f32_e32 v2, v22, v158
	v_exp_f32_e32 v168, v2
	v_sub_f32_e32 v2, v6, v158
	v_exp_f32_e32 v169, v2
	v_sub_f32_e32 v2, v23, v158
	v_exp_f32_e32 v170, v2
	v_sub_f32_e32 v2, v7, v158
	v_exp_f32_e32 v171, v2
	v_sub_f32_e32 v2, v24, v158
	v_exp_f32_e32 v172, v2
	v_sub_f32_e32 v2, v8, v158
	v_exp_f32_e32 v173, v2
	v_sub_f32_e32 v2, v25, v158
	v_exp_f32_e32 v174, v2
	v_sub_f32_e32 v2, v9, v158
	v_exp_f32_e32 v175, v2
	v_sub_f32_e32 v2, v26, v158
	v_exp_f32_e32 v176, v2
	v_sub_f32_e32 v2, v10, v158
	v_exp_f32_e32 v177, v2
	v_sub_f32_e32 v2, v27, v158
	v_exp_f32_e32 v178, v2
	v_sub_f32_e32 v2, v11, v158
	v_exp_f32_e32 v179, v2
	v_sub_f32_e32 v2, v28, v158
	v_exp_f32_e32 v180, v2
	v_sub_f32_e32 v2, v12, v158
	v_exp_f32_e32 v181, v2
	v_sub_f32_e32 v2, v29, v158
	v_exp_f32_e32 v182, v2
	v_sub_f32_e32 v2, v13, v158
	v_exp_f32_e32 v183, v2
	v_sub_f32_e32 v2, v30, v158
	v_exp_f32_e32 v184, v2
	v_sub_f32_e32 v2, v14, v158
	v_exp_f32_e32 v185, v2
	v_sub_f32_e32 v2, v31, v158
	v_sub_f32_e32 v50, 0xf149f2ca, v158
	v_exp_f32_e32 v186, v2
	v_sub_f32_e32 v2, v15, v158
	v_exp_f32_e32 v187, v2
	v_sub_f32_e32 v2, v32, v158
	v_exp_f32_e32 v3, v50
	v_exp_f32_e32 v188, v2
	v_sub_f32_e32 v2, v16, v158
	v_exp_f32_e32 v189, v2
	v_sub_f32_e32 v2, v33, v158
	v_sub_f32_e32 v18, v18, v158
	v_exp_f32_e32 v190, v2
	v_sub_f32_e32 v2, v17, v158
	v_exp_f32_e32 v160, v18
	v_exp_f32_e32 v192, v2
	v_cmp_neq_f32_e32 vcc, 1.0, v3
	s_cmp_lg_u64 vcc, 0
	v_mul_f32_e32 v191, 0, v3
	s_cselect_b64 vcc, -1, 0
	v_cndmask_b32_e32 v18, 0, v191, vcc
	v_mov_b32_e32 v19, v18
	v_mov_b32_e32 v20, v18
	v_mov_b32_e32 v21, v18
	v_mov_b32_e32 v22, v18
	v_mov_b32_e32 v23, v18
	v_mov_b32_e32 v24, v18
	v_mov_b32_e32 v25, v18
	v_mov_b32_e32 v26, v18
	v_mov_b32_e32 v27, v18
	v_mov_b32_e32 v28, v18
	v_mov_b32_e32 v29, v18
	v_mov_b32_e32 v30, v18
	v_mov_b32_e32 v31, v18
	v_mov_b32_e32 v32, v18
	v_mov_b32_e32 v33, v18
	v_cvt_pk_bf16_f32 v122, v177, v179
	v_cvt_pk_bf16_f32 v123, v181, v183
	v_cvt_pk_bf16_f32 v124, v185, v187
	v_cvt_pk_bf16_f32 v125, v189, v192
	v_cvt_pk_bf16_f32 v126, v161, v163
	v_cvt_pk_bf16_f32 v127, v165, v167
	v_cvt_pk_bf16_f32 v128, v169, v171
	v_cvt_pk_bf16_f32 v129, v173, v175
	v_cvt_pk_bf16_f32 v146, v176, v178
	v_cvt_pk_bf16_f32 v147, v180, v182
	v_cvt_pk_bf16_f32 v148, v184, v186
	v_cvt_pk_bf16_f32 v149, v188, v190
	v_cvt_pk_bf16_f32 v150, v160, v162
	v_cvt_pk_bf16_f32 v151, v164, v166
	v_cvt_pk_bf16_f32 v152, v168, v170
	v_cvt_pk_bf16_f32 v153, v172, v174
	s_waitcnt lgkmcnt(3)
	s_nop 0
	v_mfma_f32_32x32x16_bf16 v[2:17], v[34:37], v[150:153], v[18:33]
	s_waitcnt lgkmcnt(2)
	v_mfma_f32_32x32x16_bf16 v[2:17], v[38:41], v[146:149], v[2:17]
	s_waitcnt lgkmcnt(1)
	v_mfma_f32_32x32x16_bf16 v[2:17], v[42:45], v[126:129], v[2:17]
	s_waitcnt lgkmcnt(0)
	v_mfma_f32_32x32x16_bf16 v[2:17], v[46:49], v[122:125], v[2:17]
	ds_read_b128 v[34:37], v203 offset:45664
	ds_read_b128 v[38:41], v203 offset:45632
	ds_read_b128 v[42:45], v203 offset:45568
	ds_read_b128 v[46:49], v203 offset:45600
	s_waitcnt lgkmcnt(1)
	v_mfma_f32_32x32x16_bf16 v[50:65], v[42:45], v[150:153], v[18:33]
	ds_read_b128 v[198:201], v203 offset:54368
	ds_read_b128 v[204:207], v203 offset:54336
	ds_read_b128 v[208:211], v203 offset:54272
	ds_read_b128 v[212:215], v203 offset:54304
	s_waitcnt lgkmcnt(4)
	v_mfma_f32_32x32x16_bf16 v[50:65], v[46:49], v[146:149], v[50:65]
	v_mfma_f32_32x32x16_bf16 v[50:65], v[38:41], v[126:129], v[50:65]
	v_mfma_f32_32x32x16_bf16 v[50:65], v[34:37], v[122:125], v[50:65]
	s_waitcnt lgkmcnt(1)
	v_mfma_f32_32x32x16_bf16 v[34:49], v[208:211], v[150:153], v[18:33]
	s_waitcnt lgkmcnt(0)
	v_mfma_f32_32x32x16_bf16 v[34:49], v[212:215], v[146:149], v[34:49]
	v_mfma_f32_32x32x16_bf16 v[34:49], v[204:207], v[126:129], v[34:49]
	v_mfma_f32_32x32x16_bf16 v[34:49], v[198:201], v[122:125], v[34:49]
	ds_read_b128 v[198:201], v203 offset:63072
	ds_read_b128 v[204:207], v203 offset:63040
	ds_read_b128 v[208:211], v203 offset:62976
	ds_read_b128 v[212:215], v203 offset:63008
	s_waitcnt lgkmcnt(1)
	v_mfma_f32_32x32x16_bf16 v[18:33], v[208:211], v[150:153], v[18:33]
	s_waitcnt lgkmcnt(0)
	v_mfma_f32_32x32x16_bf16 v[18:33], v[212:215], v[146:149], v[18:33]
	v_mfma_f32_32x32x16_bf16 v[18:33], v[204:207], v[126:129], v[18:33]
	v_mfma_f32_32x32x16_bf16 v[18:33], v[198:201], v[122:125], v[18:33]
	ds_read_b128 v[150:153], v203 offset:36992
	ds_read_b128 v[146:149], v203 offset:37024
	ds_read_b128 v[122:125], v203 offset:37056
	ds_read_b128 v[126:129], v203 offset:37088
	v_max3_f32 v193, v82, v66, v83
	v_max_f32_e32 v198, v81, v81
	v_max3_f32 v193, v193, v67, v84
	v_max3_f32 v193, v193, v68, v85
	v_max3_f32 v193, v193, v69, v86
	v_max3_f32 v193, v193, v70, v87
	v_max3_f32 v193, v193, v71, v88
	v_max3_f32 v193, v193, v72, v89
	v_max3_f32 v193, v193, v73, v90
	v_max3_f32 v193, v193, v74, v91
	v_max3_f32 v193, v193, v75, v92
	v_max3_f32 v193, v193, v76, v93
	v_max3_f32 v193, v193, v77, v94
	v_max3_f32 v193, v193, v78, v95
	v_max3_f32 v193, v193, v79, v96
	v_max3_f32 v193, v193, v80, v97
	s_nop 0
	v_max_f32_e32 v193, v193, v193
	v_max_f32_e32 v193, v193, v198
	v_mov_b32_e32 v198, v193
	v_nop
	v_nop
	v_permlane32_swap_b32 v193, v198
	s_nop 0
	v_max3_f32 v246, v158, v193, v198
	v_sub_f32_e32 v158, v158, v246
	v_exp_f32_e32 v158, v158
	s_nop 0
	v_cmp_neq_f32_e32 vcc, 1.0, v158
	s_cbranch_vccz .LBB0_167
	v_mul_f32_e32 v16, v158, v16
	v_mul_f32_e32 v17, v158, v17
	v_mul_f32_e32 v14, v158, v14
	v_mul_f32_e32 v15, v158, v15
	v_mul_f32_e32 v12, v158, v12
	v_mul_f32_e32 v13, v158, v13
	v_mul_f32_e32 v10, v158, v10
	v_mul_f32_e32 v11, v158, v11
	v_mul_f32_e32 v8, v158, v8
	v_mul_f32_e32 v9, v158, v9
	v_mul_f32_e32 v6, v158, v6
	v_mul_f32_e32 v7, v158, v7
	v_mul_f32_e32 v4, v158, v4
	v_mul_f32_e32 v5, v158, v5
	v_mul_f32_e32 v2, v158, v2
	v_mul_f32_e32 v3, v158, v3
	v_mul_f32_e32 v64, v158, v64
	v_mul_f32_e32 v65, v158, v65
	v_mul_f32_e32 v62, v158, v62
	v_mul_f32_e32 v63, v158, v63
	v_mul_f32_e32 v60, v158, v60
	v_mul_f32_e32 v61, v158, v61
	v_mul_f32_e32 v58, v158, v58
	v_mul_f32_e32 v59, v158, v59
	v_mul_f32_e32 v56, v158, v56
	v_mul_f32_e32 v57, v158, v57
	v_mul_f32_e32 v54, v158, v54
	v_mul_f32_e32 v55, v158, v55
	v_mul_f32_e32 v52, v158, v52
	v_mul_f32_e32 v53, v158, v53
	v_mul_f32_e32 v50, v158, v50
	v_mul_f32_e32 v51, v158, v51
	v_mul_f32_e32 v48, v158, v48
	v_mul_f32_e32 v49, v158, v49
	v_mul_f32_e32 v46, v158, v46
	v_mul_f32_e32 v47, v158, v47
	v_mul_f32_e32 v44, v158, v44
	v_mul_f32_e32 v45, v158, v45
	v_mul_f32_e32 v42, v158, v42
	v_mul_f32_e32 v43, v158, v43
	v_mul_f32_e32 v40, v158, v40
	v_mul_f32_e32 v41, v158, v41
	v_mul_f32_e32 v38, v158, v38
	v_mul_f32_e32 v39, v158, v39
	v_mul_f32_e32 v36, v158, v36
	v_mul_f32_e32 v37, v158, v37
	v_mul_f32_e32 v34, v158, v34
	v_mul_f32_e32 v35, v158, v35
	v_mul_f32_e32 v32, v158, v32
	v_mul_f32_e32 v33, v158, v33
	v_mul_f32_e32 v30, v158, v30
	v_mul_f32_e32 v31, v158, v31
	v_mul_f32_e32 v28, v158, v28
	v_mul_f32_e32 v29, v158, v29
	v_mul_f32_e32 v26, v158, v26
	v_mul_f32_e32 v27, v158, v27
	v_mul_f32_e32 v24, v158, v24
	v_mul_f32_e32 v25, v158, v25
	v_mul_f32_e32 v22, v158, v22
	v_mul_f32_e32 v23, v158, v23
	v_mul_f32_e32 v20, v158, v20
	v_mul_f32_e32 v21, v158, v21
	v_mul_f32_e32 v18, v158, v18
	v_mul_f32_e32 v19, v158, v19
.LBB0_167:
	v_sub_f32_e32 v66, v66, v246
	v_exp_f32_e32 v205, v66
	v_sub_f32_e32 v66, v83, v246
	v_exp_f32_e32 v206, v66
	v_sub_f32_e32 v66, v67, v246
	v_exp_f32_e32 v207, v66
	v_sub_f32_e32 v66, v84, v246
	v_exp_f32_e32 v208, v66
	v_sub_f32_e32 v66, v68, v246
	v_exp_f32_e32 v209, v66
	v_sub_f32_e32 v66, v85, v246
	v_exp_f32_e32 v220, v66
	v_sub_f32_e32 v66, v69, v246
	v_exp_f32_e32 v221, v66
	v_sub_f32_e32 v66, v86, v246
	v_exp_f32_e32 v222, v66
	v_sub_f32_e32 v66, v70, v246
	v_exp_f32_e32 v223, v66
	v_sub_f32_e32 v66, v87, v246
	v_exp_f32_e32 v224, v66
	v_sub_f32_e32 v66, v71, v246
	v_exp_f32_e32 v225, v66
	v_sub_f32_e32 v66, v88, v246
	v_exp_f32_e32 v226, v66
	v_sub_f32_e32 v66, v72, v246
	v_exp_f32_e32 v227, v66
	v_sub_f32_e32 v66, v89, v246
	v_exp_f32_e32 v228, v66
	v_sub_f32_e32 v66, v73, v246
	v_exp_f32_e32 v229, v66
	v_sub_f32_e32 v66, v90, v246
	v_exp_f32_e32 v230, v66
	v_sub_f32_e32 v66, v74, v246
	v_exp_f32_e32 v231, v66
	v_sub_f32_e32 v66, v91, v246
	v_exp_f32_e32 v232, v66
	v_sub_f32_e32 v66, v75, v246
	v_exp_f32_e32 v233, v66
	v_sub_f32_e32 v66, v92, v246
	v_exp_f32_e32 v234, v66
	v_sub_f32_e32 v66, v76, v246
	v_exp_f32_e32 v235, v66
	v_sub_f32_e32 v66, v93, v246
	v_exp_f32_e32 v236, v66
	v_sub_f32_e32 v66, v77, v246
	v_exp_f32_e32 v237, v66
	v_sub_f32_e32 v66, v94, v246
	v_exp_f32_e32 v238, v66
	v_sub_f32_e32 v66, v78, v246
	v_exp_f32_e32 v239, v66
	v_sub_f32_e32 v66, v95, v246
	v_exp_f32_e32 v240, v66
	v_sub_f32_e32 v66, v79, v246
	v_exp_f32_e32 v241, v66
	v_sub_f32_e32 v66, v96, v246
	v_exp_f32_e32 v242, v66
	v_sub_f32_e32 v66, v80, v246
	v_exp_f32_e32 v243, v66
	v_sub_f32_e32 v66, v97, v246
	v_sub_f32_e32 v82, v82, v246
	v_exp_f32_e32 v244, v66
	v_sub_f32_e32 v66, v81, v246
	v_exp_f32_e32 v204, v82
	v_exp_f32_e32 v245, v66
	v_add_u32_e32 v193, 0x9000, v203
	v_cvt_pk_bf16_f32 v66, v231, v233
	v_cvt_pk_bf16_f32 v67, v235, v237
	v_cvt_pk_bf16_f32 v68, v239, v241
	v_cvt_pk_bf16_f32 v69, v243, v245
	v_cvt_pk_bf16_f32 v70, v205, v207
	v_cvt_pk_bf16_f32 v71, v209, v221
	v_cvt_pk_bf16_f32 v72, v223, v225
	v_cvt_pk_bf16_f32 v73, v227, v229
	v_cvt_pk_bf16_f32 v74, v230, v232
	v_cvt_pk_bf16_f32 v75, v234, v236
	v_cvt_pk_bf16_f32 v76, v238, v240
	v_cvt_pk_bf16_f32 v77, v242, v244
	v_cvt_pk_bf16_f32 v78, v204, v206
	v_cvt_pk_bf16_f32 v79, v208, v220
	v_cvt_pk_bf16_f32 v80, v222, v224
	v_cvt_pk_bf16_f32 v81, v226, v228
	s_waitcnt lgkmcnt(3)
	s_nop 0
	v_mfma_f32_32x32x16_bf16 v[2:17], v[150:153], v[78:81], v[2:17]
	ds_read_b128 v[82:85], v203 offset:45792
	ds_read_b128 v[86:89], v203 offset:45760
	ds_read_b128 v[90:93], v203 offset:45696
	ds_read_b128 v[94:97], v203 offset:45728
	s_waitcnt lgkmcnt(6)
	v_mfma_f32_32x32x16_bf16 v[2:17], v[146:149], v[74:77], v[2:17]
	s_waitcnt lgkmcnt(5)
	v_mfma_f32_32x32x16_bf16 v[2:17], v[122:125], v[70:73], v[2:17]
	s_waitcnt lgkmcnt(4)
	v_mfma_f32_32x32x16_bf16 v[2:17], v[126:129], v[66:69], v[2:17]
	s_waitcnt lgkmcnt(1)
	v_mfma_f32_32x32x16_bf16 v[50:65], v[90:93], v[78:81], v[50:65]
	s_waitcnt lgkmcnt(0)
	v_mfma_f32_32x32x16_bf16 v[50:65], v[94:97], v[74:77], v[50:65]
	v_mfma_f32_32x32x16_bf16 v[50:65], v[86:89], v[70:73], v[50:65]
	v_mfma_f32_32x32x16_bf16 v[50:65], v[82:85], v[66:69], v[50:65]
	ds_read_b128 v[82:85], v203 offset:54496
	ds_read_b128 v[86:89], v203 offset:54464
	ds_read_b128 v[90:93], v203 offset:54400
	ds_read_b128 v[94:97], v203 offset:54432
	s_waitcnt lgkmcnt(1)
	v_mfma_f32_32x32x16_bf16 v[34:49], v[90:93], v[78:81], v[34:49]
	s_waitcnt lgkmcnt(0)
	v_mfma_f32_32x32x16_bf16 v[34:49], v[94:97], v[74:77], v[34:49]
	v_mfma_f32_32x32x16_bf16 v[34:49], v[86:89], v[70:73], v[34:49]
	v_mfma_f32_32x32x16_bf16 v[34:49], v[82:85], v[66:69], v[34:49]
	ds_read_b128 v[82:85], v203 offset:63200
	ds_read_b128 v[86:89], v203 offset:63168
	ds_read_b128 v[90:93], v203 offset:63104
	ds_read_b128 v[94:97], v203 offset:63136
	s_waitcnt lgkmcnt(1)
	v_mfma_f32_32x32x16_bf16 v[18:33], v[90:93], v[78:81], v[18:33]
	s_waitcnt lgkmcnt(0)
	v_mfma_f32_32x32x16_bf16 v[18:33], v[94:97], v[74:77], v[18:33]
	v_mfma_f32_32x32x16_bf16 v[18:33], v[86:89], v[70:73], v[18:33]
	v_mfma_f32_32x32x16_bf16 v[18:33], v[82:85], v[66:69], v[18:33]
	v_add_u32_e32 v66, 0x8800, v195
	s_waitcnt vmcnt(5)
	ds_write_b128 v202, v[106:109] offset:18432
	s_waitcnt vmcnt(4)
	ds_write_b128 v202, v[118:121] offset:27648
	s_waitcnt vmcnt(3)
	ds_write2_b64 v66, v[114:115], v[116:117] offset1:2
	v_add_u32_e32 v66, 0xa800, v195
	s_waitcnt vmcnt(2)
	ds_write2_b64 v66, v[110:111], v[112:113] offset0:64 offset1:66
	v_add_u32_e32 v66, 0xc800, v195
	s_waitcnt vmcnt(1)
	ds_write2_b64 v66, v[102:103], v[104:105] offset0:128 offset1:130
	v_add_u32_e32 v66, 0xe800, v195
	s_waitcnt vmcnt(0)
	ds_write2_b64 v66, v[98:99], v[100:101] offset0:192 offset1:194
	s_waitcnt lgkmcnt(0)
	s_barrier
	ds_read_b128 v[66:69], v194 offset:18432
	ds_read_b128 v[70:73], v194 offset:18464
	ds_read_b128 v[74:77], v194 offset:23040
	ds_read_b128 v[78:81], v194 offset:23072
	ds_read_b128 v[82:85], v194 offset:18496
	ds_read_b128 v[86:89], v194 offset:18528
	ds_read_b128 v[90:93], v194 offset:23104
	ds_read_b128 v[94:97], v194 offset:23136
	s_waitcnt lgkmcnt(7)
	v_mfma_f32_32x32x16_bf16 v[114:129], v[66:69], v[130:133], 0
	s_waitcnt lgkmcnt(5)
	v_mfma_f32_32x32x16_bf16 v[98:113], v[74:77], v[130:133], 0
	v_mfma_f32_32x32x16_bf16 v[114:129], v[70:73], v[134:137], v[114:129]
	s_waitcnt lgkmcnt(4)
	v_mfma_f32_32x32x16_bf16 v[98:113], v[78:81], v[134:137], v[98:113]
	s_waitcnt lgkmcnt(3)
	v_mfma_f32_32x32x16_bf16 v[114:129], v[82:85], v[138:141], v[114:129]
	s_waitcnt lgkmcnt(1)
	v_mfma_f32_32x32x16_bf16 v[98:113], v[90:93], v[138:141], v[98:113]
	v_mfma_f32_32x32x16_bf16 v[114:129], v[86:89], v[142:145], v[114:129]
	s_waitcnt lgkmcnt(0)
	v_mfma_f32_32x32x16_bf16 v[98:113], v[94:97], v[142:145], v[98:113]
	ds_read_b128 v[66:69], v194 offset:27648
	ds_read_b128 v[146:149], v194 offset:27680
	ds_read_b128 v[70:73], v194 offset:32256
	ds_read_b128 v[150:153], v194 offset:32288
	ds_read_b128 v[198:201], v194 offset:27712
	ds_read_b128 v[210:213], v194 offset:27744
	ds_read_b128 v[214:217], v194 offset:32320
	ds_read_b128 v[248:251], v194 offset:32352
	s_waitcnt lgkmcnt(7)
	v_mfma_f32_32x32x16_bf16 v[82:97], v[66:69], v[130:133], 0
	s_waitcnt lgkmcnt(5)
	v_mfma_f32_32x32x16_bf16 v[66:81], v[70:73], v[130:133], 0
	v_mfma_f32_32x32x16_bf16 v[82:97], v[146:149], v[134:137], v[82:97]
	s_waitcnt lgkmcnt(4)
	v_mfma_f32_32x32x16_bf16 v[66:81], v[150:153], v[134:137], v[66:81]
	s_waitcnt lgkmcnt(3)
	v_mfma_f32_32x32x16_bf16 v[82:97], v[198:201], v[138:141], v[82:97]
	s_waitcnt lgkmcnt(1)
	v_mfma_f32_32x32x16_bf16 v[66:81], v[214:217], v[138:141], v[66:81]
	v_mfma_f32_32x32x16_bf16 v[82:97], v[210:213], v[142:145], v[82:97]
	s_waitcnt lgkmcnt(0)
	v_mfma_f32_32x32x16_bf16 v[66:81], v[248:251], v[142:145], v[66:81]
	ds_read_b128 v[142:145], v193 offset:34816
	ds_read_b128 v[138:141], v193 offset:34848
	ds_read_b128 v[130:133], v193 offset:34880
	ds_read_b128 v[134:137], v193 offset:34912
	v_max3_f32 v146, v114, v98, v115
	v_max_f32_e32 v147, v113, v113
	v_max3_f32 v146, v146, v99, v116
	v_max3_f32 v146, v146, v100, v117
	v_max3_f32 v146, v146, v101, v118
	v_max3_f32 v146, v146, v102, v119
	v_max3_f32 v146, v146, v103, v120
	v_max3_f32 v146, v146, v104, v121
	v_max3_f32 v146, v146, v105, v122
	v_max3_f32 v146, v146, v106, v123
	v_max3_f32 v146, v146, v107, v124
	v_max3_f32 v146, v146, v108, v125
	v_max3_f32 v146, v146, v109, v126
	v_max3_f32 v146, v146, v110, v127
	v_max3_f32 v146, v146, v111, v128
	v_max3_f32 v146, v146, v112, v129
	s_nop 0
	v_max_f32_e32 v146, v146, v146
	v_max_f32_e32 v146, v146, v147
	v_mov_b32_e32 v147, v146
	v_nop
	v_nop
	v_permlane32_swap_b32 v146, v147
	s_nop 0
	v_max3_f32 v219, v246, v146, v147
	v_sub_f32_e32 v146, v246, v219
	v_exp_f32_e32 v146, v146
	s_nop 0
	v_cmp_neq_f32_e32 vcc, 1.0, v146
	s_cbranch_vccz .LBB0_169
	v_mul_f32_e32 v16, v146, v16
	v_mul_f32_e32 v17, v146, v17
	v_mul_f32_e32 v14, v146, v14
	v_mul_f32_e32 v15, v146, v15
	v_mul_f32_e32 v12, v146, v12
	v_mul_f32_e32 v13, v146, v13
	v_mul_f32_e32 v10, v146, v10
	v_mul_f32_e32 v11, v146, v11
	v_mul_f32_e32 v8, v146, v8
	v_mul_f32_e32 v9, v146, v9
	v_mul_f32_e32 v6, v146, v6
	v_mul_f32_e32 v7, v146, v7
	v_mul_f32_e32 v4, v146, v4
	v_mul_f32_e32 v5, v146, v5
	v_mul_f32_e32 v2, v146, v2
	v_mul_f32_e32 v3, v146, v3
	v_mul_f32_e32 v64, v146, v64
	v_mul_f32_e32 v65, v146, v65
	v_mul_f32_e32 v62, v146, v62
	v_mul_f32_e32 v63, v146, v63
	v_mul_f32_e32 v60, v146, v60
	v_mul_f32_e32 v61, v146, v61
	v_mul_f32_e32 v58, v146, v58
	v_mul_f32_e32 v59, v146, v59
	v_mul_f32_e32 v56, v146, v56
	v_mul_f32_e32 v57, v146, v57
	v_mul_f32_e32 v54, v146, v54
	v_mul_f32_e32 v55, v146, v55
	v_mul_f32_e32 v52, v146, v52
	v_mul_f32_e32 v53, v146, v53
	v_mul_f32_e32 v50, v146, v50
	v_mul_f32_e32 v51, v146, v51
	v_mul_f32_e32 v48, v146, v48
	v_mul_f32_e32 v49, v146, v49
	v_mul_f32_e32 v46, v146, v46
	v_mul_f32_e32 v47, v146, v47
	v_mul_f32_e32 v44, v146, v44
	v_mul_f32_e32 v45, v146, v45
	v_mul_f32_e32 v42, v146, v42
	v_mul_f32_e32 v43, v146, v43
	v_mul_f32_e32 v40, v146, v40
	v_mul_f32_e32 v41, v146, v41
	v_mul_f32_e32 v38, v146, v38
	v_mul_f32_e32 v39, v146, v39
	v_mul_f32_e32 v36, v146, v36
	v_mul_f32_e32 v37, v146, v37
	v_mul_f32_e32 v34, v146, v34
	v_mul_f32_e32 v35, v146, v35
	v_mul_f32_e32 v32, v146, v32
	v_mul_f32_e32 v33, v146, v33
	v_mul_f32_e32 v30, v146, v30
	v_mul_f32_e32 v31, v146, v31
	v_mul_f32_e32 v28, v146, v28
	v_mul_f32_e32 v29, v146, v29
	v_mul_f32_e32 v26, v146, v26
	v_mul_f32_e32 v27, v146, v27
	v_mul_f32_e32 v24, v146, v24
	v_mul_f32_e32 v25, v146, v25
	v_mul_f32_e32 v22, v146, v22
	v_mul_f32_e32 v23, v146, v23
	v_mul_f32_e32 v20, v146, v20
	v_mul_f32_e32 v21, v146, v21
	v_mul_f32_e32 v18, v146, v18
	v_mul_f32_e32 v19, v146, v19
.LBB0_169:
	v_sub_f32_e32 v98, v98, v219
	v_exp_f32_e32 v148, v98
	v_sub_f32_e32 v98, v115, v219
	v_exp_f32_e32 v149, v98
	v_sub_f32_e32 v98, v99, v219
	v_exp_f32_e32 v150, v98
	v_sub_f32_e32 v98, v116, v219
	v_exp_f32_e32 v151, v98
	v_sub_f32_e32 v98, v100, v219
	v_exp_f32_e32 v152, v98
	v_sub_f32_e32 v98, v117, v219
	v_exp_f32_e32 v117, v98
	v_sub_f32_e32 v98, v101, v219
	v_exp_f32_e32 v153, v98
	v_sub_f32_e32 v98, v118, v219
	v_exp_f32_e32 v118, v98
	v_sub_f32_e32 v98, v102, v219
	v_exp_f32_e32 v194, v98
	v_sub_f32_e32 v98, v119, v219
	v_exp_f32_e32 v119, v98
	v_sub_f32_e32 v98, v103, v219
	v_exp_f32_e32 v195, v98
	v_sub_f32_e32 v98, v120, v219
	v_exp_f32_e32 v120, v98
	v_sub_f32_e32 v98, v104, v219
	v_exp_f32_e32 v202, v98
	v_sub_f32_e32 v98, v121, v219
	v_exp_f32_e32 v121, v98
	v_sub_f32_e32 v98, v105, v219
	v_exp_f32_e32 v203, v98
	v_sub_f32_e32 v98, v122, v219
	v_exp_f32_e32 v122, v98
	v_sub_f32_e32 v98, v106, v219
	v_exp_f32_e32 v246, v98
	v_sub_f32_e32 v98, v123, v219
	v_exp_f32_e32 v123, v98
	v_sub_f32_e32 v98, v107, v219
	v_exp_f32_e32 v247, v98
	v_sub_f32_e32 v98, v124, v219
	v_exp_f32_e32 v124, v98
	v_sub_f32_e32 v98, v108, v219
	v_exp_f32_e32 v248, v98
	v_sub_f32_e32 v98, v125, v219
	v_exp_f32_e32 v125, v98
	v_sub_f32_e32 v98, v109, v219
	v_exp_f32_e32 v249, v98
	v_sub_f32_e32 v98, v126, v219
	v_exp_f32_e32 v126, v98
	v_sub_f32_e32 v98, v110, v219
	v_exp_f32_e32 v250, v98
	v_sub_f32_e32 v98, v127, v219
	v_exp_f32_e32 v127, v98
	v_sub_f32_e32 v98, v111, v219
	v_exp_f32_e32 v251, v98
	v_sub_f32_e32 v98, v128, v219
	v_exp_f32_e32 v128, v98
	v_sub_f32_e32 v98, v112, v219
	v_exp_f32_e32 v252, v98
	v_sub_f32_e32 v98, v129, v219
	v_sub_f32_e32 v114, v114, v219
	v_exp_f32_e32 v129, v98
	v_sub_f32_e32 v98, v113, v219
	v_exp_f32_e32 v147, v114
	v_exp_f32_e32 v253, v98
	v_cvt_pk_bf16_f32 v98, v246, v247
	v_cvt_pk_bf16_f32 v99, v248, v249
	v_cvt_pk_bf16_f32 v100, v250, v251
	v_cvt_pk_bf16_f32 v101, v252, v253
	v_cvt_pk_bf16_f32 v102, v148, v150
	v_cvt_pk_bf16_f32 v103, v152, v153
	v_cvt_pk_bf16_f32 v104, v194, v195
	v_cvt_pk_bf16_f32 v105, v202, v203
	v_cvt_pk_bf16_f32 v106, v122, v123
	v_cvt_pk_bf16_f32 v107, v124, v125
	v_cvt_pk_bf16_f32 v108, v126, v127
	v_cvt_pk_bf16_f32 v109, v128, v129
	v_cvt_pk_bf16_f32 v110, v147, v149
	v_cvt_pk_bf16_f32 v111, v151, v117
	v_cvt_pk_bf16_f32 v112, v118, v119
	v_cvt_pk_bf16_f32 v113, v120, v121
	s_waitcnt lgkmcnt(3)
	s_nop 0
	v_mfma_f32_32x32x16_bf16 v[2:17], v[142:145], v[110:113], v[2:17]
	s_waitcnt lgkmcnt(2)
	v_mfma_f32_32x32x16_bf16 v[2:17], v[138:141], v[106:109], v[2:17]
	s_waitcnt lgkmcnt(1)
	v_mfma_f32_32x32x16_bf16 v[2:17], v[130:133], v[102:105], v[2:17]
	s_waitcnt lgkmcnt(0)
	v_mfma_f32_32x32x16_bf16 v[2:17], v[134:137], v[98:101], v[2:17]
	ds_read_b128 v[130:133], v193 offset:43616
	ds_read_b128 v[134:137], v193 offset:43584
	ds_read_b128 v[138:141], v193 offset:43520
	ds_read_b128 v[142:145], v193 offset:43552
	s_waitcnt lgkmcnt(1)
	v_mfma_f32_32x32x16_bf16 v[50:65], v[138:141], v[110:113], v[50:65]
	s_waitcnt lgkmcnt(0)
	v_mfma_f32_32x32x16_bf16 v[50:65], v[142:145], v[106:109], v[50:65]
	v_mfma_f32_32x32x16_bf16 v[50:65], v[134:137], v[102:105], v[50:65]
	v_mfma_f32_32x32x16_bf16 v[50:65], v[130:133], v[98:101], v[50:65]
	ds_read_b128 v[130:133], v193 offset:52320
	ds_read_b128 v[134:137], v193 offset:52288
	ds_read_b128 v[138:141], v193 offset:52224
	ds_read_b128 v[142:145], v193 offset:52256
	s_waitcnt lgkmcnt(1)
	v_mfma_f32_32x32x16_bf16 v[34:49], v[138:141], v[110:113], v[34:49]
	s_waitcnt lgkmcnt(0)
	v_mfma_f32_32x32x16_bf16 v[34:49], v[142:145], v[106:109], v[34:49]
	v_mfma_f32_32x32x16_bf16 v[34:49], v[134:137], v[102:105], v[34:49]
	v_mfma_f32_32x32x16_bf16 v[34:49], v[130:133], v[98:101], v[34:49]
	ds_read_b128 v[130:133], v193 offset:61024
	ds_read_b128 v[134:137], v193 offset:60992
	ds_read_b128 v[138:141], v193 offset:60928
	ds_read_b128 v[142:145], v193 offset:60960
	s_waitcnt lgkmcnt(1)
	v_mfma_f32_32x32x16_bf16 v[18:33], v[138:141], v[110:113], v[18:33]
	s_waitcnt lgkmcnt(0)
	v_mfma_f32_32x32x16_bf16 v[18:33], v[142:145], v[106:109], v[18:33]
	v_mfma_f32_32x32x16_bf16 v[18:33], v[134:137], v[102:105], v[18:33]
	v_mfma_f32_32x32x16_bf16 v[18:33], v[130:133], v[98:101], v[18:33]
	ds_read_b128 v[110:113], v193 offset:34944
	ds_read_b128 v[106:109], v193 offset:34976
	ds_read_b128 v[98:101], v193 offset:35008
	ds_read_b128 v[102:105], v193 offset:35040
	v_max3_f32 v114, v82, v66, v83
	v_max_f32_e32 v115, v81, v81
	v_max3_f32 v114, v114, v67, v84
	v_max3_f32 v114, v114, v68, v85
	v_max3_f32 v114, v114, v69, v86
	v_max3_f32 v114, v114, v70, v87
	v_max3_f32 v114, v114, v71, v88
	v_max3_f32 v114, v114, v72, v89
	v_max3_f32 v114, v114, v73, v90
	v_max3_f32 v114, v114, v74, v91
	v_max3_f32 v114, v114, v75, v92
	v_max3_f32 v114, v114, v76, v93
	v_max3_f32 v114, v114, v77, v94
	v_max3_f32 v114, v114, v78, v95
	v_max3_f32 v114, v114, v79, v96
	v_max3_f32 v114, v114, v80, v97
	s_nop 0
	v_max_f32_e32 v114, v114, v114
	v_max_f32_e32 v114, v114, v115
	v_mov_b32_e32 v115, v114
	v_nop
	v_nop
	v_permlane32_swap_b32 v114, v115
	s_nop 0
	v_max3_f32 v130, v219, v114, v115
	v_sub_f32_e32 v114, v219, v130
	v_exp_f32_e32 v116, v114
	s_nop 0
	v_cmp_neq_f32_e32 vcc, 1.0, v116
	s_cbranch_vccz .LBB0_158
	v_mul_f32_e32 v16, v116, v16
	v_mul_f32_e32 v17, v116, v17
	v_mul_f32_e32 v14, v116, v14
	v_mul_f32_e32 v15, v116, v15
	v_mul_f32_e32 v12, v116, v12
	v_mul_f32_e32 v13, v116, v13
	v_mul_f32_e32 v10, v116, v10
	v_mul_f32_e32 v11, v116, v11
	v_mul_f32_e32 v8, v116, v8
	v_mul_f32_e32 v9, v116, v9
	v_mul_f32_e32 v6, v116, v6
	v_mul_f32_e32 v7, v116, v7
	v_mul_f32_e32 v4, v116, v4
	v_mul_f32_e32 v5, v116, v5
	v_mul_f32_e32 v2, v116, v2
	v_mul_f32_e32 v3, v116, v3
	v_mul_f32_e32 v64, v116, v64
	v_mul_f32_e32 v65, v116, v65
	v_mul_f32_e32 v62, v116, v62
	v_mul_f32_e32 v63, v116, v63
	v_mul_f32_e32 v60, v116, v60
	v_mul_f32_e32 v61, v116, v61
	v_mul_f32_e32 v58, v116, v58
	v_mul_f32_e32 v59, v116, v59
	v_mul_f32_e32 v56, v116, v56
	v_mul_f32_e32 v57, v116, v57
	v_mul_f32_e32 v54, v116, v54
	v_mul_f32_e32 v55, v116, v55
	v_mul_f32_e32 v52, v116, v52
	v_mul_f32_e32 v53, v116, v53
	v_mul_f32_e32 v50, v116, v50
	v_mul_f32_e32 v51, v116, v51
	v_mul_f32_e32 v48, v116, v48
	v_mul_f32_e32 v49, v116, v49
	v_mul_f32_e32 v46, v116, v46
	v_mul_f32_e32 v47, v116, v47
	v_mul_f32_e32 v44, v116, v44
	v_mul_f32_e32 v45, v116, v45
	v_mul_f32_e32 v42, v116, v42
	v_mul_f32_e32 v43, v116, v43
	v_mul_f32_e32 v40, v116, v40
	v_mul_f32_e32 v41, v116, v41
	v_mul_f32_e32 v38, v116, v38
	v_mul_f32_e32 v39, v116, v39
	v_mul_f32_e32 v36, v116, v36
	v_mul_f32_e32 v37, v116, v37
	v_mul_f32_e32 v34, v116, v34
	v_mul_f32_e32 v35, v116, v35
	v_mul_f32_e32 v32, v116, v32
	v_mul_f32_e32 v33, v116, v33
	v_mul_f32_e32 v30, v116, v30
	v_mul_f32_e32 v31, v116, v31
	v_mul_f32_e32 v28, v116, v28
	v_mul_f32_e32 v29, v116, v29
	v_mul_f32_e32 v26, v116, v26
	v_mul_f32_e32 v27, v116, v27
	v_mul_f32_e32 v24, v116, v24
	v_mul_f32_e32 v25, v116, v25
	v_mul_f32_e32 v22, v116, v22
	v_mul_f32_e32 v23, v116, v23
	v_mul_f32_e32 v20, v116, v20
	v_mul_f32_e32 v21, v116, v21
	v_mul_f32_e32 v18, v116, v18
	v_mul_f32_e32 v19, v116, v19
	s_branch .LBB0_158

.LBB0_186:
	s_or_b64 exec, exec, s[0:1]
	global_load_dwordx4 v[2:5], v[204:205], off
	s_and_b32 s0, s4, 1
	s_mul_i32 s1, s0, 0x3400
	v_add_u32_e32 v10, s1, v225
	ds_read_b128 v[12:15], v10 offset:6656
	ds_read_b128 v[80:83], v10
	ds_read_b128 v[230:233], v10 offset:32
	s_waitcnt lgkmcnt(2)
	v_mfma_f32_32x32x16_bf16 v[112:127], v[12:15], v[160:163], 0
	s_waitcnt lgkmcnt(1)
	v_mfma_f32_32x32x16_bf16 v[128:143], v[80:83], v[160:163], 0
	v_mfma_f32_32x32x16_bf16 v[96:111], v[80:83], v[188:191], 0
	v_mfma_f32_32x32x16_bf16 v[80:95], v[12:15], v[188:191], 0
	ds_read_b128 v[12:15], v10 offset:6688
	s_waitcnt lgkmcnt(1)
	v_mfma_f32_32x32x16_bf16 v[128:143], v[230:233], v[156:159], v[128:143]
	s_waitcnt lgkmcnt(0)
	v_mfma_f32_32x32x16_bf16 v[112:127], v[12:15], v[156:159], v[112:127]
	v_mfma_f32_32x32x16_bf16 v[96:111], v[230:233], v[184:187], v[96:111]
	v_mfma_f32_32x32x16_bf16 v[80:95], v[12:15], v[184:187], v[80:95]
	ds_read_b128 v[12:15], v10 offset:64
	ds_read_b128 v[230:233], v10 offset:6720
	s_waitcnt lgkmcnt(1)
	v_mfma_f32_32x32x16_bf16 v[128:143], v[12:15], v[164:167], v[128:143]
	s_waitcnt lgkmcnt(0)
	v_mfma_f32_32x32x16_bf16 v[112:127], v[230:233], v[164:167], v[112:127]
	v_mfma_f32_32x32x16_bf16 v[96:111], v[12:15], v[192:195], v[96:111]
	v_mfma_f32_32x32x16_bf16 v[80:95], v[230:233], v[192:195], v[80:95]
	ds_read_b128 v[12:15], v10 offset:96
	ds_read_b128 v[230:233], v10 offset:6752
	s_waitcnt lgkmcnt(1)
	v_mfma_f32_32x32x16_bf16 v[128:143], v[12:15], v[152:155], v[128:143]
	s_waitcnt lgkmcnt(0)
	v_mfma_f32_32x32x16_bf16 v[112:127], v[230:233], v[152:155], v[112:127]
	v_mfma_f32_32x32x16_bf16 v[96:111], v[12:15], v[180:183], v[96:111]
	v_mfma_f32_32x32x16_bf16 v[80:95], v[230:233], v[180:183], v[80:95]
	ds_read_b128 v[12:15], v10 offset:128
	ds_read_b128 v[230:233], v10 offset:6784
	s_waitcnt lgkmcnt(1)
	v_mfma_f32_32x32x16_bf16 v[128:143], v[12:15], v[168:171], v[128:143]
	s_waitcnt lgkmcnt(0)
	v_mfma_f32_32x32x16_bf16 v[112:127], v[230:233], v[168:171], v[112:127]
	v_mfma_f32_32x32x16_bf16 v[96:111], v[12:15], v[176:179], v[96:111]
	v_mfma_f32_32x32x16_bf16 v[80:95], v[230:233], v[176:179], v[80:95]
	ds_read_b128 v[12:15], v10 offset:160
	ds_read_b128 v[230:233], v10 offset:6816
	s_waitcnt lgkmcnt(1)
	v_mfma_f32_32x32x16_bf16 v[128:143], v[12:15], v[148:151], v[128:143]
	s_waitcnt lgkmcnt(0)
	v_mfma_f32_32x32x16_bf16 v[112:127], v[230:233], v[148:151], v[112:127]
	v_max3_f32 v10, v128, v112, v129
	v_max3_f32 v10, v10, v113, v130
	v_max3_f32 v10, v10, v114, v131
	v_max3_f32 v10, v10, v115, v132
	v_mfma_f32_32x32x16_bf16 v[96:111], v[12:15], v[172:175], v[96:111]
	v_max3_f32 v10, v10, v116, v133
	s_nop 7
	v_max_f32_e32 v12, v127, v127
	v_max3_f32 v10, v10, v117, v134
	v_max3_f32 v10, v10, v118, v135
	v_max3_f32 v10, v10, v119, v136
	v_mfma_f32_32x32x16_bf16 v[80:95], v[230:233], v[172:175], v[80:95]
	v_max3_f32 v10, v10, v120, v137
	v_max3_f32 v10, v10, v121, v138
	v_max3_f32 v10, v10, v122, v139
	v_max3_f32 v10, v10, v123, v140
	v_max3_f32 v10, v10, v124, v141
	v_max3_f32 v10, v10, v125, v142
	v_max3_f32 v10, v10, v126, v143
	s_nop 0
	v_max_f32_e32 v10, v10, v10
	v_max_f32_e32 v10, v10, v12
	v_mov_b32_e32 v12, v10
	v_nop
	v_nop
	v_permlane32_swap_b32 v12, v10
	s_nop 0
	v_max3_f32 v12, v0, v12, v10
	v_sub_f32_e32 v0, v0, v12
	v_exp_f32_e32 v0, v0
	s_nop 0
	v_cmp_neq_f32_e32 vcc, 1.0, v0
	s_cbranch_vccz .LBB0_188
	v_mul_f32_e32 v78, v0, v78
	v_mul_f32_e32 v79, v0, v79
	v_mul_f32_e32 v76, v0, v76
	v_mul_f32_e32 v77, v0, v77
	v_mul_f32_e32 v74, v0, v74
	v_mul_f32_e32 v75, v0, v75
	v_mul_f32_e32 v72, v0, v72
	v_mul_f32_e32 v73, v0, v73
	v_mul_f32_e32 v70, v0, v70
	v_mul_f32_e32 v71, v0, v71
	v_mul_f32_e32 v68, v0, v68
	v_mul_f32_e32 v69, v0, v69
	v_mul_f32_e32 v66, v0, v66
	v_mul_f32_e32 v67, v0, v67
	v_mul_f32_e32 v64, v0, v64
	v_mul_f32_e32 v65, v0, v65
	v_mul_f32_e32 v62, v0, v62
	v_mul_f32_e32 v63, v0, v63
	v_mul_f32_e32 v60, v0, v60
	v_mul_f32_e32 v61, v0, v61
	v_mul_f32_e32 v58, v0, v58
	v_mul_f32_e32 v59, v0, v59
	v_mul_f32_e32 v56, v0, v56
	v_mul_f32_e32 v57, v0, v57
	v_mul_f32_e32 v54, v0, v54
	v_mul_f32_e32 v55, v0, v55
	v_mul_f32_e32 v52, v0, v52
	v_mul_f32_e32 v53, v0, v53
	v_mul_f32_e32 v50, v0, v50
	v_mul_f32_e32 v51, v0, v51
	v_mul_f32_e32 v48, v0, v48
	v_mul_f32_e32 v49, v0, v49
.LBB0_188:
	v_max3_f32 v10, v96, v80, v97
	v_max_f32_e32 v13, v95, v95
	v_max3_f32 v10, v10, v81, v98
	v_max3_f32 v10, v10, v82, v99
	v_max3_f32 v10, v10, v83, v100
	v_max3_f32 v10, v10, v84, v101
	v_max3_f32 v10, v10, v85, v102
	v_max3_f32 v10, v10, v86, v103
	v_max3_f32 v10, v10, v87, v104
	v_max3_f32 v10, v10, v88, v105
	v_max3_f32 v10, v10, v89, v106
	v_max3_f32 v10, v10, v90, v107
	v_max3_f32 v10, v10, v91, v108
	v_max3_f32 v10, v10, v92, v109
	v_max3_f32 v10, v10, v93, v110
	v_max3_f32 v10, v10, v94, v111
	s_nop 0
	v_max_f32_e32 v10, v10, v10
	v_max_f32_e32 v10, v10, v13
	v_mov_b32_e32 v13, v10
	v_nop
	v_nop
	v_permlane32_swap_b32 v10, v13
	s_nop 0
	v_max3_f32 v13, v228, v10, v13
	v_sub_f32_e32 v10, v228, v13
	v_exp_f32_e32 v10, v10
	s_nop 0
	v_cmp_neq_f32_e32 vcc, 1.0, v10
	s_cbranch_vccz .LBB0_190
	v_mul_f32_e32 v46, v10, v46
	v_mul_f32_e32 v47, v10, v47
	v_mul_f32_e32 v44, v10, v44
	v_mul_f32_e32 v45, v10, v45
	v_mul_f32_e32 v42, v10, v42
	v_mul_f32_e32 v43, v10, v43
	v_mul_f32_e32 v40, v10, v40
	v_mul_f32_e32 v41, v10, v41
	v_mul_f32_e32 v38, v10, v38
	v_mul_f32_e32 v39, v10, v39
	v_mul_f32_e32 v36, v10, v36
	v_mul_f32_e32 v37, v10, v37
	v_mul_f32_e32 v34, v10, v34
	v_mul_f32_e32 v35, v10, v35
	v_mul_f32_e32 v32, v10, v32
	v_mul_f32_e32 v33, v10, v33
	v_mul_f32_e32 v30, v10, v30
	v_mul_f32_e32 v31, v10, v31
	v_mul_f32_e32 v28, v10, v28
	v_mul_f32_e32 v29, v10, v29
	v_mul_f32_e32 v26, v10, v26
	v_mul_f32_e32 v27, v10, v27
	v_mul_f32_e32 v24, v10, v24
	v_mul_f32_e32 v25, v10, v25
	v_mul_f32_e32 v22, v10, v22
	v_mul_f32_e32 v23, v10, v23
	v_mul_f32_e32 v20, v10, v20
	v_mul_f32_e32 v21, v10, v21
	v_mul_f32_e32 v18, v10, v18
	v_mul_f32_e32 v19, v10, v19
	v_mul_f32_e32 v16, v10, v16
	v_mul_f32_e32 v17, v10, v17

.Lmla_stag_out:
	ds_read_b128 v[2:5], v225 offset:13312
	ds_read_b128 v[144:147], v225 offset:13472
	ds_read_b128 v[6:9], v225 offset:19968
	s_waitcnt lgkmcnt(2)
	v_mfma_f32_32x32x16_bf16 v[80:95], v[2:5], v[160:163], 0
	v_mfma_f32_32x32x16_bf16 v[112:127], v[2:5], v[188:191], 0
	ds_read_b128 v[2:5], v225 offset:13344
	s_waitcnt lgkmcnt(1)
	v_mfma_f32_32x32x16_bf16 v[96:111], v[6:9], v[160:163], 0
	v_mfma_f32_32x32x16_bf16 v[128:143], v[6:9], v[188:191], 0
	ds_read_b128 v[6:9], v225 offset:20000
	s_waitcnt lgkmcnt(1)
	v_mfma_f32_32x32x16_bf16 v[80:95], v[2:5], v[156:159], v[80:95]
	v_mfma_f32_32x32x16_bf16 v[112:127], v[2:5], v[184:187], v[112:127]
	ds_read_b128 v[2:5], v225 offset:13376
	s_waitcnt lgkmcnt(1)
	v_mfma_f32_32x32x16_bf16 v[96:111], v[6:9], v[156:159], v[96:111]
	v_mfma_f32_32x32x16_bf16 v[128:143], v[6:9], v[184:187], v[128:143]
	ds_read_b128 v[6:9], v225 offset:20032
	s_waitcnt lgkmcnt(1)
	v_mfma_f32_32x32x16_bf16 v[80:95], v[2:5], v[164:167], v[80:95]
	v_mfma_f32_32x32x16_bf16 v[112:127], v[2:5], v[192:195], v[112:127]
	ds_read_b128 v[2:5], v225 offset:13408
	s_waitcnt lgkmcnt(1)
	v_mfma_f32_32x32x16_bf16 v[96:111], v[6:9], v[164:167], v[96:111]
	v_mfma_f32_32x32x16_bf16 v[128:143], v[6:9], v[192:195], v[128:143]
	ds_read_b128 v[6:9], v225 offset:20064
	s_waitcnt lgkmcnt(1)
	v_mfma_f32_32x32x16_bf16 v[80:95], v[2:5], v[152:155], v[80:95]
	v_mfma_f32_32x32x16_bf16 v[112:127], v[2:5], v[180:183], v[112:127]
	ds_read_b128 v[2:5], v225 offset:13440
	s_waitcnt lgkmcnt(1)
	v_mfma_f32_32x32x16_bf16 v[96:111], v[6:9], v[152:155], v[96:111]
	ds_read_b128 v[152:155], v225 offset:20128
	v_mfma_f32_32x32x16_bf16 v[128:143], v[6:9], v[180:183], v[128:143]
	ds_read_b128 v[6:9], v225 offset:20096
	s_waitcnt lgkmcnt(2)
	v_mfma_f32_32x32x16_bf16 v[80:95], v[2:5], v[168:171], v[80:95]
	s_waitcnt lgkmcnt(0)
	v_mfma_f32_32x32x16_bf16 v[96:111], v[6:9], v[168:171], v[96:111]
	v_mfma_f32_32x32x16_bf16 v[80:95], v[144:147], v[148:151], v[80:95]
	v_mfma_f32_32x32x16_bf16 v[96:111], v[152:155], v[148:151], v[96:111]
	v_max3_f32 v0, v80, v96, v81
	v_max3_f32 v0, v0, v97, v82
	v_max3_f32 v0, v0, v98, v83
	v_max3_f32 v0, v0, v99, v84
	v_mfma_f32_32x32x16_bf16 v[112:127], v[2:5], v[176:179], v[112:127]
	v_max3_f32 v0, v0, v100, v85
	s_nop 7
	v_max_f32_e32 v2, v111, v111
	v_max3_f32 v0, v0, v101, v86
	v_max3_f32 v0, v0, v102, v87
	v_max3_f32 v0, v0, v103, v88
	v_mfma_f32_32x32x16_bf16 v[128:143], v[6:9], v[176:179], v[128:143]
	v_max3_f32 v0, v0, v104, v89
	v_max3_f32 v0, v0, v105, v90
	v_max3_f32 v0, v0, v106, v91
	v_max3_f32 v0, v0, v107, v92
	v_mfma_f32_32x32x16_bf16 v[112:127], v[144:147], v[172:175], v[112:127]
	v_max3_f32 v0, v0, v108, v93
	v_max3_f32 v0, v0, v109, v94
	v_max3_f32 v0, v0, v110, v95
	s_nop 0
	v_max_f32_e32 v0, v0, v0
	v_max_f32_e32 v0, v0, v2
	v_mov_b32_e32 v2, v0
	v_mfma_f32_32x32x16_bf16 v[128:143], v[152:155], v[172:175], v[128:143]
	v_nop
	v_nop
	v_permlane32_swap_b32 v0, v2
	s_nop 0
	v_max3_f32 v147, v12, v0, v2
	v_sub_f32_e32 v0, v12, v147
	v_exp_f32_e32 v14, v0
	s_nop 0
	v_cmp_neq_f32_e32 vcc, 1.0, v14
	s_cbranch_vccz .LBB0_195
	v_mul_f32_e32 v78, v14, v78
	v_mul_f32_e32 v79, v14, v79
	v_mul_f32_e32 v76, v14, v76
	v_mul_f32_e32 v77, v14, v77
	v_mul_f32_e32 v74, v14, v74
	v_mul_f32_e32 v75, v14, v75
	v_mul_f32_e32 v72, v14, v72
	v_mul_f32_e32 v73, v14, v73
	v_mul_f32_e32 v70, v14, v70
	v_mul_f32_e32 v71, v14, v71
	v_mul_f32_e32 v68, v14, v68
	v_mul_f32_e32 v69, v14, v69
	v_mul_f32_e32 v66, v14, v66
	v_mul_f32_e32 v67, v14, v67
	v_mul_f32_e32 v64, v14, v64
	v_mul_f32_e32 v65, v14, v65
	v_mul_f32_e32 v62, v14, v62
	v_mul_f32_e32 v63, v14, v63
	v_mul_f32_e32 v60, v14, v60
	v_mul_f32_e32 v61, v14, v61
	v_mul_f32_e32 v58, v14, v58
	v_mul_f32_e32 v59, v14, v59
	v_mul_f32_e32 v56, v14, v56
	v_mul_f32_e32 v57, v14, v57
	v_mul_f32_e32 v54, v14, v54
	v_mul_f32_e32 v55, v14, v55
	v_mul_f32_e32 v52, v14, v52
	v_mul_f32_e32 v53, v14, v53
	v_mul_f32_e32 v50, v14, v50
	v_mul_f32_e32 v51, v14, v51
	v_mul_f32_e32 v48, v14, v48
	v_mul_f32_e32 v49, v14, v49
.LBB0_195:
	v_max3_f32 v0, v112, v128, v113
	v_max_f32_e32 v2, v143, v143
	v_max3_f32 v0, v0, v129, v114
	v_max3_f32 v0, v0, v130, v115
	v_max3_f32 v0, v0, v131, v116
	v_max3_f32 v0, v0, v132, v117
	v_max3_f32 v0, v0, v133, v118
	v_max3_f32 v0, v0, v134, v119
	v_max3_f32 v0, v0, v135, v120
	v_max3_f32 v0, v0, v136, v121
	v_max3_f32 v0, v0, v137, v122
	v_max3_f32 v0, v0, v138, v123
	v_max3_f32 v0, v0, v139, v124
	v_max3_f32 v0, v0, v140, v125
	v_max3_f32 v0, v0, v141, v126
	v_max3_f32 v0, v0, v142, v127
	s_nop 0
	v_max_f32_e32 v0, v0, v0
	v_max_f32_e32 v0, v0, v2
	v_mov_b32_e32 v2, v0
	v_nop
	v_nop
	v_permlane32_swap_b32 v2, v0
	s_nop 0
	v_max3_f32 v2, v13, v2, v0
	v_sub_f32_e32 v0, v13, v2
	v_exp_f32_e32 v144, v0
	s_nop 0
	v_cmp_neq_f32_e32 vcc, 1.0, v144
	s_cbranch_vccz .LBB0_176
	v_mul_f32_e32 v46, v144, v46
	v_mul_f32_e32 v47, v144, v47
	v_mul_f32_e32 v44, v144, v44
	v_mul_f32_e32 v45, v144, v45
	v_mul_f32_e32 v42, v144, v42
	v_mul_f32_e32 v43, v144, v43
	v_mul_f32_e32 v40, v144, v40
	v_mul_f32_e32 v41, v144, v41
	v_mul_f32_e32 v38, v144, v38
	v_mul_f32_e32 v39, v144, v39
	v_mul_f32_e32 v36, v144, v36
	v_mul_f32_e32 v37, v144, v37
	v_mul_f32_e32 v34, v144, v34
	v_mul_f32_e32 v35, v144, v35
	v_mul_f32_e32 v32, v144, v32
	v_mul_f32_e32 v33, v144, v33
	v_mul_f32_e32 v30, v144, v30
	v_mul_f32_e32 v31, v144, v31
	v_mul_f32_e32 v28, v144, v28
	v_mul_f32_e32 v29, v144, v29
	v_mul_f32_e32 v26, v144, v26
	v_mul_f32_e32 v27, v144, v27
	v_mul_f32_e32 v24, v144, v24
	v_mul_f32_e32 v25, v144, v25
	v_mul_f32_e32 v22, v144, v22
	v_mul_f32_e32 v23, v144, v23
	v_mul_f32_e32 v20, v144, v20
	v_mul_f32_e32 v21, v144, v21
	v_mul_f32_e32 v18, v144, v18
	v_mul_f32_e32 v19, v144, v19
	v_mul_f32_e32 v16, v144, v16
	v_mul_f32_e32 v17, v144, v17
	s_branch .LBB0_176

.LBB0_227:
	s_mul_i32 s10, s7, 0x6800
	v_add_u32_e32 v0, s10, v192
	ds_read_b128 v[2:5], v0
	ds_read_b128 v[6:9], v0 offset:32
	ds_read_b128 v[10:13], v0 offset:6656
	ds_read_b128 v[48:51], v0 offset:64
	ds_read_b128 v[52:55], v0 offset:6688
	ds_read_b128 v[56:59], v0 offset:6720
	s_mulk_i32 s7, 0x4400
	s_waitcnt lgkmcnt(5)
	v_mfma_f32_32x32x16_bf16 v[96:111], v[2:5], v[120:123], 0
	s_waitcnt lgkmcnt(3)
	v_mfma_f32_32x32x16_bf16 v[80:95], v[10:13], v[120:123], 0
	v_mfma_f32_32x32x16_bf16 v[96:111], v[6:9], v[124:127], v[96:111]
	s_waitcnt lgkmcnt(1)
	v_mfma_f32_32x32x16_bf16 v[80:95], v[52:55], v[124:127], v[80:95]
	v_mfma_f32_32x32x16_bf16 v[96:111], v[48:51], v[128:131], v[96:111]
	s_waitcnt lgkmcnt(0)
	v_mfma_f32_32x32x16_bf16 v[80:95], v[56:59], v[128:131], v[80:95]
	ds_read_b128 v[2:5], v0 offset:96
	ds_read_b128 v[6:9], v0 offset:128
	ds_read_b128 v[10:13], v0 offset:6752
	ds_read_b128 v[48:51], v0 offset:160
	ds_read_b128 v[52:55], v0 offset:6784
	ds_read_b128 v[56:59], v0 offset:6816
	s_waitcnt lgkmcnt(5)
	v_mfma_f32_32x32x16_bf16 v[96:111], v[2:5], v[144:147], v[96:111]
	s_waitcnt lgkmcnt(3)
	v_mfma_f32_32x32x16_bf16 v[80:95], v[10:13], v[144:147], v[80:95]
	v_mfma_f32_32x32x16_bf16 v[96:111], v[6:9], v[148:151], v[96:111]
	s_waitcnt lgkmcnt(1)
	v_mfma_f32_32x32x16_bf16 v[80:95], v[52:55], v[148:151], v[80:95]
	v_mfma_f32_32x32x16_bf16 v[96:111], v[48:51], v[152:155], v[96:111]
	s_waitcnt lgkmcnt(0)
	v_mfma_f32_32x32x16_bf16 v[80:95], v[56:59], v[152:155], v[80:95]
	ds_read_b128 v[2:5], v0 offset:13312
	ds_read_b128 v[6:9], v0 offset:13344
	ds_read_b128 v[10:13], v0 offset:19968
	ds_read_b128 v[156:159], v0 offset:13376
	ds_read_b128 v[160:163], v0 offset:20000
	ds_read_b128 v[164:167], v0 offset:20032
	s_waitcnt lgkmcnt(5)
	v_mfma_f32_32x32x16_bf16 v[64:79], v[2:5], v[120:123], 0
	s_waitcnt lgkmcnt(3)
	v_mfma_f32_32x32x16_bf16 v[48:63], v[10:13], v[120:123], 0
	v_mfma_f32_32x32x16_bf16 v[64:79], v[6:9], v[124:127], v[64:79]
	s_waitcnt lgkmcnt(1)
	v_mfma_f32_32x32x16_bf16 v[48:63], v[160:163], v[124:127], v[48:63]
	v_mfma_f32_32x32x16_bf16 v[64:79], v[156:159], v[128:131], v[64:79]
	s_waitcnt lgkmcnt(0)
	v_mfma_f32_32x32x16_bf16 v[48:63], v[164:167], v[128:131], v[48:63]
	ds_read_b128 v[2:5], v0 offset:13408
	ds_read_b128 v[6:9], v0 offset:13440
	ds_read_b128 v[10:13], v0 offset:20064
	ds_read_b128 v[156:159], v0 offset:13472
	ds_read_b128 v[160:163], v0 offset:20096
	ds_read_b128 v[164:167], v0 offset:20128
	s_waitcnt lgkmcnt(5)
	v_mfma_f32_32x32x16_bf16 v[64:79], v[2:5], v[144:147], v[64:79]
	s_waitcnt lgkmcnt(3)
	v_mfma_f32_32x32x16_bf16 v[48:63], v[10:13], v[144:147], v[48:63]
	v_mfma_f32_32x32x16_bf16 v[64:79], v[6:9], v[148:151], v[64:79]
	s_waitcnt lgkmcnt(1)
	v_mfma_f32_32x32x16_bf16 v[48:63], v[160:163], v[148:151], v[48:63]
	v_mfma_f32_32x32x16_bf16 v[64:79], v[156:159], v[152:155], v[64:79]
	s_waitcnt lgkmcnt(0)
	v_mfma_f32_32x32x16_bf16 v[48:63], v[164:167], v[152:155], v[48:63]
	v_add_u32_e32 v14, s7, v193
	ds_read_b128 v[172:175], v14 offset:53248
	ds_read_b128 v[168:171], v14 offset:53280
	ds_read_b128 v[164:167], v14 offset:53312
	ds_read_b128 v[160:163], v14 offset:53344
	ds_read_b128 v[156:159], v14 offset:61952
	ds_read_b128 v[10:13], v14 offset:61984
	ds_read_b128 v[6:9], v14 offset:62016
	ds_read_b128 v[2:5], v14 offset:62048
	v_max3_f32 v0, v96, v80, v97
	v_max_f32_e32 v15, v95, v95
	v_max3_f32 v0, v0, v81, v98
	v_max3_f32 v0, v0, v82, v99
	v_max3_f32 v0, v0, v83, v100
	v_max3_f32 v0, v0, v84, v101
	v_max3_f32 v0, v0, v85, v102
	v_max3_f32 v0, v0, v86, v103
	v_max3_f32 v0, v0, v87, v104
	v_max3_f32 v0, v0, v88, v105
	v_max3_f32 v0, v0, v89, v106
	v_max3_f32 v0, v0, v90, v107
	v_max3_f32 v0, v0, v91, v108
	v_max3_f32 v0, v0, v92, v109
	v_max3_f32 v0, v0, v93, v110
	v_max3_f32 v0, v0, v94, v111
	s_nop 0
	v_max_f32_e32 v0, v0, v0
	v_max_f32_e32 v0, v0, v15
	v_mov_b32_e32 v15, v0
	v_nop
	v_nop
	v_permlane32_swap_b32 v0, v15
	s_nop 0
	v_max3_f32 v230, v195, v0, v15
	v_sub_f32_e32 v0, v195, v230
	v_exp_f32_e32 v0, v0
	s_nop 0
	v_cmp_neq_f32_e32 vcc, 1.0, v0
	s_cbranch_vccz .LBB0_229
	v_mul_f32_e32 v46, v0, v46
	v_mul_f32_e32 v47, v0, v47
	v_mul_f32_e32 v44, v0, v44
	v_mul_f32_e32 v45, v0, v45
	v_mul_f32_e32 v42, v0, v42
	v_mul_f32_e32 v43, v0, v43
	v_mul_f32_e32 v40, v0, v40
	v_mul_f32_e32 v41, v0, v41
	v_mul_f32_e32 v38, v0, v38
	v_mul_f32_e32 v39, v0, v39
	v_mul_f32_e32 v36, v0, v36
	v_mul_f32_e32 v37, v0, v37
	v_mul_f32_e32 v34, v0, v34
	v_mul_f32_e32 v35, v0, v35
	v_mul_f32_e32 v32, v0, v32
	v_mul_f32_e32 v33, v0, v33
	v_mul_f32_e32 v30, v0, v30
	v_mul_f32_e32 v31, v0, v31
	v_mul_f32_e32 v28, v0, v28
	v_mul_f32_e32 v29, v0, v29
	v_mul_f32_e32 v26, v0, v26
	v_mul_f32_e32 v27, v0, v27
	v_mul_f32_e32 v24, v0, v24
	v_mul_f32_e32 v25, v0, v25
	v_mul_f32_e32 v22, v0, v22
	v_mul_f32_e32 v23, v0, v23
	v_mul_f32_e32 v20, v0, v20
	v_mul_f32_e32 v21, v0, v21
	v_mul_f32_e32 v18, v0, v18
	v_mul_f32_e32 v19, v0, v19
	v_mul_f32_e32 v16, v0, v16
	v_mul_f32_e32 v17, v0, v17
.LBB0_229:
	v_sub_f32_e32 v80, v80, v230
	v_exp_f32_e32 v202, v80
	v_sub_f32_e32 v80, v97, v230
	v_exp_f32_e32 v203, v80
	v_sub_f32_e32 v80, v81, v230
	v_exp_f32_e32 v204, v80
	v_sub_f32_e32 v80, v98, v230
	v_exp_f32_e32 v205, v80
	v_sub_f32_e32 v80, v82, v230
	v_exp_f32_e32 v206, v80
	v_sub_f32_e32 v80, v99, v230
	v_exp_f32_e32 v207, v80
	v_sub_f32_e32 v80, v83, v230
	v_exp_f32_e32 v208, v80
	v_sub_f32_e32 v80, v100, v230
	v_exp_f32_e32 v100, v80
	v_sub_f32_e32 v80, v84, v230
	v_exp_f32_e32 v209, v80
	v_sub_f32_e32 v80, v101, v230
	v_exp_f32_e32 v101, v80
	v_sub_f32_e32 v80, v85, v230
	v_exp_f32_e32 v219, v80
	v_sub_f32_e32 v80, v102, v230
	v_exp_f32_e32 v102, v80
	v_sub_f32_e32 v80, v86, v230
	v_exp_f32_e32 v220, v80
	v_sub_f32_e32 v80, v103, v230
	v_exp_f32_e32 v103, v80
	v_sub_f32_e32 v80, v87, v230
	v_exp_f32_e32 v221, v80
	v_sub_f32_e32 v80, v104, v230
	v_exp_f32_e32 v104, v80
	v_sub_f32_e32 v80, v88, v230
	v_exp_f32_e32 v222, v80
	v_sub_f32_e32 v80, v105, v230
	v_exp_f32_e32 v105, v80
	v_sub_f32_e32 v80, v89, v230
	v_exp_f32_e32 v223, v80
	v_sub_f32_e32 v80, v106, v230
	v_exp_f32_e32 v106, v80
	v_sub_f32_e32 v80, v90, v230
	v_exp_f32_e32 v224, v80
	v_sub_f32_e32 v80, v107, v230
	v_exp_f32_e32 v107, v80
	v_sub_f32_e32 v80, v91, v230
	v_exp_f32_e32 v225, v80
	v_sub_f32_e32 v80, v108, v230
	v_exp_f32_e32 v108, v80
	v_sub_f32_e32 v80, v92, v230
	v_exp_f32_e32 v226, v80
	v_sub_f32_e32 v80, v109, v230
	v_exp_f32_e32 v109, v80
	v_sub_f32_e32 v80, v93, v230
	v_exp_f32_e32 v227, v80
	v_sub_f32_e32 v80, v110, v230
	v_exp_f32_e32 v110, v80
	v_sub_f32_e32 v80, v94, v230
	v_exp_f32_e32 v228, v80
	v_sub_f32_e32 v80, v111, v230
	v_sub_f32_e32 v15, v96, v230
	v_exp_f32_e32 v111, v80
	v_sub_f32_e32 v80, v95, v230
	v_exp_f32_e32 v15, v15
	v_exp_f32_e32 v229, v80
	v_cvt_pk_bf16_f32 v80, v222, v223
	v_cvt_pk_bf16_f32 v81, v224, v225
	v_cvt_pk_bf16_f32 v82, v226, v227
	v_cvt_pk_bf16_f32 v83, v228, v229
	v_cvt_pk_bf16_f32 v84, v202, v204
	v_cvt_pk_bf16_f32 v85, v206, v208
	v_cvt_pk_bf16_f32 v86, v209, v219
	v_cvt_pk_bf16_f32 v87, v220, v221
	v_cvt_pk_bf16_f32 v88, v104, v105
	v_cvt_pk_bf16_f32 v89, v106, v107
	v_cvt_pk_bf16_f32 v90, v108, v109
	v_cvt_pk_bf16_f32 v91, v110, v111
	v_cvt_pk_bf16_f32 v92, v15, v203
	v_cvt_pk_bf16_f32 v93, v205, v207
	v_cvt_pk_bf16_f32 v94, v100, v101
	v_cvt_pk_bf16_f32 v95, v102, v103
	s_waitcnt lgkmcnt(7)
	s_nop 0
	v_mfma_f32_32x32x16_bf16 v[32:47], v[172:175], v[92:95], v[32:47]
	s_waitcnt lgkmcnt(3)
	v_mfma_f32_32x32x16_bf16 v[16:31], v[156:159], v[92:95], v[16:31]
	v_mfma_f32_32x32x16_bf16 v[32:47], v[168:171], v[88:91], v[32:47]
	s_waitcnt lgkmcnt(2)
	v_mfma_f32_32x32x16_bf16 v[16:31], v[10:13], v[88:91], v[16:31]
	v_mfma_f32_32x32x16_bf16 v[32:47], v[164:167], v[84:87], v[32:47]
	s_waitcnt lgkmcnt(1)
	v_mfma_f32_32x32x16_bf16 v[16:31], v[6:9], v[84:87], v[16:31]
	v_mfma_f32_32x32x16_bf16 v[32:47], v[160:163], v[80:83], v[32:47]
	s_waitcnt lgkmcnt(0)
	v_mfma_f32_32x32x16_bf16 v[16:31], v[2:5], v[80:83], v[16:31]
	ds_read_b128 v[96:99], v14 offset:53376
	ds_read_b128 v[92:95], v14 offset:53408
	ds_read_b128 v[88:91], v14 offset:53440
	ds_read_b128 v[84:87], v14 offset:53472
	ds_read_b128 v[80:83], v14 offset:62080
	ds_read_b128 v[10:13], v14 offset:62112
	ds_read_b128 v[6:9], v14 offset:62144
	ds_read_b128 v[2:5], v14 offset:62176
	v_max3_f32 v14, v64, v48, v65
	v_max_f32_e32 v156, v63, v63
	v_max3_f32 v14, v14, v49, v66
	v_max3_f32 v14, v14, v50, v67
	v_max3_f32 v14, v14, v51, v68
	v_max3_f32 v14, v14, v52, v69
	v_max3_f32 v14, v14, v53, v70
	v_max3_f32 v14, v14, v54, v71
	v_max3_f32 v14, v14, v55, v72
	v_max3_f32 v14, v14, v56, v73
	v_max3_f32 v14, v14, v57, v74
	v_max3_f32 v14, v14, v58, v75
	v_max3_f32 v14, v14, v59, v76
	v_max3_f32 v14, v14, v60, v77
	v_max3_f32 v14, v14, v61, v78
	v_max3_f32 v14, v14, v62, v79
	s_nop 0
	v_max_f32_e32 v14, v14, v14
	v_max_f32_e32 v14, v14, v156
	v_mov_b32_e32 v156, v14
	v_nop
	v_nop
	v_permlane32_swap_b32 v14, v156
	s_nop 0
	v_max3_f32 v195, v230, v14, v156
	v_sub_f32_e32 v14, v230, v195
	v_exp_f32_e32 v14, v14
	s_nop 0
	v_cmp_neq_f32_e32 vcc, 1.0, v14
	s_cbranch_vccz .LBB0_231
	v_mul_f32_e32 v46, v14, v46
	v_mul_f32_e32 v47, v14, v47
	v_mul_f32_e32 v44, v14, v44
	v_mul_f32_e32 v45, v14, v45
	v_mul_f32_e32 v42, v14, v42
	v_mul_f32_e32 v43, v14, v43
	v_mul_f32_e32 v40, v14, v40
	v_mul_f32_e32 v41, v14, v41
	v_mul_f32_e32 v38, v14, v38
	v_mul_f32_e32 v39, v14, v39
	v_mul_f32_e32 v36, v14, v36
	v_mul_f32_e32 v37, v14, v37
	v_mul_f32_e32 v34, v14, v34
	v_mul_f32_e32 v35, v14, v35
	v_mul_f32_e32 v32, v14, v32
	v_mul_f32_e32 v33, v14, v33
	v_mul_f32_e32 v30, v14, v30
	v_mul_f32_e32 v31, v14, v31
	v_mul_f32_e32 v28, v14, v28
	v_mul_f32_e32 v29, v14, v29
	v_mul_f32_e32 v26, v14, v26
	v_mul_f32_e32 v27, v14, v27
	v_mul_f32_e32 v24, v14, v24
	v_mul_f32_e32 v25, v14, v25
	v_mul_f32_e32 v22, v14, v22
	v_mul_f32_e32 v23, v14, v23
	v_mul_f32_e32 v20, v14, v20
	v_mul_f32_e32 v21, v14, v21
	v_mul_f32_e32 v18, v14, v18
	v_mul_f32_e32 v19, v14, v19
	v_mul_f32_e32 v16, v14, v16
	v_mul_f32_e32 v17, v14, v17

.LBB0_238:
	v_cmp_lt_i32_e64 s[10:11], s31, v6
	v_mov_b32_e32 v2, v6
	s_and_saveexec_b64 s[20:21], s[10:11]
	v_add_u32_e32 v2, 0xffffe000, v6
	v_lshrrev_b32_e32 v2, 12, v2
	v_mul_u32_u24_e32 v2, 0x1200, v2
	v_and_b32_e32 v3, 0xfff, v6
	v_add3_u32 v2, v2, v3, s86
	s_or_b64 exec, exec, s[20:21]
	v_ashrrev_i32_e32 v3, 31, v2
	v_lshlrev_b64 v[2:3], 9, v[2:3]
	v_lshl_add_u64 v[14:15], v[8:9], 0, v[2:3]
	global_load_dwordx2 v[16:17], v[14:15], off
	s_andn2_b64 vcc, exec, s[16:17]
	s_waitcnt vmcnt(0)
	v_and_b32_e32 v3, 0xffff0000, v16
	v_lshlrev_b32_e32 v2, 16, v16
	v_and_b32_e32 v5, 0xffff0000, v17
	v_lshlrev_b32_e32 v4, 16, v17
	s_cbranch_vccnz .LBB0_242
	v_mov_b32_e32 v26, v3
	v_mov_b32_e32 v27, v5
	v_mov_b32_e32 v16, v2
	v_mov_b32_e32 v17, v4
	v_pk_mul_f32 v[26:27], v[26:27], v[26:27]
	s_nop 0
	v_pk_fma_f32 v[16:17], v[16:17], v[16:17], v[26:27]
	global_load_dwordx4 v[26:29], v[10:11], off
	v_add_f32_e32 v7, v16, v17
	ds_bpermute_b32 v16, v18, v7
	s_waitcnt lgkmcnt(0)
	v_add_f32_e32 v7, v7, v16
	ds_bpermute_b32 v16, v19, v7
	s_waitcnt lgkmcnt(0)
	v_add_f32_e32 v7, v7, v16
	ds_bpermute_b32 v16, v20, v7
	s_waitcnt lgkmcnt(0)
	v_add_f32_e32 v7, v7, v16
	ds_bpermute_b32 v16, v21, v7
	s_waitcnt lgkmcnt(0)
	v_add_f32_e32 v7, v7, v16
	v_fmamk_f32 v7, v7, 0x3c800000, v252
	v_cmp_gt_f32_e32 vcc, s67, v7
	v_mul_f32_e32 v16, 0x4b800000, v7
	s_nop 0
	v_cndmask_b32_e32 v7, v7, v16, vcc
	v_rsq_f32_e32 v7, v7
	s_nop 0
	v_mul_f32_e32 v16, 0x45800000, v7
	v_cndmask_b32_e32 v16, v7, v16, vcc
	s_waitcnt vmcnt(0)
	v_mul_f32_e32 v26, v16, v26
	v_mul_f32_e32 v27, v16, v27
	v_pk_mul_f32 v[16:17], v[28:29], v[16:17] op_sel_hi:[1,0]
	v_pk_mul_f32 v[2:3], v[26:27], v[2:3]
	v_pk_mul_f32 v[4:5], v[16:17], v[4:5]
